# v32 with softmax-phase priority 3 instead of 1
# speedup vs baseline: 1.0274x; 1.0274x over previous
; #define LAS __attribute__((address_space(3)))
; DI void expsum(f32x16& p, float& l_reg, bf16x8& pa0, bf16x8& pa1) {
; #pragma unroll
;     for (int r = 0; r < 16; ++r) p[r] = __builtin_amdgcn_exp2f(p[r]);
;     float ps = 0.f;
; #pragma unroll
;     for (int r = 0; r < 16; ++r) ps += p[r];
;     l_reg += ps; asm volatile("" : "+v"(l_reg));
;     ...
;     ATT_PK4(p, 0, pa0); ATT_PK4(p, 8, pa1);
;     ...
; }
; DI int v_rd_base(int lane) { return ((lane & 3) << 3) | (((lane >> 2) & 3) << 6) | (((lane >> 4) & 1) << 5) | (((lane >> 5) & 1) << 8); }
; template <int OFF> DI s16x4 tr_read(int vb) { s16x4 r; asm volatile("ds_read_b64_tr_b16 %0, %1 offset:%2" : "=&v"(r) : "v"(vb), "i"(OFF) : "memory"); return r; }
; template <int H> DI void v_reads(s16x4* vf, int vb) {
;     vf[0] = tr_read<v_rd_off(0, 2 * H, 0)>(vb); vf[1] = tr_read<v_rd_off(0, 2 * H, 1)>(vb); vf[2] = tr_read<v_rd_off(0, 2 * H + 1, 0)>(vb); vf[3] = tr_read<v_rd_off(0, 2 * H + 1, 1)>(vb);
;     vf[4] = tr_read<v_rd_off(1, 2 * H, 0)>(vb); vf[5] = tr_read<v_rd_off(1, 2 * H, 1)>(vb); vf[6] = tr_read<v_rd_off(1, 2 * H + 1, 0)>(vb); vf[7] = tr_read<v_rd_off(1, 2 * H + 1, 1)>(vb);
;     vf[8] = tr_read<v_rd_off(2, 2 * H, 0)>(vb); vf[9] = tr_read<v_rd_off(2, 2 * H, 1)>(vb); vf[10] = tr_read<v_rd_off(2, 2 * H + 1, 0)>(vb); vf[11] = tr_read<v_rd_off(2, 2 * H + 1, 1)>(vb);
;     vf[12] = tr_read<v_rd_off(3, 2 * H, 0)>(vb); vf[13] = tr_read<v_rd_off(3, 2 * H, 1)>(vb); vf[14] = tr_read<v_rd_off(3, 2 * H + 1, 0)>(vb); vf[15] = tr_read<v_rd_off(3, 2 * H + 1, 1)>(vb);
; }
; DI void pv_mma(f32x16* o, const s16x4* vf, bf16x8 pa0, bf16x8 pa1) {
;     ...
; #pragma unroll
;     for (int d0 = 0; d0 < 4; ++d0) {
;         o[d0] = __builtin_amdgcn_mfma_f32_32x32x16_bf16(pa0, ATT_PK(vf[4 * d0], vf[4 * d0 + 1]), o[d0], 0, 0, 0);
;         o[d0] = __builtin_amdgcn_mfma_f32_32x32x16_bf16(pa1, ATT_PK(vf[4 * d0 + 2], vf[4 * d0 + 3]), o[d0], 0, 0, 0); }
;     ...
; }
; template <int DQK, int D0A, int D0B> DI void k_reads(bf16x8* kf, const LAS unsigned char* Ks, int half, int r32, int hi) {
; #pragma unroll
;     for (int d0 = D0A; d0 < D0B; ++d0) kf[d0 - D0A] = *(const LAS bf16x8*)(Ks + half * (32 * DQK * 2) + kswz<DQK>(r32, (d0 * 16 + hi * 8) * 2));
; }
; template <int D0A, int D0B> DI void qk_mma(f32x16& p, const bf16x8* kf, const bf16x8* qr) {
; #pragma unroll
;     for (int d0 = D0A; d0 < D0B; ++d0) {
.LBB0_1922:
	s_add_i32 s3, s0, -1
	s_add_i32 s2, s22, 0xffffa000
	s_and_b32 s2, s2, 0x6000
	v_add_u32_e32 v121, s2, v114
	v_add_u32_e32 v122, v121, v115
	v_add_u32_e32 v126, v121, v116
	ds_read_b128 v[122:125], v122 offset:4096
	ds_read_b128 v[132:135], v126 offset:4096
	v_add_u32_e32 v126, v121, v117
	v_add_u32_e32 v121, v121, v118
	s_lshl_b32 s2, s1, 14
	ds_read_b128 v[136:139], v126 offset:4096
	ds_read_b128 v[140:143], v121 offset:4096
	v_add_u32_e32 v121, s2, v106
	ds_read_b64_tr_b16 v[144:145], v121 offset:0
	ds_read_b64_tr_b16 v[146:147], v121 offset:0x800
	ds_read_b64_tr_b16 v[148:149], v121 offset:0x1000
	ds_read_b64_tr_b16 v[150:151], v121 offset:0x1800
	ds_read_b64_tr_b16 v[152:153], v121 offset:0x200
	ds_read_b64_tr_b16 v[154:155], v121 offset:0xa00
	ds_read_b64_tr_b16 v[156:157], v121 offset:0x1200
	ds_read_b64_tr_b16 v[158:159], v121 offset:0x1a00
	ds_read_b64_tr_b16 v[162:163], v121 offset:0x400
	ds_read_b64_tr_b16 v[164:165], v121 offset:0xc00
	ds_read_b64_tr_b16 v[166:167], v121 offset:0x1400
	ds_read_b64_tr_b16 v[168:169], v121 offset:0x1c00
	ds_read_b64_tr_b16 v[170:171], v121 offset:0x600
	ds_read_b64_tr_b16 v[172:173], v121 offset:0xe00
	ds_read_b64_tr_b16 v[174:175], v121 offset:0x1600
	ds_read_b64_tr_b16 v[176:177], v121 offset:0x1e00
	s_setprio 3
	v_exp_f32_e32 v64, v64
	v_exp_f32_e32 v65, v65
	v_exp_f32_e32 v66, v66
	v_exp_f32_e32 v67, v67
	v_exp_f32_e32 v68, v68
	v_add_f32_e32 v126, 0, v64
	v_exp_f32_e32 v69, v69
	v_add_f32_e32 v126, v65, v126
	v_exp_f32_e32 v70, v70
	v_add_f32_e32 v126, v66, v126
	v_exp_f32_e32 v71, v71
	v_add_f32_e32 v126, v67, v126
	v_exp_f32_e32 v72, v72
	v_add_f32_e32 v126, v68, v126
	v_exp_f32_e32 v73, v73
	v_add_f32_e32 v126, v69, v126
	v_exp_f32_e32 v74, v74
	v_add_f32_e32 v126, v70, v126
	v_exp_f32_e32 v75, v75
	v_add_f32_e32 v126, v71, v126
	v_exp_f32_e32 v76, v76
	v_add_f32_e32 v126, v72, v126
	v_exp_f32_e32 v77, v77
	v_add_f32_e32 v126, v73, v126
	v_exp_f32_e32 v78, v78
	v_add_f32_e32 v126, v74, v126
	v_exp_f32_e32 v79, v79
	v_add_f32_e32 v126, v75, v126
	v_add_f32_e32 v126, v76, v126
	v_add_f32_e32 v126, v77, v126
	v_add_f32_e32 v126, v78, v126
	v_add_f32_e32 v126, v79, v126
	v_add_f32_e32 v120, v126, v120
	v_cvt_pk_bf16_f32 v64, v64, v65
	v_cvt_pk_bf16_f32 v65, v66, v67
	v_cvt_pk_bf16_f32 v66, v68, v69
	v_cvt_pk_bf16_f32 v67, v70, v71
	v_cvt_pk_bf16_f32 v68, v72, v73
	v_cvt_pk_bf16_f32 v69, v74, v75
	v_cvt_pk_bf16_f32 v70, v76, v77
	v_cvt_pk_bf16_f32 v71, v78, v79
	s_nop 0
	v_permlane32_swap_b32_e32 v64, v66
	v_permlane32_swap_b32_e32 v65, v67
	v_permlane32_swap_b32_e32 v68, v70
	v_permlane32_swap_b32_e32 v69, v71
	s_waitcnt lgkmcnt(0)
	s_setprio 0
	v_mfma_f32_32x32x16_bf16 v[0:15], v[64:67], v[144:147], v[0:15]
	s_cmp_lt_i32 s3, s55
	s_cselect_b64 vcc, -1, 0
	s_cmp_ge_i32 s3, s97
	s_cselect_b64 s[74:75], -1, 0
	s_or_b64 s[74:75], vcc, s[74:75]
	s_and_b64 vcc, exec, s[74:75]
	v_mfma_f32_32x32x16_bf16 v[48:63], v[64:67], v[152:155], v[48:63]
	v_mfma_f32_32x32x16_bf16 v[32:47], v[64:67], v[162:165], v[32:47]
	v_mfma_f32_32x32x16_bf16 v[16:31], v[64:67], v[170:173], v[16:31]
	v_mfma_f32_32x32x16_bf16 v[0:15], v[68:71], v[148:151], v[0:15]
	v_mfma_f32_32x32x16_bf16 v[48:63], v[68:71], v[156:159], v[48:63]
	v_mfma_f32_32x32x16_bf16 v[32:47], v[68:71], v[166:169], v[32:47]
	v_mfma_f32_32x32x16_bf16 v[16:31], v[68:71], v[174:177], v[16:31]
	v_mfma_f32_32x32x16_bf16 v[64:79], v[122:125], v[92:95], 0
	v_mfma_f32_32x32x16_bf16 v[64:79], v[132:135], v[88:91], v[64:79]
	v_mfma_f32_32x32x16_bf16 v[64:79], v[136:139], v[84:87], v[64:79]
	v_mfma_f32_32x32x16_bf16 v[64:79], v[140:143], v[80:83], v[64:79]
	v_add_u32_e32 v122, s7, v119
	s_cbranch_vccnz .LBB0_1924
	v_add_u32_e32 v138, 0x28908, v122
	v_add_u32_e32 v140, 0x28920, v122
	v_add_u32_e32 v142, 0x28928, v122
	v_add_u32_e32 v124, 0x28940, v122
	v_add_u32_e32 v126, 0x28948, v122
	v_add_u32_e32 v132, 0x28960, v122
	v_add_u32_e32 v134, 0x28968, v122
	v_add_u32_e32 v123, 0x28900, v122
	ds_read2_b32 v[124:125], v124 offset1:1
	ds_read2_b32 v[126:127], v126 offset1:1
	ds_read2_b32 v[132:133], v132 offset1:1
	ds_read2_b32 v[134:135], v134 offset1:1
	ds_read2_b32 v[136:137], v123 offset1:1
	ds_read2_b32 v[138:139], v138 offset1:1
	ds_read2_b32 v[140:141], v140 offset1:1
	ds_read2_b32 v[142:143], v142 offset1:1
	s_waitcnt lgkmcnt(0)
	v_pk_add_f32 v[78:79], v[78:79], v[134:135]
	v_pk_add_f32 v[76:77], v[76:77], v[132:133]
	v_pk_add_f32 v[74:75], v[74:75], v[126:127]
	v_pk_add_f32 v[72:73], v[72:73], v[124:125]
	v_pk_add_f32 v[70:71], v[70:71], v[142:143]
	v_pk_add_f32 v[68:69], v[68:69], v[140:141]
	v_pk_add_f32 v[66:67], v[66:67], v[138:139]
	v_pk_add_f32 v[64:65], v[64:65], v[136:137]
; DI void expsum(f32x16& p, float& l_reg, bf16x8& pa0, bf16x8& pa1) {
; #pragma unroll
;     for (int r = 0; r < 16; ++r) p[r] = __builtin_amdgcn_exp2f(p[r]);
;     float ps = 0.f;
; #pragma unroll
;     for (int r = 0; r < 16; ++r) ps += p[r];
;     l_reg += ps; asm volatile("" : "+v"(l_reg));
;     ...
;     ATT_PK4(p, 0, pa0); ATT_PK4(p, 8, pa1);
;     ...
; }
; DI int v_rd_base(int lane) { return ((lane & 3) << 3) | (((lane >> 2) & 3) << 6) | (((lane >> 4) & 1) << 5) | (((lane >> 5) & 1) << 8); }
; template <int OFF> DI s16x4 tr_read(int vb) { s16x4 r; asm volatile("ds_read_b64_tr_b16 %0, %1 offset:%2" : "=&v"(r) : "v"(vb), "i"(OFF) : "memory"); return r; }
; template <int H> DI void v_reads(s16x4* vf, int vb) {
;     vf[0] = tr_read<v_rd_off(0, 2 * H, 0)>(vb); vf[1] = tr_read<v_rd_off(0, 2 * H, 1)>(vb); vf[2] = tr_read<v_rd_off(0, 2 * H + 1, 0)>(vb); vf[3] = tr_read<v_rd_off(0, 2 * H + 1, 1)>(vb);
;     vf[4] = tr_read<v_rd_off(1, 2 * H, 0)>(vb); vf[5] = tr_read<v_rd_off(1, 2 * H, 1)>(vb); vf[6] = tr_read<v_rd_off(1, 2 * H + 1, 0)>(vb); vf[7] = tr_read<v_rd_off(1, 2 * H + 1, 1)>(vb);
;     vf[8] = tr_read<v_rd_off(2, 2 * H, 0)>(vb); vf[9] = tr_read<v_rd_off(2, 2 * H, 1)>(vb); vf[10] = tr_read<v_rd_off(2, 2 * H + 1, 0)>(vb); vf[11] = tr_read<v_rd_off(2, 2 * H + 1, 1)>(vb);
;     vf[12] = tr_read<v_rd_off(3, 2 * H, 0)>(vb); vf[13] = tr_read<v_rd_off(3, 2 * H, 1)>(vb); vf[14] = tr_read<v_rd_off(3, 2 * H + 1, 0)>(vb); vf[15] = tr_read<v_rd_off(3, 2 * H + 1, 1)>(vb);
; }
.LBB0_1924:
	s_add_i32 s3, s22, 0xffffc000
	s_and_b32 s3, s3, 0x6000
	v_add_u32_e32 v123, s3, v114
	v_add_u32_e32 v140, v123, v118
	v_add_u32_e32 v136, v123, v117
	v_add_u32_e32 v132, v123, v116
	v_add_u32_e32 v123, v123, v115
	ds_read_b128 v[124:127], v123
	ds_read_b128 v[132:135], v132
	ds_read_b128 v[136:139], v136
	ds_read_b128 v[140:143], v140
	ds_read_b64_tr_b16 v[144:145], v121 offset:0x2000
	ds_read_b64_tr_b16 v[146:147], v121 offset:0x2800
	ds_read_b64_tr_b16 v[148:149], v121 offset:0x3000
	ds_read_b64_tr_b16 v[150:151], v121 offset:0x3800
	ds_read_b64_tr_b16 v[152:153], v121 offset:0x2200
	ds_read_b64_tr_b16 v[154:155], v121 offset:0x2a00
	ds_read_b64_tr_b16 v[156:157], v121 offset:0x3200
	ds_read_b64_tr_b16 v[158:159], v121 offset:0x3a00
	ds_read_b64_tr_b16 v[162:163], v121 offset:0x2400
	ds_read_b64_tr_b16 v[164:165], v121 offset:0x2c00
	ds_read_b64_tr_b16 v[166:167], v121 offset:0x3400
	ds_read_b64_tr_b16 v[168:169], v121 offset:0x3c00
	ds_read_b64_tr_b16 v[170:171], v121 offset:0x2600
	ds_read_b64_tr_b16 v[172:173], v121 offset:0x2e00
	ds_read_b64_tr_b16 v[174:175], v121 offset:0x3600
	ds_read_b64_tr_b16 v[176:177], v121 offset:0x3e00
	s_setprio 3
	v_exp_f32_e32 v64, v64
	v_exp_f32_e32 v65, v65
	v_exp_f32_e32 v66, v66
	v_exp_f32_e32 v67, v67
	v_exp_f32_e32 v68, v68
	v_add_f32_e32 v121, 0, v64
	v_exp_f32_e32 v69, v69
	v_add_f32_e32 v121, v65, v121
	v_exp_f32_e32 v70, v70
	v_add_f32_e32 v121, v66, v121
	v_exp_f32_e32 v71, v71
	v_add_f32_e32 v121, v67, v121
	v_exp_f32_e32 v72, v72
	v_add_f32_e32 v121, v68, v121
	v_exp_f32_e32 v73, v73
	v_add_f32_e32 v121, v69, v121
	v_exp_f32_e32 v74, v74
	v_add_f32_e32 v121, v70, v121
	v_exp_f32_e32 v75, v75
	v_add_f32_e32 v121, v71, v121
	v_exp_f32_e32 v76, v76
	v_add_f32_e32 v121, v72, v121
	v_exp_f32_e32 v77, v77
	v_add_f32_e32 v121, v73, v121
	v_exp_f32_e32 v78, v78
	v_add_f32_e32 v121, v74, v121
	v_exp_f32_e32 v79, v79
	v_add_f32_e32 v121, v75, v121
	v_add_f32_e32 v121, v76, v121
	v_add_f32_e32 v121, v77, v121
	v_add_f32_e32 v121, v78, v121
	v_add_f32_e32 v121, v79, v121
	v_add_f32_e32 v120, v120, v121
	v_cvt_pk_bf16_f32 v64, v64, v65
	v_cvt_pk_bf16_f32 v65, v66, v67
	v_cvt_pk_bf16_f32 v66, v68, v69
	v_cvt_pk_bf16_f32 v67, v70, v71
	v_cvt_pk_bf16_f32 v68, v72, v73
	v_cvt_pk_bf16_f32 v69, v74, v75
	v_cvt_pk_bf16_f32 v70, v76, v77
	v_cvt_pk_bf16_f32 v71, v78, v79
	s_nop 0
	v_permlane32_swap_b32_e32 v64, v66
	v_permlane32_swap_b32_e32 v65, v67
	v_permlane32_swap_b32_e32 v68, v70
	v_permlane32_swap_b32_e32 v69, v71
	s_waitcnt lgkmcnt(0)
	s_setprio 0
	s_cmp_lt_u32 s33, 0x100
	s_cbranch_scc1 .Lstg_d0_mid_11
	s_waitcnt vmcnt(3)
	s_barrier

; #define LAS __attribute__((address_space(3)))
; DI void expsum(f32x16& p, float& l_reg, bf16x8& pa0, bf16x8& pa1) {
; #pragma unroll
;     for (int r = 0; r < 16; ++r) p[r] = __builtin_amdgcn_exp2f(p[r]);
;     float ps = 0.f;
; #pragma unroll
;     for (int r = 0; r < 16; ++r) ps += p[r];
;     l_reg += ps; asm volatile("" : "+v"(l_reg));
;     ...
;     ATT_PK4(p, 0, pa0); ATT_PK4(p, 8, pa1);
;     ...
; }
; DI int v_rd_base(int lane) { return ((lane & 3) << 3) | (((lane >> 2) & 3) << 6) | (((lane >> 4) & 1) << 5) | (((lane >> 5) & 1) << 8); }
; template <int OFF> DI s16x4 tr_read(int vb) { s16x4 r; asm volatile("ds_read_b64_tr_b16 %0, %1 offset:%2" : "=&v"(r) : "v"(vb), "i"(OFF) : "memory"); return r; }
; template <int H> DI void v_reads(s16x4* vf, int vb) {
;     vf[0] = tr_read<v_rd_off(0, 2 * H, 0)>(vb); vf[1] = tr_read<v_rd_off(0, 2 * H, 1)>(vb); vf[2] = tr_read<v_rd_off(0, 2 * H + 1, 0)>(vb); vf[3] = tr_read<v_rd_off(0, 2 * H + 1, 1)>(vb);
;     vf[4] = tr_read<v_rd_off(1, 2 * H, 0)>(vb); vf[5] = tr_read<v_rd_off(1, 2 * H, 1)>(vb); vf[6] = tr_read<v_rd_off(1, 2 * H + 1, 0)>(vb); vf[7] = tr_read<v_rd_off(1, 2 * H + 1, 1)>(vb);
;     vf[8] = tr_read<v_rd_off(2, 2 * H, 0)>(vb); vf[9] = tr_read<v_rd_off(2, 2 * H, 1)>(vb); vf[10] = tr_read<v_rd_off(2, 2 * H + 1, 0)>(vb); vf[11] = tr_read<v_rd_off(2, 2 * H + 1, 1)>(vb);
;     vf[12] = tr_read<v_rd_off(3, 2 * H, 0)>(vb); vf[13] = tr_read<v_rd_off(3, 2 * H, 1)>(vb); vf[14] = tr_read<v_rd_off(3, 2 * H + 1, 0)>(vb); vf[15] = tr_read<v_rd_off(3, 2 * H + 1, 1)>(vb);
; }
; DI void pv_mma(f32x16* o, const s16x4* vf, bf16x8 pa0, bf16x8 pa1) {
;     ...
; #pragma unroll
;     for (int d0 = 0; d0 < 4; ++d0) {
;         o[d0] = __builtin_amdgcn_mfma_f32_32x32x16_bf16(pa0, ATT_PK(vf[4 * d0], vf[4 * d0 + 1]), o[d0], 0, 0, 0);
;         o[d0] = __builtin_amdgcn_mfma_f32_32x32x16_bf16(pa1, ATT_PK(vf[4 * d0 + 2], vf[4 * d0 + 3]), o[d0], 0, 0, 0); }
;     ...
; }
; template <int DQK, int D0A, int D0B> DI void k_reads(bf16x8* kf, const LAS unsigned char* Ks, int half, int r32, int hi) {
; #pragma unroll
;     for (int d0 = D0A; d0 < D0B; ++d0) kf[d0 - D0A] = *(const LAS bf16x8*)(Ks + half * (32 * DQK * 2) + kswz<DQK>(r32, (d0 * 16 + hi * 8) * 2));
; }
; template <int D0A, int D0B> DI void qk_mma(f32x16& p, const bf16x8* kf, const bf16x8* qr) {
; #pragma unroll
;     for (int d0 = D0A; d0 < D0B; ++d0) {
.LBB0_1930:
	s_mov_b64 s[96:97], 0xc00
	ds_read_b128 v[98:101], v107 offset:12288
	ds_read_b128 v[102:105], v108 offset:12288
	ds_read_b128 v[114:117], v109 offset:12288
	ds_read_b128 v[122:125], v110 offset:12288
	v_lshl_add_u32 v96, s64, 14, v106
	ds_read_b64_tr_b16 v[132:133], v96 offset:0
	ds_read_b64_tr_b16 v[134:135], v96 offset:0x800
	ds_read_b64_tr_b16 v[136:137], v96 offset:0x1000
	ds_read_b64_tr_b16 v[138:139], v96 offset:0x1800
	ds_read_b64_tr_b16 v[140:141], v96 offset:0x200
	ds_read_b64_tr_b16 v[142:143], v96 offset:0xa00
	ds_read_b64_tr_b16 v[144:145], v96 offset:0x1200
	ds_read_b64_tr_b16 v[146:147], v96 offset:0x1a00
	ds_read_b64_tr_b16 v[148:149], v96 offset:0x400
	ds_read_b64_tr_b16 v[150:151], v96 offset:0xc00
	ds_read_b64_tr_b16 v[152:153], v96 offset:0x1400
	ds_read_b64_tr_b16 v[154:155], v96 offset:0x1c00
	ds_read_b64_tr_b16 v[156:157], v96 offset:0x600
	ds_read_b64_tr_b16 v[158:159], v96 offset:0xe00
	ds_read_b64_tr_b16 v[162:163], v96 offset:0x1600
	ds_read_b64_tr_b16 v[164:165], v96 offset:0x1e00
	s_setprio 3
	v_exp_f32_e32 v64, v64
	v_exp_f32_e32 v65, v65
	v_exp_f32_e32 v66, v66
	v_exp_f32_e32 v67, v67
	v_exp_f32_e32 v68, v68
	v_add_f32_e32 v97, 0, v64
	v_exp_f32_e32 v69, v69
	v_add_f32_e32 v97, v65, v97
	v_exp_f32_e32 v70, v70
	v_add_f32_e32 v97, v66, v97
	v_exp_f32_e32 v71, v71
	v_add_f32_e32 v97, v67, v97
	v_exp_f32_e32 v72, v72
	v_add_f32_e32 v97, v68, v97
	v_exp_f32_e32 v73, v73
	v_add_f32_e32 v97, v69, v97
	v_exp_f32_e32 v74, v74
	v_add_f32_e32 v97, v70, v97
	v_exp_f32_e32 v75, v75
	v_add_f32_e32 v97, v71, v97
	v_exp_f32_e32 v76, v76
	v_add_f32_e32 v97, v72, v97
	v_exp_f32_e32 v77, v77
	v_add_f32_e32 v97, v73, v97
	v_exp_f32_e32 v78, v78
	v_add_f32_e32 v97, v74, v97
	v_exp_f32_e32 v79, v79
	v_add_f32_e32 v97, v75, v97
	v_add_f32_e32 v97, v76, v97
	v_add_f32_e32 v97, v77, v97
	v_add_f32_e32 v97, v78, v97
	v_add_f32_e32 v97, v79, v97
	v_add_f32_e32 v97, v97, v120
	v_cvt_pk_bf16_f32 v64, v64, v65
	v_cvt_pk_bf16_f32 v65, v66, v67
	v_cvt_pk_bf16_f32 v66, v68, v69
	v_cvt_pk_bf16_f32 v67, v70, v71
	v_cvt_pk_bf16_f32 v68, v72, v73
	v_cvt_pk_bf16_f32 v69, v74, v75
	v_cvt_pk_bf16_f32 v70, v76, v77
	v_cvt_pk_bf16_f32 v71, v78, v79
	s_nop 0
	v_permlane32_swap_b32_e32 v64, v66
	v_permlane32_swap_b32_e32 v65, v67
	v_permlane32_swap_b32_e32 v68, v70
	v_permlane32_swap_b32_e32 v69, v71
	s_waitcnt lgkmcnt(0)
	s_setprio 0
	v_mfma_f32_32x32x16_bf16 v[0:15], v[64:67], v[132:135], v[0:15]
	s_cmp_gt_i32 s55, 61
	s_cselect_b64 s[0:1], -1, 0
	s_cmp_lt_i32 s58, 62
	s_cselect_b64 s[2:3], -1, 0
	s_or_b64 s[0:1], s[0:1], s[2:3]
	s_and_b64 vcc, exec, s[0:1]
	v_mfma_f32_32x32x16_bf16 v[48:63], v[64:67], v[140:143], v[48:63]
	v_mfma_f32_32x32x16_bf16 v[32:47], v[64:67], v[148:151], v[32:47]
	v_mfma_f32_32x32x16_bf16 v[16:31], v[64:67], v[156:159], v[16:31]
	v_mfma_f32_32x32x16_bf16 v[0:15], v[68:71], v[136:139], v[0:15]
	v_mfma_f32_32x32x16_bf16 v[48:63], v[68:71], v[144:147], v[48:63]
	v_mfma_f32_32x32x16_bf16 v[32:47], v[68:71], v[152:155], v[32:47]
	v_mfma_f32_32x32x16_bf16 v[16:31], v[68:71], v[162:165], v[16:31]
	s_waitcnt lgkmcnt(0)
	v_mfma_f32_32x32x16_bf16 v[64:79], v[98:101], v[92:95], 0
	v_mfma_f32_32x32x16_bf16 v[64:79], v[102:105], v[88:91], v[64:79]
	v_mfma_f32_32x32x16_bf16 v[64:79], v[114:117], v[84:87], v[64:79]
	v_mfma_f32_32x32x16_bf16 v[64:79], v[122:125], v[80:83], v[64:79]
	s_cbranch_vccnz .LBB0_1932
	v_sub_u32_e32 v98, 0xf40, v111
	v_lshlrev_b32_e32 v98, 2, v98
	v_add3_u32 v98, s88, v98, v130
	v_add_u32_e32 v114, 0x400, v98
	v_add_u32_e32 v116, 0x408, v98
	v_add_u32_e32 v118, 0x420, v98
	v_add_u32_e32 v120, 0x428, v98
	v_add_u32_e32 v99, 0x440, v98
	v_add_u32_e32 v100, 0x448, v98
	v_add_u32_e32 v102, 0x460, v98
	v_add_u32_e32 v104, 0x468, v98
	ds_read2_b32 v[98:99], v99 offset1:1
	ds_read2_b32 v[100:101], v100 offset1:1
	ds_read2_b32 v[102:103], v102 offset1:1
	ds_read2_b32 v[104:105], v104 offset1:1
	ds_read2_b32 v[114:115], v114 offset1:1
	ds_read2_b32 v[116:117], v116 offset1:1
	ds_read2_b32 v[118:119], v118 offset1:1
	ds_read2_b32 v[120:121], v120 offset1:1
	s_waitcnt lgkmcnt(0)
	v_pk_add_f32 v[78:79], v[78:79], v[104:105]
	v_pk_add_f32 v[76:77], v[76:77], v[102:103]
	v_pk_add_f32 v[74:75], v[74:75], v[100:101]
	v_pk_add_f32 v[72:73], v[72:73], v[98:99]
	v_pk_add_f32 v[70:71], v[70:71], v[120:121]
	v_pk_add_f32 v[68:69], v[68:69], v[118:119]
	v_pk_add_f32 v[66:67], v[66:67], v[116:117]
	v_pk_add_f32 v[64:65], v[64:65], v[114:115]
.LBB0_1932:
	s_movk_i32 s64, 0x70
	ds_read_b128 v[98:101], v107 offset:16384
	ds_read_b128 v[102:105], v108 offset:16384
	ds_read_b128 v[114:117], v109 offset:16384
	ds_read_b128 v[118:121], v110 offset:16384
	ds_read_b64_tr_b16 v[122:123], v96 offset:0x2000
	ds_read_b64_tr_b16 v[124:125], v96 offset:0x2800
	ds_read_b64_tr_b16 v[132:133], v96 offset:0x3000
	ds_read_b64_tr_b16 v[134:135], v96 offset:0x3800
	ds_read_b64_tr_b16 v[136:137], v96 offset:0x2200
	ds_read_b64_tr_b16 v[138:139], v96 offset:0x2a00
	ds_read_b64_tr_b16 v[140:141], v96 offset:0x3200
	ds_read_b64_tr_b16 v[142:143], v96 offset:0x3a00
	ds_read_b64_tr_b16 v[144:145], v96 offset:0x2400
	ds_read_b64_tr_b16 v[146:147], v96 offset:0x2c00
	ds_read_b64_tr_b16 v[148:149], v96 offset:0x3400
	ds_read_b64_tr_b16 v[150:151], v96 offset:0x3c00
	ds_read_b64_tr_b16 v[152:153], v96 offset:0x2600
	ds_read_b64_tr_b16 v[154:155], v96 offset:0x2e00
	ds_read_b64_tr_b16 v[156:157], v96 offset:0x3600
	ds_read_b64_tr_b16 v[158:159], v96 offset:0x3e00
	s_nop 5
	s_setprio 3
	v_exp_f32_e32 v64, v64
	v_exp_f32_e32 v65, v65
	v_exp_f32_e32 v66, v66
	v_exp_f32_e32 v67, v67
	v_exp_f32_e32 v68, v68
	v_add_f32_e32 v96, 0, v64
	v_exp_f32_e32 v69, v69
	v_add_f32_e32 v96, v65, v96
	v_exp_f32_e32 v70, v70
	v_add_f32_e32 v96, v66, v96
	v_exp_f32_e32 v71, v71
	v_add_f32_e32 v96, v67, v96
	v_exp_f32_e32 v72, v72
	v_add_f32_e32 v96, v68, v96
	v_exp_f32_e32 v73, v73
	v_add_f32_e32 v96, v69, v96
	v_exp_f32_e32 v74, v74
	v_add_f32_e32 v96, v70, v96
	v_exp_f32_e32 v75, v75
	v_add_f32_e32 v96, v71, v96
	v_exp_f32_e32 v76, v76
	v_add_f32_e32 v96, v72, v96
	v_exp_f32_e32 v77, v77
	v_add_f32_e32 v96, v73, v96
	v_exp_f32_e32 v78, v78
	v_add_f32_e32 v96, v74, v96
	v_exp_f32_e32 v79, v79
	v_add_f32_e32 v96, v75, v96
	v_add_f32_e32 v96, v76, v96
	v_add_f32_e32 v96, v77, v96
	v_add_f32_e32 v96, v78, v96
	v_add_f32_e32 v96, v79, v96
	v_add_f32_e32 v96, v97, v96
	v_cvt_pk_bf16_f32 v64, v64, v65
	v_cvt_pk_bf16_f32 v65, v66, v67
	v_cvt_pk_bf16_f32 v66, v68, v69
	v_cvt_pk_bf16_f32 v67, v70, v71
	v_cvt_pk_bf16_f32 v68, v72, v73
	v_cvt_pk_bf16_f32 v69, v74, v75
	v_cvt_pk_bf16_f32 v70, v76, v77
	v_cvt_pk_bf16_f32 v71, v78, v79
	s_nop 0
	v_permlane32_swap_b32_e32 v64, v66
	v_permlane32_swap_b32_e32 v65, v67
	v_permlane32_swap_b32_e32 v68, v70
	v_permlane32_swap_b32_e32 v69, v71
	s_waitcnt lgkmcnt(0)
	s_setprio 0
	s_cmp_lt_u32 s33, 0x100
	s_cbranch_scc1 .Lstg_d0_m61_13
	s_waitcnt vmcnt(0)
	s_barrier

; #define LAS __attribute__((address_space(3)))
; DI void expsum(f32x16& p, float& l_reg, bf16x8& pa0, bf16x8& pa1) {
; #pragma unroll
;     for (int r = 0; r < 16; ++r) p[r] = __builtin_amdgcn_exp2f(p[r]);
;     float ps = 0.f;
; #pragma unroll
;     for (int r = 0; r < 16; ++r) ps += p[r];
;     l_reg += ps; asm volatile("" : "+v"(l_reg));
;     ...
;     ATT_PK4(p, 0, pa0); ATT_PK4(p, 8, pa1);
;     ...
; }
; DI int v_rd_base(int lane) { return ((lane & 3) << 3) | (((lane >> 2) & 3) << 6) | (((lane >> 4) & 1) << 5) | (((lane >> 5) & 1) << 8); }
; template <int OFF> DI s16x4 tr_read(int vb) { s16x4 r; asm volatile("ds_read_b64_tr_b16 %0, %1 offset:%2" : "=&v"(r) : "v"(vb), "i"(OFF) : "memory"); return r; }
; template <int H> DI void v_reads(s16x4* vf, int vb) {
;     vf[0] = tr_read<v_rd_off(0, 2 * H, 0)>(vb); vf[1] = tr_read<v_rd_off(0, 2 * H, 1)>(vb); vf[2] = tr_read<v_rd_off(0, 2 * H + 1, 0)>(vb); vf[3] = tr_read<v_rd_off(0, 2 * H + 1, 1)>(vb);
;     vf[4] = tr_read<v_rd_off(1, 2 * H, 0)>(vb); vf[5] = tr_read<v_rd_off(1, 2 * H, 1)>(vb); vf[6] = tr_read<v_rd_off(1, 2 * H + 1, 0)>(vb); vf[7] = tr_read<v_rd_off(1, 2 * H + 1, 1)>(vb);
;     vf[8] = tr_read<v_rd_off(2, 2 * H, 0)>(vb); vf[9] = tr_read<v_rd_off(2, 2 * H, 1)>(vb); vf[10] = tr_read<v_rd_off(2, 2 * H + 1, 0)>(vb); vf[11] = tr_read<v_rd_off(2, 2 * H + 1, 1)>(vb);
;     vf[12] = tr_read<v_rd_off(3, 2 * H, 0)>(vb); vf[13] = tr_read<v_rd_off(3, 2 * H, 1)>(vb); vf[14] = tr_read<v_rd_off(3, 2 * H + 1, 0)>(vb); vf[15] = tr_read<v_rd_off(3, 2 * H + 1, 1)>(vb);
; }
; DI void pv_mma(f32x16* o, const s16x4* vf, bf16x8 pa0, bf16x8 pa1) {
;     ...
; #pragma unroll
;     for (int d0 = 0; d0 < 4; ++d0) {
;         o[d0] = __builtin_amdgcn_mfma_f32_32x32x16_bf16(pa0, ATT_PK(vf[4 * d0], vf[4 * d0 + 1]), o[d0], 0, 0, 0);
;         o[d0] = __builtin_amdgcn_mfma_f32_32x32x16_bf16(pa1, ATT_PK(vf[4 * d0 + 2], vf[4 * d0 + 3]), o[d0], 0, 0, 0); }
;     ...
; }
; template <int DQK, int D0A, int D0B> DI void k_reads(bf16x8* kf, const LAS unsigned char* Ks, int half, int r32, int hi) {
; #pragma unroll
;     for (int d0 = D0A; d0 < D0B; ++d0) kf[d0 - D0A] = *(const LAS bf16x8*)(Ks + half * (32 * DQK * 2) + kswz<DQK>(r32, (d0 * 16 + hi * 8) * 2));
; }
; template <int D0A, int D0B> DI void qk_mma(f32x16& p, const bf16x8* kf, const bf16x8* qr) {
; #pragma unroll
;     for (int d0 = D0A; d0 < D0B; ++d0) {
.LBB0_1936:
	ds_read_b128 v[100:103], v107 offset:20480
	ds_read_b128 v[114:117], v108 offset:20480
	ds_read_b128 v[118:121], v109 offset:20480
	ds_read_b128 v[122:125], v110 offset:20480
	v_add_u32_e32 v98, 0x8000, v106
	ds_read_b64_tr_b16 v[132:133], v98 offset:0
	ds_read_b64_tr_b16 v[134:135], v98 offset:0x800
	ds_read_b64_tr_b16 v[136:137], v98 offset:0x1000
	ds_read_b64_tr_b16 v[138:139], v98 offset:0x1800
	ds_read_b64_tr_b16 v[140:141], v98 offset:0x200
	ds_read_b64_tr_b16 v[142:143], v98 offset:0xa00
	ds_read_b64_tr_b16 v[144:145], v98 offset:0x1200
	ds_read_b64_tr_b16 v[146:147], v98 offset:0x1a00
	ds_read_b64_tr_b16 v[148:149], v98 offset:0x400
	ds_read_b64_tr_b16 v[150:151], v98 offset:0xc00
	ds_read_b64_tr_b16 v[152:153], v98 offset:0x1400
	ds_read_b64_tr_b16 v[154:155], v98 offset:0x1c00
	ds_read_b64_tr_b16 v[156:157], v98 offset:0x600
	ds_read_b64_tr_b16 v[158:159], v98 offset:0xe00
	ds_read_b64_tr_b16 v[162:163], v98 offset:0x1600
	ds_read_b64_tr_b16 v[164:165], v98 offset:0x1e00
	s_setprio 3
	v_exp_f32_e32 v64, v64
	v_exp_f32_e32 v65, v65
	v_exp_f32_e32 v66, v66
	v_exp_f32_e32 v67, v67
	v_exp_f32_e32 v68, v68
	v_add_f32_e32 v99, 0, v64
	v_exp_f32_e32 v69, v69
	v_add_f32_e32 v99, v65, v99
	v_exp_f32_e32 v70, v70
	v_add_f32_e32 v99, v66, v99
	v_exp_f32_e32 v71, v71
	v_add_f32_e32 v99, v67, v99
	v_exp_f32_e32 v72, v72
	v_add_f32_e32 v99, v68, v99
	v_exp_f32_e32 v73, v73
	v_add_f32_e32 v99, v69, v99
	v_exp_f32_e32 v74, v74
	v_add_f32_e32 v99, v70, v99
	v_exp_f32_e32 v75, v75
	v_add_f32_e32 v99, v71, v99
	v_exp_f32_e32 v76, v76
	v_add_f32_e32 v99, v72, v99
	v_exp_f32_e32 v77, v77
	v_add_f32_e32 v99, v73, v99
	v_exp_f32_e32 v78, v78
	v_add_f32_e32 v99, v74, v99
	v_exp_f32_e32 v79, v79
	v_add_f32_e32 v99, v75, v99
	v_add_f32_e32 v99, v76, v99
	v_add_f32_e32 v99, v77, v99
	v_add_f32_e32 v99, v78, v99
	v_add_f32_e32 v99, v79, v99
	v_add_f32_e32 v96, v99, v96
	v_cvt_pk_bf16_f32 v64, v64, v65
	v_cvt_pk_bf16_f32 v65, v66, v67
	v_cvt_pk_bf16_f32 v66, v68, v69
	v_cvt_pk_bf16_f32 v67, v70, v71
	v_cvt_pk_bf16_f32 v68, v72, v73
	v_cvt_pk_bf16_f32 v69, v74, v75
	v_cvt_pk_bf16_f32 v70, v76, v77
	v_cvt_pk_bf16_f32 v71, v78, v79
	s_nop 0
	v_permlane32_swap_b32_e32 v64, v66
	v_permlane32_swap_b32_e32 v65, v67
	v_permlane32_swap_b32_e32 v68, v70
	v_permlane32_swap_b32_e32 v69, v71
	s_waitcnt lgkmcnt(0)
	s_setprio 0
	v_mfma_f32_32x32x16_bf16 v[0:15], v[64:67], v[132:135], v[0:15]
	s_and_b64 vcc, exec, s[2:3]
	v_mfma_f32_32x32x16_bf16 v[48:63], v[64:67], v[140:143], v[48:63]
	v_mfma_f32_32x32x16_bf16 v[32:47], v[64:67], v[148:151], v[32:47]
	v_mfma_f32_32x32x16_bf16 v[16:31], v[64:67], v[156:159], v[16:31]
	v_mfma_f32_32x32x16_bf16 v[0:15], v[68:71], v[136:139], v[0:15]
	v_mfma_f32_32x32x16_bf16 v[48:63], v[68:71], v[144:147], v[48:63]
	v_mfma_f32_32x32x16_bf16 v[32:47], v[68:71], v[152:155], v[32:47]
	v_mfma_f32_32x32x16_bf16 v[16:31], v[68:71], v[162:165], v[16:31]
	s_waitcnt lgkmcnt(0)
	v_mfma_f32_32x32x16_bf16 v[64:79], v[100:103], v[92:95], 0
	v_mfma_f32_32x32x16_bf16 v[64:79], v[114:117], v[88:91], v[64:79]
	v_mfma_f32_32x32x16_bf16 v[64:79], v[118:121], v[84:87], v[64:79]
	v_mfma_f32_32x32x16_bf16 v[64:79], v[122:125], v[80:83], v[64:79]
	s_cbranch_vccnz .LBB0_1938
	v_add3_u32 v97, s88, v97, v130
	v_add_u32_e32 v118, 0x408, v97
	v_add_u32_e32 v120, 0x420, v97
	v_add_u32_e32 v122, 0x428, v97
	v_add_u32_e32 v100, 0x440, v97
	v_add_u32_e32 v102, 0x448, v97
	v_add_u32_e32 v104, 0x460, v97
	v_add_u32_e32 v99, 0x400, v97
	v_add_u32_e32 v97, 0x468, v97
	ds_read2_b32 v[100:101], v100 offset1:1
	ds_read2_b32 v[102:103], v102 offset1:1
	ds_read2_b32 v[104:105], v104 offset1:1
	ds_read2_b32 v[114:115], v97 offset1:1
	ds_read2_b32 v[116:117], v99 offset1:1
	ds_read2_b32 v[118:119], v118 offset1:1
	ds_read2_b32 v[120:121], v120 offset1:1
	ds_read2_b32 v[122:123], v122 offset1:1
	s_waitcnt lgkmcnt(0)
	v_pk_add_f32 v[78:79], v[78:79], v[114:115]
	v_pk_add_f32 v[76:77], v[76:77], v[104:105]
	v_pk_add_f32 v[74:75], v[74:75], v[102:103]
	v_pk_add_f32 v[72:73], v[72:73], v[100:101]
	v_pk_add_f32 v[70:71], v[70:71], v[122:123]
	v_pk_add_f32 v[68:69], v[68:69], v[120:121]
	v_pk_add_f32 v[66:67], v[66:67], v[118:119]
	v_pk_add_f32 v[64:65], v[64:65], v[116:117]
.LBB0_1938:
	ds_read_b128 v[100:103], v107 offset:24576
	ds_read_b128 v[114:117], v108 offset:24576
	ds_read_b128 v[118:121], v109 offset:24576
	ds_read_b128 v[122:125], v110 offset:24576
	ds_read_b64_tr_b16 v[132:133], v98 offset:0x2000
	ds_read_b64_tr_b16 v[134:135], v98 offset:0x2800
	ds_read_b64_tr_b16 v[136:137], v98 offset:0x3000
	ds_read_b64_tr_b16 v[138:139], v98 offset:0x3800
	ds_read_b64_tr_b16 v[140:141], v98 offset:0x2200
	ds_read_b64_tr_b16 v[142:143], v98 offset:0x2a00
	ds_read_b64_tr_b16 v[144:145], v98 offset:0x3200
	ds_read_b64_tr_b16 v[146:147], v98 offset:0x3a00
	ds_read_b64_tr_b16 v[148:149], v98 offset:0x2400
	ds_read_b64_tr_b16 v[150:151], v98 offset:0x2c00
	ds_read_b64_tr_b16 v[152:153], v98 offset:0x3400
	ds_read_b64_tr_b16 v[154:155], v98 offset:0x3c00
	ds_read_b64_tr_b16 v[156:157], v98 offset:0x2600
	ds_read_b64_tr_b16 v[158:159], v98 offset:0x2e00
	ds_read_b64_tr_b16 v[162:163], v98 offset:0x3600
	ds_read_b64_tr_b16 v[164:165], v98 offset:0x3e00
	s_nop 6
	s_setprio 3
	v_exp_f32_e32 v64, v64
	v_exp_f32_e32 v65, v65
	v_exp_f32_e32 v66, v66
	v_exp_f32_e32 v67, v67
	v_exp_f32_e32 v68, v68
	v_add_f32_e32 v97, 0, v64
	v_exp_f32_e32 v69, v69
	v_add_f32_e32 v97, v65, v97
	v_exp_f32_e32 v70, v70
	v_add_f32_e32 v97, v66, v97
	v_exp_f32_e32 v71, v71
	v_add_f32_e32 v97, v67, v97
	v_exp_f32_e32 v72, v72
	v_add_f32_e32 v97, v68, v97
	v_exp_f32_e32 v73, v73
	v_add_f32_e32 v97, v69, v97
	v_exp_f32_e32 v74, v74
	v_add_f32_e32 v97, v70, v97
	v_exp_f32_e32 v75, v75
	v_add_f32_e32 v97, v71, v97
	v_exp_f32_e32 v76, v76
	v_add_f32_e32 v97, v72, v97
	v_exp_f32_e32 v77, v77
	v_add_f32_e32 v97, v73, v97
	v_exp_f32_e32 v78, v78
	v_add_f32_e32 v97, v74, v97
	v_exp_f32_e32 v79, v79
	v_add_f32_e32 v97, v75, v97
	v_add_f32_e32 v97, v76, v97
	v_add_f32_e32 v97, v77, v97
	v_add_f32_e32 v97, v78, v97
	v_add_f32_e32 v97, v79, v97
	v_add_f32_e32 v96, v96, v97
	v_cvt_pk_bf16_f32 v64, v64, v65
	v_cvt_pk_bf16_f32 v65, v66, v67
	v_cvt_pk_bf16_f32 v66, v68, v69
	v_cvt_pk_bf16_f32 v67, v70, v71
	v_cvt_pk_bf16_f32 v68, v72, v73
	v_cvt_pk_bf16_f32 v69, v74, v75
	v_cvt_pk_bf16_f32 v70, v76, v77
	v_cvt_pk_bf16_f32 v71, v78, v79
	s_nop 0
	v_permlane32_swap_b32_e32 v64, v66
	v_permlane32_swap_b32_e32 v65, v67
	v_permlane32_swap_b32_e32 v68, v70
	v_permlane32_swap_b32_e32 v69, v71
	s_waitcnt lgkmcnt(0)
	s_setprio 0
	s_cmp_lt_u32 s33, 0x100
	s_cbranch_scc1 .Lstg_d0_m62_15
	s_waitcnt vmcnt(0)
	s_barrier

; #define LAS __attribute__((address_space(3)))
; DI void expsum(f32x16& p, float& l_reg, bf16x8& pa0, bf16x8& pa1) {
; #pragma unroll
;     for (int r = 0; r < 16; ++r) p[r] = __builtin_amdgcn_exp2f(p[r]);
;     float ps = 0.f;
; #pragma unroll
;     for (int r = 0; r < 16; ++r) ps += p[r];
;     l_reg += ps; asm volatile("" : "+v"(l_reg));
;     ...
;     ATT_PK4(p, 0, pa0); ATT_PK4(p, 8, pa1);
;     ...
; }
; DI int v_rd_base(int lane) { return ((lane & 3) << 3) | (((lane >> 2) & 3) << 6) | (((lane >> 4) & 1) << 5) | (((lane >> 5) & 1) << 8); }
; template <int OFF> DI s16x4 tr_read(int vb) { s16x4 r; asm volatile("ds_read_b64_tr_b16 %0, %1 offset:%2" : "=&v"(r) : "v"(vb), "i"(OFF) : "memory"); return r; }
; template <int H> DI void v_reads(s16x4* vf, int vb) {
;     vf[0] = tr_read<v_rd_off(0, 2 * H, 0)>(vb); vf[1] = tr_read<v_rd_off(0, 2 * H, 1)>(vb); vf[2] = tr_read<v_rd_off(0, 2 * H + 1, 0)>(vb); vf[3] = tr_read<v_rd_off(0, 2 * H + 1, 1)>(vb);
;     vf[4] = tr_read<v_rd_off(1, 2 * H, 0)>(vb); vf[5] = tr_read<v_rd_off(1, 2 * H, 1)>(vb); vf[6] = tr_read<v_rd_off(1, 2 * H + 1, 0)>(vb); vf[7] = tr_read<v_rd_off(1, 2 * H + 1, 1)>(vb);
;     vf[8] = tr_read<v_rd_off(2, 2 * H, 0)>(vb); vf[9] = tr_read<v_rd_off(2, 2 * H, 1)>(vb); vf[10] = tr_read<v_rd_off(2, 2 * H + 1, 0)>(vb); vf[11] = tr_read<v_rd_off(2, 2 * H + 1, 1)>(vb);
;     vf[12] = tr_read<v_rd_off(3, 2 * H, 0)>(vb); vf[13] = tr_read<v_rd_off(3, 2 * H, 1)>(vb); vf[14] = tr_read<v_rd_off(3, 2 * H + 1, 0)>(vb); vf[15] = tr_read<v_rd_off(3, 2 * H + 1, 1)>(vb);
; }
; DI void pv_mma(f32x16* o, const s16x4* vf, bf16x8 pa0, bf16x8 pa1) {
;     ...
; #pragma unroll
;     for (int d0 = 0; d0 < 4; ++d0) {
;         o[d0] = __builtin_amdgcn_mfma_f32_32x32x16_bf16(pa0, ATT_PK(vf[4 * d0], vf[4 * d0 + 1]), o[d0], 0, 0, 0);
;         o[d0] = __builtin_amdgcn_mfma_f32_32x32x16_bf16(pa1, ATT_PK(vf[4 * d0 + 2], vf[4 * d0 + 3]), o[d0], 0, 0, 0); }
;     ...
; }
; template <int DQK, int D0A, int D0B> DI void k_reads(bf16x8* kf, const LAS unsigned char* Ks, int half, int r32, int hi) {
; #pragma unroll
;     for (int d0 = D0A; d0 < D0B; ++d0) kf[d0 - D0A] = *(const LAS bf16x8*)(Ks + half * (32 * DQK * 2) + kswz<DQK>(r32, (d0 * 16 + hi * 8) * 2));
; }
; template <int D0A, int D0B> DI void qk_mma(f32x16& p, const bf16x8* kf, const bf16x8* qr) {
; #pragma unroll
;     for (int d0 = D0A; d0 < D0B; ++d0) {
.LBB0_1942:
	ds_read_b128 v[98:101], v107 offset:28672
	ds_read_b128 v[102:105], v108 offset:28672
	ds_read_b128 v[112:115], v109 offset:28672
	ds_read_b128 v[108:111], v110 offset:28672
	ds_read_b64_tr_b16 v[116:117], v106 offset:0
	ds_read_b64_tr_b16 v[118:119], v106 offset:0x800
	ds_read_b64_tr_b16 v[120:121], v106 offset:0x1000
	ds_read_b64_tr_b16 v[122:123], v106 offset:0x1800
	ds_read_b64_tr_b16 v[124:125], v106 offset:0x200
	ds_read_b64_tr_b16 v[126:127], v106 offset:0xa00
	ds_read_b64_tr_b16 v[132:133], v106 offset:0x1200
	ds_read_b64_tr_b16 v[134:135], v106 offset:0x1a00
	ds_read_b64_tr_b16 v[136:137], v106 offset:0x400
	ds_read_b64_tr_b16 v[138:139], v106 offset:0xc00
	ds_read_b64_tr_b16 v[140:141], v106 offset:0x1400
	ds_read_b64_tr_b16 v[142:143], v106 offset:0x1c00
	ds_read_b64_tr_b16 v[144:145], v106 offset:0x600
	ds_read_b64_tr_b16 v[146:147], v106 offset:0xe00
	ds_read_b64_tr_b16 v[148:149], v106 offset:0x1600
	ds_read_b64_tr_b16 v[150:151], v106 offset:0x1e00
	s_setprio 3
	v_exp_f32_e32 v64, v64
	v_exp_f32_e32 v65, v65
	v_exp_f32_e32 v66, v66
	v_exp_f32_e32 v67, v67
	v_exp_f32_e32 v68, v68
	v_add_f32_e32 v107, 0, v64
	v_exp_f32_e32 v69, v69
	v_add_f32_e32 v107, v65, v107
	v_exp_f32_e32 v70, v70
	v_add_f32_e32 v107, v66, v107
	v_exp_f32_e32 v71, v71
	v_add_f32_e32 v107, v67, v107
	v_exp_f32_e32 v72, v72
	v_add_f32_e32 v107, v68, v107
	v_exp_f32_e32 v73, v73
	v_add_f32_e32 v107, v69, v107
	v_exp_f32_e32 v74, v74
	v_add_f32_e32 v107, v70, v107
	v_exp_f32_e32 v75, v75
	v_add_f32_e32 v107, v71, v107
	v_exp_f32_e32 v76, v76
	v_add_f32_e32 v107, v72, v107
	v_exp_f32_e32 v77, v77
	v_add_f32_e32 v107, v73, v107
	v_exp_f32_e32 v78, v78
	v_add_f32_e32 v107, v74, v107
	v_exp_f32_e32 v79, v79
	v_add_f32_e32 v107, v75, v107
	v_add_f32_e32 v107, v76, v107
	v_add_f32_e32 v107, v77, v107
	v_add_f32_e32 v107, v78, v107
	v_add_f32_e32 v107, v79, v107
	v_add_f32_e32 v96, v107, v96
	v_cvt_pk_bf16_f32 v64, v64, v65
	v_cvt_pk_bf16_f32 v65, v66, v67
	v_cvt_pk_bf16_f32 v66, v68, v69
	v_cvt_pk_bf16_f32 v67, v70, v71
	v_cvt_pk_bf16_f32 v68, v72, v73
	v_cvt_pk_bf16_f32 v69, v74, v75
	v_cvt_pk_bf16_f32 v70, v76, v77
	v_cvt_pk_bf16_f32 v71, v78, v79
	s_nop 0
	v_permlane32_swap_b32_e32 v64, v66
	v_permlane32_swap_b32_e32 v65, v67
	v_permlane32_swap_b32_e32 v68, v70
	v_permlane32_swap_b32_e32 v69, v71
	s_waitcnt lgkmcnt(0)
	s_setprio 0
	v_mfma_f32_32x32x16_bf16 v[0:15], v[64:67], v[116:119], v[0:15]
	s_and_b64 vcc, exec, s[2:3]
	v_mfma_f32_32x32x16_bf16 v[48:63], v[64:67], v[124:127], v[48:63]
	v_mfma_f32_32x32x16_bf16 v[32:47], v[64:67], v[136:139], v[32:47]
	v_mfma_f32_32x32x16_bf16 v[16:31], v[64:67], v[144:147], v[16:31]
	v_mfma_f32_32x32x16_bf16 v[0:15], v[68:71], v[120:123], v[0:15]
	v_mfma_f32_32x32x16_bf16 v[48:63], v[68:71], v[132:135], v[48:63]
	v_mfma_f32_32x32x16_bf16 v[32:47], v[68:71], v[140:143], v[32:47]
	v_mfma_f32_32x32x16_bf16 v[16:31], v[68:71], v[148:151], v[16:31]
	s_waitcnt lgkmcnt(0)
	v_mfma_f32_32x32x16_bf16 v[64:79], v[98:101], v[92:95], 0
	v_mfma_f32_32x32x16_bf16 v[64:79], v[102:105], v[88:91], v[64:79]
	v_mfma_f32_32x32x16_bf16 v[64:79], v[112:115], v[84:87], v[64:79]
	v_mfma_f32_32x32x16_bf16 v[64:79], v[108:111], v[80:83], v[64:79]
	s_cbranch_vccnz .LBB0_1944
	v_add3_u32 v80, s88, v97, v130
	v_add_u32_e32 v88, 0x400, v80
	v_add_u32_e32 v90, 0x408, v80
	v_add_u32_e32 v92, 0x420, v80
	v_add_u32_e32 v94, 0x428, v80
	v_add_u32_e32 v81, 0x440, v80
	v_add_u32_e32 v82, 0x448, v80
	v_add_u32_e32 v84, 0x460, v80
	v_add_u32_e32 v86, 0x468, v80
	ds_read2_b32 v[80:81], v81 offset1:1
	ds_read2_b32 v[82:83], v82 offset1:1
	ds_read2_b32 v[84:85], v84 offset1:1
	ds_read2_b32 v[86:87], v86 offset1:1
	ds_read2_b32 v[88:89], v88 offset1:1
	ds_read2_b32 v[90:91], v90 offset1:1
	ds_read2_b32 v[92:93], v92 offset1:1
	ds_read2_b32 v[94:95], v94 offset1:1
	s_waitcnt lgkmcnt(0)
	v_pk_add_f32 v[78:79], v[78:79], v[86:87]
	v_pk_add_f32 v[76:77], v[76:77], v[84:85]
	v_pk_add_f32 v[74:75], v[74:75], v[82:83]
	v_pk_add_f32 v[72:73], v[72:73], v[80:81]
	v_pk_add_f32 v[70:71], v[70:71], v[94:95]
	v_pk_add_f32 v[68:69], v[68:69], v[92:93]
	v_pk_add_f32 v[66:67], v[66:67], v[90:91]
	v_pk_add_f32 v[64:65], v[64:65], v[88:89]
.LBB0_1944:
	s_lshl_b32 s0, s54, 2
	s_add_i32 s0, s0, 0
	s_add_i32 s0, s0, 0x24000
	ds_read_b64_tr_b16 v[80:81], v106 offset:0x2000
	ds_read_b64_tr_b16 v[82:83], v106 offset:0x2800
	ds_read_b64_tr_b16 v[84:85], v106 offset:0x3000
	ds_read_b64_tr_b16 v[86:87], v106 offset:0x3800
	ds_read_b64_tr_b16 v[88:89], v106 offset:0x2200
	ds_read_b64_tr_b16 v[90:91], v106 offset:0x2a00
	ds_read_b64_tr_b16 v[92:93], v106 offset:0x3200
	ds_read_b64_tr_b16 v[94:95], v106 offset:0x3a00
	ds_read_b64_tr_b16 v[98:99], v106 offset:0x2400
	ds_read_b64_tr_b16 v[100:101], v106 offset:0x2c00
	ds_read_b64_tr_b16 v[102:103], v106 offset:0x3400
	ds_read_b64_tr_b16 v[104:105], v106 offset:0x3c00
	ds_read_b64_tr_b16 v[108:109], v106 offset:0x2600
	ds_read_b64_tr_b16 v[110:111], v106 offset:0x2e00
	ds_read_b64_tr_b16 v[112:113], v106 offset:0x3600
	ds_read_b64_tr_b16 v[114:115], v106 offset:0x3e00
	s_nop 7
	s_setprio 3
	v_exp_f32_e32 v97, v64
	v_exp_f32_e32 v65, v65
	v_exp_f32_e32 v106, v66
	v_exp_f32_e32 v67, v67
	v_exp_f32_e32 v68, v68
	v_add_f32_e32 v64, 0, v97
	v_exp_f32_e32 v69, v69
	v_add_f32_e32 v64, v65, v64
	v_exp_f32_e32 v70, v70
	v_add_f32_e32 v64, v106, v64
	v_exp_f32_e32 v71, v71
	v_add_f32_e32 v64, v67, v64
	v_exp_f32_e32 v72, v72
	v_add_f32_e32 v64, v68, v64
	v_exp_f32_e32 v73, v73
	v_add_f32_e32 v64, v69, v64
	v_exp_f32_e32 v74, v74
	v_add_f32_e32 v64, v70, v64
	v_exp_f32_e32 v75, v75
	v_add_f32_e32 v64, v71, v64
	v_exp_f32_e32 v76, v76
	v_add_f32_e32 v64, v72, v64
	v_exp_f32_e32 v77, v77
	v_add_f32_e32 v64, v73, v64
	v_exp_f32_e32 v78, v78
	v_add_f32_e32 v64, v74, v64
	v_exp_f32_e32 v79, v79
	v_add_f32_e32 v64, v75, v64
	v_add_f32_e32 v64, v76, v64
	v_add_f32_e32 v64, v77, v64
	v_add_f32_e32 v64, v78, v64
	v_add_f32_e32 v64, v79, v64
	v_add_f32_e32 v64, v96, v64
	v_cvt_pk_bf16_f32 v66, v97, v65
	v_cvt_pk_bf16_f32 v67, v106, v67
	v_cvt_pk_bf16_f32 v68, v68, v69
	v_cvt_pk_bf16_f32 v69, v70, v71
	v_cvt_pk_bf16_f32 v70, v72, v73
	v_cvt_pk_bf16_f32 v71, v74, v75
	v_cvt_pk_bf16_f32 v72, v76, v77
	v_cvt_pk_bf16_f32 v73, v78, v79
	s_nop 0
	v_permlane32_swap_b32_e32 v66, v68
	v_permlane32_swap_b32_e32 v67, v69
	v_permlane32_swap_b32_e32 v70, v72
	v_permlane32_swap_b32_e32 v71, v73
	s_waitcnt lgkmcnt(0)
; template <int TAG = 0> DI int fresh_tid(int wv) { int l; asm volatile("v_mbcnt_lo_u32_b32 %0, -1, 0\n\tv_mbcnt_hi_u32_b32 %0, -1, %0 ; site %1" : "=v"(l) : "n"(TAG)); return wv * 64 + l; }
; DI unsigned short f2bf(float x) { unsigned u = __float_as_uint(x); u += 0x7fffu + ((u >> 16) & 1u); return (unsigned short)(u >> 16); }
; DI int crow(int r, int hi) { return (r & 3) + 8 * (r >> 2) + 4 * hi; }
; DI float swap_sum(float v) { auto rr = __builtin_amdgcn_permlane32_swap(__float_as_uint(v), __float_as_uint(v), false, false); return __uint_as_float(rr[0]) + __uint_as_float(rr[1]); }
; template <int DQK, int MODE, int LDQ, int LDK, int LDV> ...
;     ...
;     __builtin_amdgcn_s_setprio(0);
;     ...
;     l_reg = swap_sum(l_reg);
;     { const int lane2 = fresh_tid<110 + MODE>(wv) & 63, r32 = lane2 & 31, hi = lane2 >> 5;
;     if (hi == 0) li_l[r32] = l_reg;
;     asm volatile("s_waitcnt lgkmcnt(0)" ::: "memory");
;     float s0v[MODE == 2 ? 16 : 1][4];
;     if constexpr (MODE == 2) {
; #pragma unroll
;         for (int r = 0; r < 16; ++r)
; #pragma unroll
;             for (int d0 = 0; d0 < 4; ++d0) s0v[r][d0] = S0[(size_t)(wid * 32 + crow(r, hi)) * 512 + d0 * 32 + r32];
;     }
; #pragma unroll
;     for (int r = 0; r < 16; ++r) { const int orow = wid * 32 + crow(r, hi); const float rl = __builtin_amdgcn_rcpf(li_l[crow(r, hi)]);
;         if constexpr (MODE == 0) {
; #pragma unroll
;             for (int d0 = 0; d0 < 4; ++d0) AOb[(size_t)orow * 1024 + d0 * 32 + r32] = f2bf(o[d0][r] * rl);
;         } else if constexpr (MODE == 1) {
; #pragma unroll
;             for (int d0 = 0; d0 < 4; ++d0) S0[(size_t)orow * 512 + d0 * 32 + r32] = o[d0][r] * rl;
	s_setprio 0
	v_mfma_f32_32x32x16_bf16 v[0:15], v[66:69], v[80:83], v[0:15]
	v_mfma_f32_32x32x16_bf16 v[48:63], v[66:69], v[88:91], v[48:63]
	v_mfma_f32_32x32x16_bf16 v[32:47], v[66:69], v[98:101], v[32:47]
	v_mfma_f32_32x32x16_bf16 v[16:31], v[66:69], v[108:111], v[16:31]
	v_mfma_f32_32x32x16_bf16 v[0:15], v[70:73], v[84:87], v[0:15]
	v_mfma_f32_32x32x16_bf16 v[48:63], v[70:73], v[92:95], v[48:63]
	v_mfma_f32_32x32x16_bf16 v[32:47], v[70:73], v[102:105], v[32:47]
	v_mfma_f32_32x32x16_bf16 v[16:31], v[70:73], v[112:115], v[16:31]
	s_setprio 0
	v_mbcnt_lo_u32_b32 v66, -1, 0
	v_mbcnt_hi_u32_b32 v66, -1, v66
	v_mov_b32_e32 v67, v64
	v_and_b32_e32 v65, 31, v66
	v_bfe_u32 v66, v66, 5, 1
	v_permlane32_swap_b32_e32 v64, v67
	v_cmp_eq_u32_e32 vcc, 0, v66
	s_and_saveexec_b64 s[2:3], vcc
	v_lshl_add_u32 v68, v65, 2, s0
	v_add_f32_e32 v64, v64, v67
	ds_write_b32 v68, v64
	s_or_b64 exec, exec, s[2:3]
	s_waitcnt lgkmcnt(0)
	v_lshl_add_u32 v68, v66, 4, s0
	ds_read_b128 v[70:73], v68
	ds_read_b128 v[74:77], v68 offset:32
	s_lshl_b64 s[58:59], s[40:41], 11
	v_readlane_b32 s1, v255, 2
	s_add_u32 s1, s1, s58
	v_readlane_b32 s2, v255, 0
	s_addc_u32 s2, s2, s59
	s_lshl_b32 s3, s87, 2
	s_waitcnt lgkmcnt(0)
	v_rcp_f32_e32 v69, v70
	s_add_u32 s54, s1, s3
	v_lshl_or_b32 v66, v66, 2, s94
	s_addc_u32 s55, s2, 0
	v_lshlrev_b32_e32 v130, 2, v65
	v_ashrrev_i32_e32 v67, 31, v66
	v_lshl_add_u64 v[64:65], s[54:55], 0, v[130:131]
	v_lshlrev_b64 v[78:79], 11, v[66:67]
	v_lshl_add_u64 v[78:79], v[64:65], 0, v[78:79]
	v_mul_f32_e32 v0, v0, v69
	global_store_dword v[78:79], v0, off
	v_mul_f32_e32 v0, v48, v69
	global_store_dword v[78:79], v0, off offset:128
	v_mul_f32_e32 v0, v32, v69
	global_store_dword v[78:79], v0, off offset:256
	v_mul_f32_e32 v0, v16, v69
	global_store_dword v[78:79], v0, off offset:384
	v_rcp_f32_e32 v0, v71
	v_or_b32_e32 v70, 1, v66
	v_ashrrev_i32_e32 v71, 31, v70
	v_lshlrev_b64 v[70:71], 11, v[70:71]
	v_lshl_add_u64 v[70:71], v[64:65], 0, v[70:71]
	v_mul_f32_e32 v1, v1, v0
	global_store_dword v[70:71], v1, off
	v_mul_f32_e32 v1, v49, v0
	global_store_dword v[70:71], v1, off offset:128
	v_mul_f32_e32 v1, v33, v0
	v_mul_f32_e32 v0, v17, v0
	v_rcp_f32_e32 v16, v72
	global_store_dword v[70:71], v0, off offset:384
	v_or_b32_e32 v0, 2, v66
	global_store_dword v[70:71], v1, off offset:256
	v_ashrrev_i32_e32 v1, 31, v0
	v_lshlrev_b64 v[0:1], 11, v[0:1]
	v_lshl_add_u64 v[0:1], v[64:65], 0, v[0:1]
	v_mul_f32_e32 v2, v2, v16
	global_store_dword v[0:1], v2, off
	v_mul_f32_e32 v2, v50, v16
	global_store_dword v[0:1], v2, off offset:128
	v_mul_f32_e32 v2, v34, v16
	global_store_dword v[0:1], v2, off offset:256
	v_mul_f32_e32 v2, v18, v16
	global_store_dword v[0:1], v2, off offset:384
	v_rcp_f32_e32 v2, v73
	v_or_b32_e32 v0, 3, v66
	v_ashrrev_i32_e32 v1, 31, v0
	v_lshlrev_b64 v[0:1], 11, v[0:1]
	v_lshl_add_u64 v[0:1], v[64:65], 0, v[0:1]
	v_mul_f32_e32 v3, v3, v2
	global_store_dword v[0:1], v3, off
	v_mul_f32_e32 v3, v51, v2
	global_store_dword v[0:1], v3, off offset:128
	v_mul_f32_e32 v3, v35, v2
	v_mul_f32_e32 v2, v19, v2
	global_store_dword v[0:1], v2, off offset:384
	v_rcp_f32_e32 v2, v74
	global_store_dword v[0:1], v3, off offset:256
	v_or_b32_e32 v0, 8, v66
	v_ashrrev_i32_e32 v1, 31, v0
	v_lshlrev_b64 v[0:1], 11, v[0:1]
	v_lshl_add_u64 v[0:1], v[64:65], 0, v[0:1]
	v_mul_f32_e32 v3, v4, v2
	global_store_dword v[0:1], v3, off
	v_mul_f32_e32 v3, v52, v2
	global_store_dword v[0:1], v3, off offset:128
	v_mul_f32_e32 v3, v36, v2
	v_mul_f32_e32 v2, v20, v2
	global_store_dword v[0:1], v2, off offset:384
	v_rcp_f32_e32 v2, v75
	global_store_dword v[0:1], v3, off offset:256
	v_or_b32_e32 v0, 9, v66
	v_ashrrev_i32_e32 v1, 31, v0
	v_lshlrev_b64 v[0:1], 11, v[0:1]
	v_lshl_add_u64 v[0:1], v[64:65], 0, v[0:1]
	v_mul_f32_e32 v3, v5, v2
	global_store_dword v[0:1], v3, off
	v_mul_f32_e32 v3, v53, v2
	global_store_dword v[0:1], v3, off offset:128
	v_mul_f32_e32 v3, v37, v2
	v_mul_f32_e32 v2, v21, v2
	global_store_dword v[0:1], v2, off offset:384
	v_rcp_f32_e32 v2, v76
	global_store_dword v[0:1], v3, off offset:256
	v_or_b32_e32 v0, 10, v66
	v_ashrrev_i32_e32 v1, 31, v0
	v_lshlrev_b64 v[0:1], 11, v[0:1]
	v_lshl_add_u64 v[0:1], v[64:65], 0, v[0:1]
	v_mul_f32_e32 v3, v6, v2
	global_store_dword v[0:1], v3, off
	v_mul_f32_e32 v3, v54, v2
	global_store_dword v[0:1], v3, off offset:128
	v_mul_f32_e32 v3, v38, v2
	v_mul_f32_e32 v2, v22, v2
	v_rcp_f32_e32 v6, v77
	global_store_dword v[0:1], v3, off offset:256
	global_store_dword v[0:1], v2, off offset:384
	v_or_b32_e32 v0, 11, v66
	v_ashrrev_i32_e32 v1, 31, v0
	v_lshlrev_b64 v[0:1], 11, v[0:1]
	v_lshl_add_u64 v[4:5], v[64:65], 0, v[0:1]
	v_mul_f32_e32 v0, v7, v6
	global_store_dword v[4:5], v0, off
	v_mul_f32_e32 v0, v55, v6
	global_store_dword v[4:5], v0, off offset:128
	v_mul_f32_e32 v0, v39, v6
	global_store_dword v[4:5], v0, off offset:256
	ds_read_b128 v[0:3], v68 offset:64
	v_mul_f32_e32 v6, v23, v6
	global_store_dword v[4:5], v6, off offset:384
	ds_read_b128 v[4:7], v68 offset:96
	v_or_b32_e32 v16, 16, v66
	s_waitcnt lgkmcnt(0)
; DI unsigned short f2bf(float x) { unsigned u = __float_as_uint(x); u += 0x7fffu + ((u >> 16) & 1u); return (unsigned short)(u >> 16); }
; DI int crow(int r, int hi) { return (r & 3) + 8 * (r >> 2) + 4 * hi; }
; template <int DQK, int MODE, int LDQ, int LDK, int LDV> ...
;     ...
;     for (int r = 0; r < 16; ++r) { const int orow = wid * 32 + crow(r, hi); const float rl = __builtin_amdgcn_rcpf(li_l[crow(r, hi)]);
;         if constexpr (MODE == 0) {
; #pragma unroll
;             for (int d0 = 0; d0 < 4; ++d0) AOb[(size_t)orow * 1024 + d0 * 32 + r32] = f2bf(o[d0][r] * rl);
;         } else if constexpr (MODE == 1) {
; #pragma unroll
;             for (int d0 = 0; d0 < 4; ++d0) S0[(size_t)orow * 512 + d0 * 32 + r32] = o[d0][r] * rl;
; DI void phase4(const Params& p, LAS unsigned char* lds, int wv) {
;     ...
;             __syncthreads();
	v_rcp_f32_e32 v0, v0
	v_ashrrev_i32_e32 v17, 31, v16
	v_lshlrev_b64 v[16:17], 11, v[16:17]
	v_lshl_add_u64 v[16:17], v[64:65], 0, v[16:17]
	v_mul_f32_e32 v8, v8, v0
	global_store_dword v[16:17], v8, off
	v_mul_f32_e32 v8, v56, v0
	global_store_dword v[16:17], v8, off offset:128
	v_mul_f32_e32 v8, v40, v0
	global_store_dword v[16:17], v8, off offset:256
	v_mul_f32_e32 v0, v24, v0
	v_rcp_f32_e32 v8, v1
	global_store_dword v[16:17], v0, off offset:384
	v_or_b32_e32 v0, 17, v66
	v_ashrrev_i32_e32 v1, 31, v0
	v_lshlrev_b64 v[0:1], 11, v[0:1]
	v_lshl_add_u64 v[0:1], v[64:65], 0, v[0:1]
	v_mul_f32_e32 v9, v9, v8
	global_store_dword v[0:1], v9, off
	v_mul_f32_e32 v9, v57, v8
	global_store_dword v[0:1], v9, off offset:128
	v_mul_f32_e32 v9, v41, v8
	v_mul_f32_e32 v8, v25, v8
	v_rcp_f32_e32 v2, v2
	global_store_dword v[0:1], v9, off offset:256
	global_store_dword v[0:1], v8, off offset:384
	v_or_b32_e32 v0, 18, v66
	v_ashrrev_i32_e32 v1, 31, v0
	v_lshlrev_b64 v[0:1], 11, v[0:1]
	v_lshl_add_u64 v[0:1], v[64:65], 0, v[0:1]
	v_mul_f32_e32 v8, v10, v2
	global_store_dword v[0:1], v8, off
	v_mul_f32_e32 v8, v58, v2
	global_store_dword v[0:1], v8, off offset:128
	v_mul_f32_e32 v8, v42, v2
	v_mul_f32_e32 v2, v26, v2
	global_store_dword v[0:1], v2, off offset:384
	v_rcp_f32_e32 v2, v3
	global_store_dword v[0:1], v8, off offset:256
	v_or_b32_e32 v0, 19, v66
	v_ashrrev_i32_e32 v1, 31, v0
	v_lshlrev_b64 v[0:1], 11, v[0:1]
	v_lshl_add_u64 v[0:1], v[64:65], 0, v[0:1]
	v_mul_f32_e32 v3, v11, v2
	global_store_dword v[0:1], v3, off
	v_mul_f32_e32 v3, v59, v2
	global_store_dword v[0:1], v3, off offset:128
	v_mul_f32_e32 v3, v43, v2
	v_mul_f32_e32 v2, v27, v2
	global_store_dword v[0:1], v2, off offset:384
	v_rcp_f32_e32 v2, v4
	global_store_dword v[0:1], v3, off offset:256
	v_or_b32_e32 v0, 24, v66
	v_ashrrev_i32_e32 v1, 31, v0
	v_lshlrev_b64 v[0:1], 11, v[0:1]
	v_lshl_add_u64 v[0:1], v[64:65], 0, v[0:1]
	v_mul_f32_e32 v3, v12, v2
	global_store_dword v[0:1], v3, off
	v_mul_f32_e32 v3, v60, v2
	global_store_dword v[0:1], v3, off offset:128
	v_mul_f32_e32 v3, v44, v2
	v_mul_f32_e32 v2, v28, v2
	global_store_dword v[0:1], v2, off offset:384
	v_rcp_f32_e32 v2, v5
	global_store_dword v[0:1], v3, off offset:256
	v_or_b32_e32 v0, 25, v66
	v_ashrrev_i32_e32 v1, 31, v0
	v_lshlrev_b64 v[0:1], 11, v[0:1]
	v_lshl_add_u64 v[0:1], v[64:65], 0, v[0:1]
	v_mul_f32_e32 v3, v13, v2
	global_store_dword v[0:1], v3, off
	v_mul_f32_e32 v3, v61, v2
	global_store_dword v[0:1], v3, off offset:128
	v_mul_f32_e32 v3, v45, v2
	v_mul_f32_e32 v2, v29, v2
	global_store_dword v[0:1], v2, off offset:384
	v_rcp_f32_e32 v2, v6
	global_store_dword v[0:1], v3, off offset:256
	v_or_b32_e32 v0, 26, v66
	v_ashrrev_i32_e32 v1, 31, v0
	v_lshlrev_b64 v[0:1], 11, v[0:1]
	v_lshl_add_u64 v[0:1], v[64:65], 0, v[0:1]
	v_mul_f32_e32 v3, v14, v2
	global_store_dword v[0:1], v3, off
	v_mul_f32_e32 v3, v62, v2
	global_store_dword v[0:1], v3, off offset:128
	v_mul_f32_e32 v3, v46, v2
	v_mul_f32_e32 v2, v30, v2
	global_store_dword v[0:1], v2, off offset:384
	v_rcp_f32_e32 v2, v7
	global_store_dword v[0:1], v3, off offset:256
	v_or_b32_e32 v0, 27, v66
	v_ashrrev_i32_e32 v1, 31, v0
	v_lshlrev_b64 v[0:1], 11, v[0:1]
	v_lshl_add_u64 v[0:1], v[64:65], 0, v[0:1]
	v_mul_f32_e32 v3, v15, v2
	global_store_dword v[0:1], v3, off
	v_mul_f32_e32 v3, v63, v2
	global_store_dword v[0:1], v3, off offset:128
	v_mul_f32_e32 v3, v47, v2
	v_mul_f32_e32 v2, v31, v2
	global_store_dword v[0:1], v3, off offset:256
	global_store_dword v[0:1], v2, off offset:384
	s_waitcnt vmcnt(0)
	s_barrier
; DI float bf2f(unsigned short h) { return __uint_as_float((unsigned)h << 16); }
; template <int DQK, int MODE, int LDQ, int LDK, int LDV> ...
;     ...
;     int kgo[NKP], vgo[2];
; #pragma unroll
;     for (int i = 0; i < NKP; ++i) { const int L = (wid + 8 * i) * 64 + lane, row = L / CPR, slot = L % CPR, cc = (slot & ~7) | ((slot & 7) ^ ((row >> 1) & 7)); kgo[i] = row * LDK + cc * 8; }
; #pragma unroll
;     for (int i = 0; i < 2; ++i) { const int L = (2 * wid + i) * 64 + lane, st = L >> 5, w5 = L & 31, kk = (st >> 2) * 8 + (w5 >> 2), c = (st & 3) * 32 + (w5 & 3) * 8;
;         const int k = (kk & ~0xC) | ((kk & 4) << 1) | ((kk & 8) >> 1); vgo[i] = k * LDV + c; }
;     ...
;     ATT_DMA_K(0); ATT_DMA_K(1); ATT_DMA_V(0, 0); ATT_DMA_K(2); ATT_DMA_V(1, 1);
;     bf16x8 qr[ND0];
;     { const bf16_t* Qw = Qb + (size_t)(wid * 32 + r32) * LDQ + hi * 8;
; #pragma unroll
;       for (int d0 = 0; d0 < ND0; ++d0) qr[d0] = *(const bf16x8*)(Qw + d0 * 16);
;       if constexpr (MODE == 0) {
;           float ss = 0.f;
; #pragma unroll
;           for (int d0 = 0; d0 < ND0; ++d0)
; #pragma unroll
;               for (int j = 0; j < 8; ++j) { const float f = bf2f((unsigned short)qr[d0][j]); ss += f * f; }
;           ss = swap_sum(ss);
;           const float rstd = rsqrtf(ss * (1.f / DQK) + EPS) * C;
; #pragma unroll
;           for (int d0 = 0; d0 < ND0; ++d0) { const float* g = gq + d0 * 16 + hi * 8;
;               { float f[8]; _Pragma("unroll") for (int j = 0; j < 8; ++j) f[j] = bf2f((unsigned short)qr[d0][j]) * rstd * g[j];
;                 u32x4 w = {cvtpk(f[0], f[1]), cvtpk(f[2], f[3]), cvtpk(f[4], f[5]), cvtpk(f[6], f[7])}; qr[d0] = __builtin_bit_cast(bf16x8, w); asm volatile("" ::: "memory"); } }
;       } }
;     const int qlo = q0 + wid * 32, qpos = qlo + r32;
;     const int tL = MODE == 0 ? 0 : (qlo >= 191 ? (qlo - 127) >> 6 : 0), tR = MODE == 0 ? NT : min(NT, (qlo + 222) >> 6);
;     float fL = 1.f, fR = 1.f; if constexpr (MODE != 0) { fL = __builtin_amdgcn_exp2f(bt[0]); fR = __builtin_amdgcn_exp2f(-bt[448]); }
;     ...
;     const int vbase = (int)(unsigned)(size_t)lds + V_OFF + v_rd_base(lane);
;     ...
;     constexpr int NDA = ND0 > 6 ? 6 : ND0;
;     ...
;     f32x16 pA, pB; bf16x8 pa0, pa1;
;     int v0 = 0, v1 = 1, v2 = 2;
;     ATT_TOP(NKP + 2);
;     { bf16x8 kf[NDA]; k_reads<DQK, 0, NDA>(kf, lds, 0, r32, hi); ATT_LGKM0(); qk_mma<0, NDA>(pA, kf, qr);
	v_mbcnt_lo_u32_b32 v7, -1, 0
	v_mbcnt_hi_u32_b32 v7, -1, v7
	s_mov_b64 s[4:5], 0x880
	v_add_u32_e32 v0, s33, v7
	v_bfe_u32 v4, v0, 2, 2
	v_readfirstlane_b32 s0, v0
	s_ashr_i32 s2, s0, 31
	s_ashr_i32 s1, s0, 6
	v_mov_b32_e32 v1, s0
	v_bfi_b32 v1, s63, v1, v7
	s_lshr_b32 s2, s2, 29
	v_add_u32_e32 v3, s2, v1
	s_lshl_b32 s2, s1, 7
	v_ashrrev_i32_e32 v9, 3, v3
	v_and_b32_e32 v3, 0x1ffffff8, v3
	s_ashr_i32 s3, s2, 4
	v_lshrrev_b32_e32 v0, 1, v0
	v_sub_u32_e32 v1, v1, v3
	v_lshrrev_b32_e32 v3, 1, v9
	v_lshlrev_b32_e32 v18, 3, v7
	s_and_b32 s2, s3, -16
	v_and_b32_e32 v6, 8, v0
	s_lshr_b32 s3, s3, 1
	v_bitop3_b32 v1, v3, v1, 7 bitop3:0x6c
	v_and_b32_e32 v3, 32, v7
	v_and_b32_e32 v5, 24, v18
	s_and_b32 s3, s3, 4
	v_or3_b32 v0, v6, v4, s2
	v_or_b32_e32 v10, v3, v5
	v_or_b32_e32 v0, s3, v0
	v_lshl_or_b32 v96, v0, 11, v10
	v_lshlrev_b32_e32 v0, 11, v9
	v_lshl_add_u32 v0, v1, 3, v0
	v_ashrrev_i32_e32 v1, 31, v0
	v_lshlrev_b64 v[10:11], 1, v[0:1]
	v_lshl_add_u64 v[12:13], s[46:47], 0, v[10:11]
	v_lshl_add_u64 v[12:13], v[12:13], 0, s[4:5]
	s_lshl_b32 s4, s1, 10
	s_add_i32 s94, s4, 0
	s_mov_b32 m0, s94
	v_lshl_add_u64 v[10:11], s[48:49], 0, v[10:11]
	s_mov_b64 s[4:5], 0x40080
	global_load_lds_dwordx4 v[12:13], off
	v_lshl_add_u64 v[12:13], v[10:11], 0, s[4:5]
	s_add_i32 m0, s94, 0x2000
	s_lshl_b32 s4, s1, 11
	v_ashrrev_i32_e32 v97, 31, v96
	global_load_lds_dwordx4 v[12:13], off
	s_add_i32 s6, s4, 0
	v_lshlrev_b64 v[12:13], 1, v[96:97]
	s_add_i32 s48, s6, 0x18000
	v_lshl_add_u64 v[14:15], s[46:47], 0, v[12:13]
	v_lshl_add_u64 v[16:17], v[14:15], 0, s[96:97]
	s_mov_b32 m0, s48
	s_mov_b64 s[4:5], 0xc80
	global_load_lds_dwordx4 v[16:17], off
	v_lshl_add_u64 v[14:15], v[14:15], 0, s[4:5]
	s_add_i32 m0, s6, 0x18400
	s_mov_b64 s[4:5], 0x80080
	v_or_b32_e32 v98, 64, v96
	global_load_lds_dwordx4 v[14:15], off
	v_lshl_add_u64 v[10:11], v[10:11], 0, s[4:5]
	s_add_i32 m0, s94, 0x4000
	v_ashrrev_i32_e32 v99, 31, v98
	global_load_lds_dwordx4 v[10:11], off
	s_add_i32 m0, s6, 0x1c000
	v_lshl_add_u64 v[10:11], s[52:53], 0, v[12:13]
	v_and_b32_e32 v2, 31, v7
	global_load_lds_dwordx4 v[10:11], off
	v_lshl_add_u64 v[10:11], v[98:99], 1, s[52:53]
	s_add_i32 m0, s6, 0x1c400
	s_lshl_b32 s46, s1, 5
	global_load_lds_dwordx4 v[10:11], off
	v_or_b32_e32 v10, s46, v2
	v_ashrrev_i32_e32 v11, 31, v10
	v_bfe_u32 v8, v7, 5, 1
	v_lshlrev_b64 v[10:11], 12, v[10:11]
	v_lshl_add_u64 v[10:11], s[44:45], 0, v[10:11]
	v_lshlrev_b32_e32 v130, 4, v8
	v_lshl_add_u64 v[10:11], v[10:11], 0, v[130:131]
	global_load_dwordx4 v[92:95], v[10:11], off offset:1152
	global_load_dwordx4 v[88:91], v[10:11], off offset:1184
	global_load_dwordx4 v[84:87], v[10:11], off offset:1216
	global_load_dwordx4 v[80:83], v[10:11], off offset:1248
	v_and_b32_e32 v11, 0x70, v18
	v_mov_b32_e32 v9, s88
	v_mov_b32_e32 v10, s81
	v_lshl_add_u32 v114, v2, 7, 0
	v_bitop3_b32 v115, v130, v18, s64 bitop3:0x78
	v_bitop3_b32 v117, v130, v11, 64 bitop3:0x36
	s_add_i32 s4, s46, s89
	ds_read_b32 v9, v9
	ds_read_b32 v10, v10
	s_waitcnt vmcnt(3)
	s_barrier
	v_add_u32_e32 v107, v114, v115
	v_bitop3_b32 v116, v130, v11, 32 bitop3:0x36
	v_add_u32_e32 v109, v114, v117
	v_bitop3_b32 v118, v130, v11, s65 bitop3:0x36
	s_add_i32 s5, s4, 0xffffff81
	v_add_u32_e32 v108, v114, v116
	ds_read_b128 v[12:15], v107
	ds_read_b128 v[16:19], v108
	v_add_u32_e32 v110, v114, v118
	ds_read_b128 v[20:23], v109
	ds_read_b128 v[24:27], v110
	s_ashr_i32 s5, s5, 6
	s_cmpk_gt_i32 s4, 0xbe
	v_or_b32_e32 v111, s4, v2
	s_cselect_b32 s47, s5, 0
	s_addk_i32 s4, 0xde
	s_ashr_i32 s45, s4, 6
	s_waitcnt lgkmcnt(0)
	s_waitcnt vmcnt(0) lgkmcnt(0)
	v_mfma_f32_32x32x16_bf16 v[64:79], v[12:15], v[92:95], 0
	s_cmp_gt_i32 s47, 0
	s_cselect_b64 s[4:5], -1, 0
	s_cmp_lt_i32 s45, 1
	s_cselect_b64 s[6:7], -1, 0
	s_or_b64 s[4:5], s[6:7], s[4:5]
	s_and_b64 vcc, exec, s[4:5]
	v_mfma_f32_32x32x16_bf16 v[64:79], v[16:19], v[88:91], v[64:79]
	v_mfma_f32_32x32x16_bf16 v[64:79], v[20:23], v[84:87], v[64:79]
	v_mfma_f32_32x32x16_bf16 v[64:79], v[24:27], v[80:83], v[64:79]
	s_cbranch_vccnz .LBB0_1948
	v_lshlrev_b32_e32 v8, 2, v8
	v_sub_u32_e32 v8, v8, v111
	v_lshl_add_u32 v8, v8, 2, s88
	ds_read2_b32 v[12:13], v8 offset0:240 offset1:241
	ds_read2_b32 v[14:15], v8 offset0:242 offset1:243
	ds_read2_b32 v[16:17], v8 offset0:248 offset1:249
	ds_read2_b32 v[18:19], v8 offset0:250 offset1:251
	ds_read2_b32 v[20:21], v8 offset0:224 offset1:225
	ds_read2_b32 v[22:23], v8 offset0:226 offset1:227
	ds_read2_b32 v[24:25], v8 offset0:232 offset1:233
	ds_read2_b32 v[26:27], v8 offset0:234 offset1:235
	s_waitcnt lgkmcnt(4)
	v_pk_add_f32 v[78:79], v[78:79], v[18:19]
	v_pk_add_f32 v[76:77], v[76:77], v[16:17]
	v_pk_add_f32 v[74:75], v[74:75], v[14:15]
	v_pk_add_f32 v[72:73], v[72:73], v[12:13]
	s_waitcnt lgkmcnt(0)
	v_pk_add_f32 v[70:71], v[70:71], v[26:27]
	v_pk_add_f32 v[68:69], v[68:69], v[24:25]
	v_pk_add_f32 v[66:67], v[66:67], v[22:23]
	v_pk_add_f32 v[64:65], v[64:65], v[20:21]

; #define LAS __attribute__((address_space(3)))
; DI void expsum(f32x16& p, float& l_reg, bf16x8& pa0, bf16x8& pa1) {
; #pragma unroll
;     for (int r = 0; r < 16; ++r) p[r] = __builtin_amdgcn_exp2f(p[r]);
;     float ps = 0.f;
; #pragma unroll
;     for (int r = 0; r < 16; ++r) ps += p[r];
;     l_reg += ps; asm volatile("" : "+v"(l_reg));
;     ...
;     ATT_PK4(p, 0, pa0); ATT_PK4(p, 8, pa1);
;     ...
; }
; DI int v_rd_base(int lane) { return ((lane & 3) << 3) | (((lane >> 2) & 3) << 6) | (((lane >> 4) & 1) << 5) | (((lane >> 5) & 1) << 8); }
; template <int OFF> DI s16x4 tr_read(int vb) { s16x4 r; asm volatile("ds_read_b64_tr_b16 %0, %1 offset:%2" : "=&v"(r) : "v"(vb), "i"(OFF) : "memory"); return r; }
; template <int H> DI void v_reads(s16x4* vf, int vb) {
;     vf[0] = tr_read<v_rd_off(0, 2 * H, 0)>(vb); vf[1] = tr_read<v_rd_off(0, 2 * H, 1)>(vb); vf[2] = tr_read<v_rd_off(0, 2 * H + 1, 0)>(vb); vf[3] = tr_read<v_rd_off(0, 2 * H + 1, 1)>(vb);
;     vf[4] = tr_read<v_rd_off(1, 2 * H, 0)>(vb); vf[5] = tr_read<v_rd_off(1, 2 * H, 1)>(vb); vf[6] = tr_read<v_rd_off(1, 2 * H + 1, 0)>(vb); vf[7] = tr_read<v_rd_off(1, 2 * H + 1, 1)>(vb);
;     vf[8] = tr_read<v_rd_off(2, 2 * H, 0)>(vb); vf[9] = tr_read<v_rd_off(2, 2 * H, 1)>(vb); vf[10] = tr_read<v_rd_off(2, 2 * H + 1, 0)>(vb); vf[11] = tr_read<v_rd_off(2, 2 * H + 1, 1)>(vb);
;     vf[12] = tr_read<v_rd_off(3, 2 * H, 0)>(vb); vf[13] = tr_read<v_rd_off(3, 2 * H, 1)>(vb); vf[14] = tr_read<v_rd_off(3, 2 * H + 1, 0)>(vb); vf[15] = tr_read<v_rd_off(3, 2 * H + 1, 1)>(vb);
; }
; DI void pv_mma(f32x16* o, const s16x4* vf, bf16x8 pa0, bf16x8 pa1) {
;     ...
; #pragma unroll
;     for (int d0 = 0; d0 < 4; ++d0) {
;         o[d0] = __builtin_amdgcn_mfma_f32_32x32x16_bf16(pa0, ATT_PK(vf[4 * d0], vf[4 * d0 + 1]), o[d0], 0, 0, 0);
;         o[d0] = __builtin_amdgcn_mfma_f32_32x32x16_bf16(pa1, ATT_PK(vf[4 * d0 + 2], vf[4 * d0 + 3]), o[d0], 0, 0, 0); }
;     ...
; }
; template <int DQK, int D0A, int D0B> DI void k_reads(bf16x8* kf, const LAS unsigned char* Ks, int half, int r32, int hi) {
; #pragma unroll
;     for (int d0 = D0A; d0 < D0B; ++d0) kf[d0 - D0A] = *(const LAS bf16x8*)(Ks + half * (32 * DQK * 2) + kswz<DQK>(r32, (d0 * 16 + hi * 8) * 2));
; }
; template <int D0A, int D0B> DI void qk_mma(f32x16& p, const bf16x8* kf, const bf16x8* qr) {
; #pragma unroll
;     for (int d0 = D0A; d0 < D0B; ++d0) {
.LBB0_1953:
	s_add_i32 s3, s0, -1
	s_add_i32 s2, s22, 0xffffa000
	s_and_b32 s2, s2, 0x6000
	v_add_u32_e32 v121, s2, v114
	v_add_u32_e32 v122, v121, v115
	v_add_u32_e32 v126, v121, v116
	ds_read_b128 v[122:125], v122 offset:4096
	ds_read_b128 v[132:135], v126 offset:4096
	v_add_u32_e32 v126, v121, v117
	v_add_u32_e32 v121, v121, v118
	s_lshl_b32 s2, s23, 14
	ds_read_b128 v[136:139], v126 offset:4096
	ds_read_b128 v[140:143], v121 offset:4096
	v_add_u32_e32 v121, s2, v106
	ds_read_b64_tr_b16 v[144:145], v121 offset:0
	ds_read_b64_tr_b16 v[146:147], v121 offset:0x800
	ds_read_b64_tr_b16 v[148:149], v121 offset:0x1000
	ds_read_b64_tr_b16 v[150:151], v121 offset:0x1800
	ds_read_b64_tr_b16 v[152:153], v121 offset:0x200
	ds_read_b64_tr_b16 v[154:155], v121 offset:0xa00
	ds_read_b64_tr_b16 v[156:157], v121 offset:0x1200
	ds_read_b64_tr_b16 v[158:159], v121 offset:0x1a00
	ds_read_b64_tr_b16 v[162:163], v121 offset:0x400
	ds_read_b64_tr_b16 v[164:165], v121 offset:0xc00
	ds_read_b64_tr_b16 v[166:167], v121 offset:0x1400
	ds_read_b64_tr_b16 v[168:169], v121 offset:0x1c00
	ds_read_b64_tr_b16 v[170:171], v121 offset:0x600
	ds_read_b64_tr_b16 v[172:173], v121 offset:0xe00
	ds_read_b64_tr_b16 v[174:175], v121 offset:0x1600
	ds_read_b64_tr_b16 v[176:177], v121 offset:0x1e00
	s_setprio 3
	v_exp_f32_e32 v64, v64
	v_exp_f32_e32 v65, v65
	v_exp_f32_e32 v66, v66
	v_exp_f32_e32 v67, v67
	v_exp_f32_e32 v68, v68
	v_add_f32_e32 v126, 0, v64
	v_exp_f32_e32 v69, v69
	v_add_f32_e32 v126, v65, v126
	v_exp_f32_e32 v70, v70
	v_add_f32_e32 v126, v66, v126
	v_exp_f32_e32 v71, v71
	v_add_f32_e32 v126, v67, v126
	v_exp_f32_e32 v72, v72
	v_add_f32_e32 v126, v68, v126
	v_exp_f32_e32 v73, v73
	v_add_f32_e32 v126, v69, v126
	v_exp_f32_e32 v74, v74
	v_add_f32_e32 v126, v70, v126
	v_exp_f32_e32 v75, v75
	v_add_f32_e32 v126, v71, v126
	v_exp_f32_e32 v76, v76
	v_add_f32_e32 v126, v72, v126
	v_exp_f32_e32 v77, v77
	v_add_f32_e32 v126, v73, v126
	v_exp_f32_e32 v78, v78
	v_add_f32_e32 v126, v74, v126
	v_exp_f32_e32 v79, v79
	v_add_f32_e32 v126, v75, v126
	v_add_f32_e32 v126, v76, v126
	v_add_f32_e32 v126, v77, v126
	v_add_f32_e32 v126, v78, v126
	v_add_f32_e32 v126, v79, v126
	v_add_f32_e32 v120, v126, v120
	v_cvt_pk_bf16_f32 v64, v64, v65
	v_cvt_pk_bf16_f32 v65, v66, v67
	v_cvt_pk_bf16_f32 v66, v68, v69
	v_cvt_pk_bf16_f32 v67, v70, v71
	v_cvt_pk_bf16_f32 v68, v72, v73
	v_cvt_pk_bf16_f32 v69, v74, v75
	v_cvt_pk_bf16_f32 v70, v76, v77
	v_cvt_pk_bf16_f32 v71, v78, v79
	s_nop 0
	v_permlane32_swap_b32_e32 v64, v66
	v_permlane32_swap_b32_e32 v65, v67
	v_permlane32_swap_b32_e32 v68, v70
	v_permlane32_swap_b32_e32 v69, v71
	s_waitcnt lgkmcnt(0)
	s_setprio 0
	v_mfma_f32_32x32x16_bf16 v[0:15], v[64:67], v[144:147], v[0:15]
	s_cmp_lt_i32 s3, s47
	s_cselect_b64 s[74:75], -1, 0
	s_cmp_ge_i32 s3, s52
	s_cselect_b64 s[90:91], -1, 0
	s_or_b64 s[74:75], s[74:75], s[90:91]
	s_and_b64 vcc, exec, s[74:75]
	v_mfma_f32_32x32x16_bf16 v[48:63], v[64:67], v[152:155], v[48:63]
	v_mfma_f32_32x32x16_bf16 v[16:31], v[64:67], v[162:165], v[16:31]
	v_mfma_f32_32x32x16_bf16 v[32:47], v[64:67], v[170:173], v[32:47]
	v_mfma_f32_32x32x16_bf16 v[0:15], v[68:71], v[148:151], v[0:15]
	v_mfma_f32_32x32x16_bf16 v[48:63], v[68:71], v[156:159], v[48:63]
	v_mfma_f32_32x32x16_bf16 v[16:31], v[68:71], v[166:169], v[16:31]
	v_mfma_f32_32x32x16_bf16 v[32:47], v[68:71], v[174:177], v[32:47]
	v_mfma_f32_32x32x16_bf16 v[64:79], v[122:125], v[92:95], 0
	v_mfma_f32_32x32x16_bf16 v[64:79], v[132:135], v[88:91], v[64:79]
	v_mfma_f32_32x32x16_bf16 v[64:79], v[136:139], v[84:87], v[64:79]
	v_mfma_f32_32x32x16_bf16 v[64:79], v[140:143], v[80:83], v[64:79]
	v_add_u32_e32 v122, s7, v119
	s_cbranch_vccnz .LBB0_1955
	v_add_u32_e32 v138, 0x28908, v122
	v_add_u32_e32 v140, 0x28920, v122
	v_add_u32_e32 v142, 0x28928, v122
	v_add_u32_e32 v124, 0x28940, v122
	v_add_u32_e32 v126, 0x28948, v122
	v_add_u32_e32 v132, 0x28960, v122
	v_add_u32_e32 v134, 0x28968, v122
	v_add_u32_e32 v123, 0x28900, v122
	ds_read2_b32 v[124:125], v124 offset1:1
	ds_read2_b32 v[126:127], v126 offset1:1
	ds_read2_b32 v[132:133], v132 offset1:1
	ds_read2_b32 v[134:135], v134 offset1:1
	ds_read2_b32 v[136:137], v123 offset1:1
	ds_read2_b32 v[138:139], v138 offset1:1
	ds_read2_b32 v[140:141], v140 offset1:1
	ds_read2_b32 v[142:143], v142 offset1:1
	s_waitcnt lgkmcnt(0)
	v_pk_add_f32 v[78:79], v[78:79], v[134:135]
	v_pk_add_f32 v[76:77], v[76:77], v[132:133]
	v_pk_add_f32 v[74:75], v[74:75], v[126:127]
	v_pk_add_f32 v[72:73], v[72:73], v[124:125]
	v_pk_add_f32 v[70:71], v[70:71], v[142:143]
	v_pk_add_f32 v[68:69], v[68:69], v[140:141]
	v_pk_add_f32 v[66:67], v[66:67], v[138:139]
	v_pk_add_f32 v[64:65], v[64:65], v[136:137]

; #define LAS __attribute__((address_space(3)))
; DI void expsum(f32x16& p, float& l_reg, bf16x8& pa0, bf16x8& pa1) {
; #pragma unroll
;     for (int r = 0; r < 16; ++r) p[r] = __builtin_amdgcn_exp2f(p[r]);
;     float ps = 0.f;
; #pragma unroll
;     for (int r = 0; r < 16; ++r) ps += p[r];
;     l_reg += ps; asm volatile("" : "+v"(l_reg));
;     ...
;     ATT_PK4(p, 0, pa0); ATT_PK4(p, 8, pa1);
;     ...
; }
; DI int v_rd_base(int lane) { return ((lane & 3) << 3) | (((lane >> 2) & 3) << 6) | (((lane >> 4) & 1) << 5) | (((lane >> 5) & 1) << 8); }
; template <int OFF> DI s16x4 tr_read(int vb) { s16x4 r; asm volatile("ds_read_b64_tr_b16 %0, %1 offset:%2" : "=&v"(r) : "v"(vb), "i"(OFF) : "memory"); return r; }
; template <int H> DI void v_reads(s16x4* vf, int vb) {
;     vf[0] = tr_read<v_rd_off(0, 2 * H, 0)>(vb); vf[1] = tr_read<v_rd_off(0, 2 * H, 1)>(vb); vf[2] = tr_read<v_rd_off(0, 2 * H + 1, 0)>(vb); vf[3] = tr_read<v_rd_off(0, 2 * H + 1, 1)>(vb);
;     vf[4] = tr_read<v_rd_off(1, 2 * H, 0)>(vb); vf[5] = tr_read<v_rd_off(1, 2 * H, 1)>(vb); vf[6] = tr_read<v_rd_off(1, 2 * H + 1, 0)>(vb); vf[7] = tr_read<v_rd_off(1, 2 * H + 1, 1)>(vb);
;     vf[8] = tr_read<v_rd_off(2, 2 * H, 0)>(vb); vf[9] = tr_read<v_rd_off(2, 2 * H, 1)>(vb); vf[10] = tr_read<v_rd_off(2, 2 * H + 1, 0)>(vb); vf[11] = tr_read<v_rd_off(2, 2 * H + 1, 1)>(vb);
;     vf[12] = tr_read<v_rd_off(3, 2 * H, 0)>(vb); vf[13] = tr_read<v_rd_off(3, 2 * H, 1)>(vb); vf[14] = tr_read<v_rd_off(3, 2 * H + 1, 0)>(vb); vf[15] = tr_read<v_rd_off(3, 2 * H + 1, 1)>(vb);
; }
; DI void pv_mma(f32x16* o, const s16x4* vf, bf16x8 pa0, bf16x8 pa1) {
;     ...
; #pragma unroll
;     for (int d0 = 0; d0 < 4; ++d0) {
;         o[d0] = __builtin_amdgcn_mfma_f32_32x32x16_bf16(pa0, ATT_PK(vf[4 * d0], vf[4 * d0 + 1]), o[d0], 0, 0, 0);
;         o[d0] = __builtin_amdgcn_mfma_f32_32x32x16_bf16(pa1, ATT_PK(vf[4 * d0 + 2], vf[4 * d0 + 3]), o[d0], 0, 0, 0); }
;     ...
; }
; template <int DQK, int D0A, int D0B> DI void k_reads(bf16x8* kf, const LAS unsigned char* Ks, int half, int r32, int hi) {
; #pragma unroll
;     for (int d0 = D0A; d0 < D0B; ++d0) kf[d0 - D0A] = *(const LAS bf16x8*)(Ks + half * (32 * DQK * 2) + kswz<DQK>(r32, (d0 * 16 + hi * 8) * 2));
; }
; template <int D0A, int D0B> DI void qk_mma(f32x16& p, const bf16x8* kf, const bf16x8* qr) {
; #pragma unroll
;     for (int d0 = D0A; d0 < D0B; ++d0) {
.LBB0_1961:
	ds_read_b128 v[98:101], v107 offset:12288
	ds_read_b128 v[102:105], v108 offset:12288
	ds_read_b128 v[114:117], v109 offset:12288
	ds_read_b128 v[122:125], v110 offset:12288
	v_lshl_add_u32 v96, s49, 14, v106
	ds_read_b64_tr_b16 v[132:133], v96 offset:0
	ds_read_b64_tr_b16 v[134:135], v96 offset:0x800
	ds_read_b64_tr_b16 v[136:137], v96 offset:0x1000
	ds_read_b64_tr_b16 v[138:139], v96 offset:0x1800
	ds_read_b64_tr_b16 v[140:141], v96 offset:0x200
	ds_read_b64_tr_b16 v[142:143], v96 offset:0xa00
	ds_read_b64_tr_b16 v[144:145], v96 offset:0x1200
	ds_read_b64_tr_b16 v[146:147], v96 offset:0x1a00
	ds_read_b64_tr_b16 v[148:149], v96 offset:0x400
	ds_read_b64_tr_b16 v[150:151], v96 offset:0xc00
	ds_read_b64_tr_b16 v[152:153], v96 offset:0x1400
	ds_read_b64_tr_b16 v[154:155], v96 offset:0x1c00
	ds_read_b64_tr_b16 v[156:157], v96 offset:0x600
	ds_read_b64_tr_b16 v[158:159], v96 offset:0xe00
	ds_read_b64_tr_b16 v[162:163], v96 offset:0x1600
	ds_read_b64_tr_b16 v[164:165], v96 offset:0x1e00
	s_setprio 3
	v_exp_f32_e32 v64, v64
	v_exp_f32_e32 v65, v65
	v_exp_f32_e32 v66, v66
	v_exp_f32_e32 v67, v67
	v_exp_f32_e32 v68, v68
	v_add_f32_e32 v97, 0, v64
	v_exp_f32_e32 v69, v69
	v_add_f32_e32 v97, v65, v97
	v_exp_f32_e32 v70, v70
	v_add_f32_e32 v97, v66, v97
	v_exp_f32_e32 v71, v71
	v_add_f32_e32 v97, v67, v97
	v_exp_f32_e32 v72, v72
	v_add_f32_e32 v97, v68, v97
	v_exp_f32_e32 v73, v73
	v_add_f32_e32 v97, v69, v97
	v_exp_f32_e32 v74, v74
	v_add_f32_e32 v97, v70, v97
	v_exp_f32_e32 v75, v75
	v_add_f32_e32 v97, v71, v97
	v_exp_f32_e32 v76, v76
	v_add_f32_e32 v97, v72, v97
	v_exp_f32_e32 v77, v77
	v_add_f32_e32 v97, v73, v97
	v_exp_f32_e32 v78, v78
	v_add_f32_e32 v97, v74, v97
	v_exp_f32_e32 v79, v79
	v_add_f32_e32 v97, v75, v97
	v_add_f32_e32 v97, v76, v97
	v_add_f32_e32 v97, v77, v97
	v_add_f32_e32 v97, v78, v97
	v_add_f32_e32 v97, v79, v97
	v_add_f32_e32 v97, v97, v120
	v_cvt_pk_bf16_f32 v64, v64, v65
	v_cvt_pk_bf16_f32 v65, v66, v67
	v_cvt_pk_bf16_f32 v66, v68, v69
	v_cvt_pk_bf16_f32 v67, v70, v71
	v_cvt_pk_bf16_f32 v68, v72, v73
	v_cvt_pk_bf16_f32 v69, v74, v75
	v_cvt_pk_bf16_f32 v70, v76, v77
	v_cvt_pk_bf16_f32 v71, v78, v79
	s_nop 0
	v_permlane32_swap_b32_e32 v64, v66
	v_permlane32_swap_b32_e32 v65, v67
	v_permlane32_swap_b32_e32 v68, v70
	v_permlane32_swap_b32_e32 v69, v71
	s_waitcnt lgkmcnt(0)
	s_setprio 0
	v_mfma_f32_32x32x16_bf16 v[0:15], v[64:67], v[132:135], v[0:15]
	s_cmp_gt_i32 s47, 61
	s_cselect_b64 s[0:1], -1, 0
	s_cmp_lt_i32 s45, 62
	s_cselect_b64 s[2:3], -1, 0
	s_or_b64 s[0:1], s[0:1], s[2:3]
	s_and_b64 vcc, exec, s[0:1]
	v_mfma_f32_32x32x16_bf16 v[48:63], v[64:67], v[140:143], v[48:63]
	v_mfma_f32_32x32x16_bf16 v[16:31], v[64:67], v[148:151], v[16:31]
	v_mfma_f32_32x32x16_bf16 v[32:47], v[64:67], v[156:159], v[32:47]
	v_mfma_f32_32x32x16_bf16 v[0:15], v[68:71], v[136:139], v[0:15]
	v_mfma_f32_32x32x16_bf16 v[48:63], v[68:71], v[144:147], v[48:63]
	v_mfma_f32_32x32x16_bf16 v[16:31], v[68:71], v[152:155], v[16:31]
	v_mfma_f32_32x32x16_bf16 v[32:47], v[68:71], v[162:165], v[32:47]
	s_waitcnt lgkmcnt(0)
	v_mfma_f32_32x32x16_bf16 v[64:79], v[98:101], v[92:95], 0
	v_mfma_f32_32x32x16_bf16 v[64:79], v[102:105], v[88:91], v[64:79]
	v_mfma_f32_32x32x16_bf16 v[64:79], v[114:117], v[84:87], v[64:79]
	v_mfma_f32_32x32x16_bf16 v[64:79], v[122:125], v[80:83], v[64:79]
	s_cbranch_vccnz .LBB0_1963
	v_sub_u32_e32 v98, 0xf40, v111
	v_lshlrev_b32_e32 v98, 2, v98
	v_add3_u32 v98, s88, v98, v130
	v_add_u32_e32 v114, 0x400, v98
	v_add_u32_e32 v116, 0x408, v98
	v_add_u32_e32 v118, 0x420, v98
	v_add_u32_e32 v120, 0x428, v98
	v_add_u32_e32 v99, 0x440, v98
	v_add_u32_e32 v100, 0x448, v98
	v_add_u32_e32 v102, 0x460, v98
	v_add_u32_e32 v104, 0x468, v98
	ds_read2_b32 v[98:99], v99 offset1:1
	ds_read2_b32 v[100:101], v100 offset1:1
	ds_read2_b32 v[102:103], v102 offset1:1
	ds_read2_b32 v[104:105], v104 offset1:1
	ds_read2_b32 v[114:115], v114 offset1:1
	ds_read2_b32 v[116:117], v116 offset1:1
	ds_read2_b32 v[118:119], v118 offset1:1
	ds_read2_b32 v[120:121], v120 offset1:1
	s_waitcnt lgkmcnt(0)
	v_pk_add_f32 v[78:79], v[78:79], v[104:105]
	v_pk_add_f32 v[76:77], v[76:77], v[102:103]
	v_pk_add_f32 v[74:75], v[74:75], v[100:101]
	v_pk_add_f32 v[72:73], v[72:73], v[98:99]
	v_pk_add_f32 v[70:71], v[70:71], v[120:121]
	v_pk_add_f32 v[68:69], v[68:69], v[118:119]
	v_pk_add_f32 v[66:67], v[66:67], v[116:117]
	v_pk_add_f32 v[64:65], v[64:65], v[114:115]
.LBB0_1963:
	ds_read_b128 v[98:101], v107 offset:16384
	ds_read_b128 v[102:105], v108 offset:16384
	ds_read_b128 v[114:117], v109 offset:16384
	ds_read_b128 v[118:121], v110 offset:16384
	ds_read_b64_tr_b16 v[122:123], v96 offset:0x2000
	ds_read_b64_tr_b16 v[124:125], v96 offset:0x2800
	ds_read_b64_tr_b16 v[132:133], v96 offset:0x3000
	ds_read_b64_tr_b16 v[134:135], v96 offset:0x3800
	ds_read_b64_tr_b16 v[136:137], v96 offset:0x2200
	ds_read_b64_tr_b16 v[138:139], v96 offset:0x2a00
	ds_read_b64_tr_b16 v[140:141], v96 offset:0x3200
	ds_read_b64_tr_b16 v[142:143], v96 offset:0x3a00
	ds_read_b64_tr_b16 v[144:145], v96 offset:0x2400
	ds_read_b64_tr_b16 v[146:147], v96 offset:0x2c00
	ds_read_b64_tr_b16 v[148:149], v96 offset:0x3400
	ds_read_b64_tr_b16 v[150:151], v96 offset:0x3c00
	ds_read_b64_tr_b16 v[152:153], v96 offset:0x2600
	ds_read_b64_tr_b16 v[154:155], v96 offset:0x2e00
	ds_read_b64_tr_b16 v[156:157], v96 offset:0x3600
	ds_read_b64_tr_b16 v[158:159], v96 offset:0x3e00
	s_nop 6
	s_setprio 3
	v_exp_f32_e32 v64, v64
	v_exp_f32_e32 v65, v65
	v_exp_f32_e32 v66, v66
	v_exp_f32_e32 v67, v67
	v_exp_f32_e32 v68, v68
	v_add_f32_e32 v96, 0, v64
	v_exp_f32_e32 v69, v69
	v_add_f32_e32 v96, v65, v96
	v_exp_f32_e32 v70, v70
	v_add_f32_e32 v96, v66, v96
	v_exp_f32_e32 v71, v71
	v_add_f32_e32 v96, v67, v96
	v_exp_f32_e32 v72, v72
	v_add_f32_e32 v96, v68, v96
	v_exp_f32_e32 v73, v73
	v_add_f32_e32 v96, v69, v96
	v_exp_f32_e32 v74, v74
	v_add_f32_e32 v96, v70, v96
	v_exp_f32_e32 v75, v75
	v_add_f32_e32 v96, v71, v96
	v_exp_f32_e32 v76, v76
	v_add_f32_e32 v96, v72, v96
	v_exp_f32_e32 v77, v77
	v_add_f32_e32 v96, v73, v96
	v_exp_f32_e32 v78, v78
	v_add_f32_e32 v96, v74, v96
	v_exp_f32_e32 v79, v79
	v_add_f32_e32 v96, v75, v96
	v_add_f32_e32 v96, v76, v96
	v_add_f32_e32 v96, v77, v96
	v_add_f32_e32 v96, v78, v96
	v_add_f32_e32 v96, v79, v96
	v_add_f32_e32 v96, v97, v96
	v_cvt_pk_bf16_f32 v64, v64, v65
	v_cvt_pk_bf16_f32 v65, v66, v67
	v_cvt_pk_bf16_f32 v66, v68, v69
	v_cvt_pk_bf16_f32 v67, v70, v71
	v_cvt_pk_bf16_f32 v68, v72, v73
	v_cvt_pk_bf16_f32 v69, v74, v75
	v_cvt_pk_bf16_f32 v70, v76, v77
	v_cvt_pk_bf16_f32 v71, v78, v79
	s_nop 0
	v_permlane32_swap_b32_e32 v64, v66
	v_permlane32_swap_b32_e32 v65, v67
	v_permlane32_swap_b32_e32 v68, v70
	v_permlane32_swap_b32_e32 v69, v71
	s_waitcnt lgkmcnt(0)
	s_setprio 0
	s_cmp_lt_u32 s33, 0x100
	s_cbranch_scc1 .Lstg_d1_m61_21
	s_waitcnt vmcnt(0)
	s_barrier

; #define LAS __attribute__((address_space(3)))
; DI void expsum(f32x16& p, float& l_reg, bf16x8& pa0, bf16x8& pa1) {
; #pragma unroll
;     for (int r = 0; r < 16; ++r) p[r] = __builtin_amdgcn_exp2f(p[r]);
;     float ps = 0.f;
; #pragma unroll
;     for (int r = 0; r < 16; ++r) ps += p[r];
;     l_reg += ps; asm volatile("" : "+v"(l_reg));
;     ...
;     ATT_PK4(p, 0, pa0); ATT_PK4(p, 8, pa1);
;     ...
; }
; DI int v_rd_base(int lane) { return ((lane & 3) << 3) | (((lane >> 2) & 3) << 6) | (((lane >> 4) & 1) << 5) | (((lane >> 5) & 1) << 8); }
; template <int OFF> DI s16x4 tr_read(int vb) { s16x4 r; asm volatile("ds_read_b64_tr_b16 %0, %1 offset:%2" : "=&v"(r) : "v"(vb), "i"(OFF) : "memory"); return r; }
; template <int H> DI void v_reads(s16x4* vf, int vb) {
;     vf[0] = tr_read<v_rd_off(0, 2 * H, 0)>(vb); vf[1] = tr_read<v_rd_off(0, 2 * H, 1)>(vb); vf[2] = tr_read<v_rd_off(0, 2 * H + 1, 0)>(vb); vf[3] = tr_read<v_rd_off(0, 2 * H + 1, 1)>(vb);
;     vf[4] = tr_read<v_rd_off(1, 2 * H, 0)>(vb); vf[5] = tr_read<v_rd_off(1, 2 * H, 1)>(vb); vf[6] = tr_read<v_rd_off(1, 2 * H + 1, 0)>(vb); vf[7] = tr_read<v_rd_off(1, 2 * H + 1, 1)>(vb);
;     vf[8] = tr_read<v_rd_off(2, 2 * H, 0)>(vb); vf[9] = tr_read<v_rd_off(2, 2 * H, 1)>(vb); vf[10] = tr_read<v_rd_off(2, 2 * H + 1, 0)>(vb); vf[11] = tr_read<v_rd_off(2, 2 * H + 1, 1)>(vb);
;     vf[12] = tr_read<v_rd_off(3, 2 * H, 0)>(vb); vf[13] = tr_read<v_rd_off(3, 2 * H, 1)>(vb); vf[14] = tr_read<v_rd_off(3, 2 * H + 1, 0)>(vb); vf[15] = tr_read<v_rd_off(3, 2 * H + 1, 1)>(vb);
; }
; DI void pv_mma(f32x16* o, const s16x4* vf, bf16x8 pa0, bf16x8 pa1) {
;     ...
; #pragma unroll
;     for (int d0 = 0; d0 < 4; ++d0) {
;         o[d0] = __builtin_amdgcn_mfma_f32_32x32x16_bf16(pa0, ATT_PK(vf[4 * d0], vf[4 * d0 + 1]), o[d0], 0, 0, 0);
;         o[d0] = __builtin_amdgcn_mfma_f32_32x32x16_bf16(pa1, ATT_PK(vf[4 * d0 + 2], vf[4 * d0 + 3]), o[d0], 0, 0, 0); }
;     ...
; }
; template <int DQK, int D0A, int D0B> DI void k_reads(bf16x8* kf, const LAS unsigned char* Ks, int half, int r32, int hi) {
; #pragma unroll
;     for (int d0 = D0A; d0 < D0B; ++d0) kf[d0 - D0A] = *(const LAS bf16x8*)(Ks + half * (32 * DQK * 2) + kswz<DQK>(r32, (d0 * 16 + hi * 8) * 2));
; }
; template <int D0A, int D0B> DI void qk_mma(f32x16& p, const bf16x8* kf, const bf16x8* qr) {
; #pragma unroll
;     for (int d0 = D0A; d0 < D0B; ++d0) {
.LBB0_1967:
	ds_read_b128 v[100:103], v107 offset:20480
	ds_read_b128 v[114:117], v108 offset:20480
	ds_read_b128 v[118:121], v109 offset:20480
	ds_read_b128 v[122:125], v110 offset:20480
	v_add_u32_e32 v98, 0x8000, v106
	ds_read_b64_tr_b16 v[132:133], v98 offset:0
	ds_read_b64_tr_b16 v[134:135], v98 offset:0x800
	ds_read_b64_tr_b16 v[136:137], v98 offset:0x1000
	ds_read_b64_tr_b16 v[138:139], v98 offset:0x1800
	ds_read_b64_tr_b16 v[140:141], v98 offset:0x200
	ds_read_b64_tr_b16 v[142:143], v98 offset:0xa00
	ds_read_b64_tr_b16 v[144:145], v98 offset:0x1200
	ds_read_b64_tr_b16 v[146:147], v98 offset:0x1a00
	ds_read_b64_tr_b16 v[148:149], v98 offset:0x400
	ds_read_b64_tr_b16 v[150:151], v98 offset:0xc00
	ds_read_b64_tr_b16 v[152:153], v98 offset:0x1400
	ds_read_b64_tr_b16 v[154:155], v98 offset:0x1c00
	ds_read_b64_tr_b16 v[156:157], v98 offset:0x600
	ds_read_b64_tr_b16 v[158:159], v98 offset:0xe00
	ds_read_b64_tr_b16 v[162:163], v98 offset:0x1600
	ds_read_b64_tr_b16 v[164:165], v98 offset:0x1e00
	s_setprio 3
	v_exp_f32_e32 v64, v64
	v_exp_f32_e32 v65, v65
	v_exp_f32_e32 v66, v66
	v_exp_f32_e32 v67, v67
	v_exp_f32_e32 v68, v68
	v_add_f32_e32 v99, 0, v64
	v_exp_f32_e32 v69, v69
	v_add_f32_e32 v99, v65, v99
	v_exp_f32_e32 v70, v70
	v_add_f32_e32 v99, v66, v99
	v_exp_f32_e32 v71, v71
	v_add_f32_e32 v99, v67, v99
	v_exp_f32_e32 v72, v72
	v_add_f32_e32 v99, v68, v99
	v_exp_f32_e32 v73, v73
	v_add_f32_e32 v99, v69, v99
	v_exp_f32_e32 v74, v74
	v_add_f32_e32 v99, v70, v99
	v_exp_f32_e32 v75, v75
	v_add_f32_e32 v99, v71, v99
	v_exp_f32_e32 v76, v76
	v_add_f32_e32 v99, v72, v99
	v_exp_f32_e32 v77, v77
	v_add_f32_e32 v99, v73, v99
	v_exp_f32_e32 v78, v78
	v_add_f32_e32 v99, v74, v99
	v_exp_f32_e32 v79, v79
	v_add_f32_e32 v99, v75, v99
	v_add_f32_e32 v99, v76, v99
	v_add_f32_e32 v99, v77, v99
	v_add_f32_e32 v99, v78, v99
	v_add_f32_e32 v99, v79, v99
	v_add_f32_e32 v96, v99, v96
	v_cvt_pk_bf16_f32 v64, v64, v65
	v_cvt_pk_bf16_f32 v65, v66, v67
	v_cvt_pk_bf16_f32 v66, v68, v69
	v_cvt_pk_bf16_f32 v67, v70, v71
	v_cvt_pk_bf16_f32 v68, v72, v73
	v_cvt_pk_bf16_f32 v69, v74, v75
	v_cvt_pk_bf16_f32 v70, v76, v77
	v_cvt_pk_bf16_f32 v71, v78, v79
	s_nop 0
	v_permlane32_swap_b32_e32 v64, v66
	v_permlane32_swap_b32_e32 v65, v67
	v_permlane32_swap_b32_e32 v68, v70
	v_permlane32_swap_b32_e32 v69, v71
	s_waitcnt lgkmcnt(0)
	s_setprio 0
	v_mfma_f32_32x32x16_bf16 v[0:15], v[64:67], v[132:135], v[0:15]
	s_and_b64 vcc, exec, s[2:3]
	v_mfma_f32_32x32x16_bf16 v[48:63], v[64:67], v[140:143], v[48:63]
	v_mfma_f32_32x32x16_bf16 v[16:31], v[64:67], v[148:151], v[16:31]
	v_mfma_f32_32x32x16_bf16 v[32:47], v[64:67], v[156:159], v[32:47]
	v_mfma_f32_32x32x16_bf16 v[0:15], v[68:71], v[136:139], v[0:15]
	v_mfma_f32_32x32x16_bf16 v[48:63], v[68:71], v[144:147], v[48:63]
	v_mfma_f32_32x32x16_bf16 v[16:31], v[68:71], v[152:155], v[16:31]
	v_mfma_f32_32x32x16_bf16 v[32:47], v[68:71], v[162:165], v[32:47]
	s_waitcnt lgkmcnt(0)
	v_mfma_f32_32x32x16_bf16 v[64:79], v[100:103], v[92:95], 0
	v_mfma_f32_32x32x16_bf16 v[64:79], v[114:117], v[88:91], v[64:79]
	v_mfma_f32_32x32x16_bf16 v[64:79], v[118:121], v[84:87], v[64:79]
	v_mfma_f32_32x32x16_bf16 v[64:79], v[122:125], v[80:83], v[64:79]
	s_cbranch_vccnz .LBB0_1969
	v_add3_u32 v97, s88, v97, v130
	v_add_u32_e32 v118, 0x408, v97
	v_add_u32_e32 v120, 0x420, v97
	v_add_u32_e32 v122, 0x428, v97
	v_add_u32_e32 v100, 0x440, v97
	v_add_u32_e32 v102, 0x448, v97
	v_add_u32_e32 v104, 0x460, v97
	v_add_u32_e32 v99, 0x400, v97
	v_add_u32_e32 v97, 0x468, v97
	ds_read2_b32 v[100:101], v100 offset1:1
	ds_read2_b32 v[102:103], v102 offset1:1
	ds_read2_b32 v[104:105], v104 offset1:1
	ds_read2_b32 v[114:115], v97 offset1:1
	ds_read2_b32 v[116:117], v99 offset1:1
	ds_read2_b32 v[118:119], v118 offset1:1
	ds_read2_b32 v[120:121], v120 offset1:1
	ds_read2_b32 v[122:123], v122 offset1:1
	s_waitcnt lgkmcnt(0)
	v_pk_add_f32 v[78:79], v[78:79], v[114:115]
	v_pk_add_f32 v[76:77], v[76:77], v[104:105]
	v_pk_add_f32 v[74:75], v[74:75], v[102:103]
	v_pk_add_f32 v[72:73], v[72:73], v[100:101]
	v_pk_add_f32 v[70:71], v[70:71], v[122:123]
	v_pk_add_f32 v[68:69], v[68:69], v[120:121]
	v_pk_add_f32 v[66:67], v[66:67], v[118:119]
	v_pk_add_f32 v[64:65], v[64:65], v[116:117]

; #define LAS __attribute__((address_space(3)))
; DI void expsum(f32x16& p, float& l_reg, bf16x8& pa0, bf16x8& pa1) {
; #pragma unroll
;     for (int r = 0; r < 16; ++r) p[r] = __builtin_amdgcn_exp2f(p[r]);
;     float ps = 0.f;
; #pragma unroll
;     for (int r = 0; r < 16; ++r) ps += p[r];
;     l_reg += ps; asm volatile("" : "+v"(l_reg));
;     ...
;     ATT_PK4(p, 0, pa0); ATT_PK4(p, 8, pa1);
;     ...
; }
; DI int v_rd_base(int lane) { return ((lane & 3) << 3) | (((lane >> 2) & 3) << 6) | (((lane >> 4) & 1) << 5) | (((lane >> 5) & 1) << 8); }
; template <int OFF> DI s16x4 tr_read(int vb) { s16x4 r; asm volatile("ds_read_b64_tr_b16 %0, %1 offset:%2" : "=&v"(r) : "v"(vb), "i"(OFF) : "memory"); return r; }
; template <int H> DI void v_reads(s16x4* vf, int vb) {
;     vf[0] = tr_read<v_rd_off(0, 2 * H, 0)>(vb); vf[1] = tr_read<v_rd_off(0, 2 * H, 1)>(vb); vf[2] = tr_read<v_rd_off(0, 2 * H + 1, 0)>(vb); vf[3] = tr_read<v_rd_off(0, 2 * H + 1, 1)>(vb);
;     vf[4] = tr_read<v_rd_off(1, 2 * H, 0)>(vb); vf[5] = tr_read<v_rd_off(1, 2 * H, 1)>(vb); vf[6] = tr_read<v_rd_off(1, 2 * H + 1, 0)>(vb); vf[7] = tr_read<v_rd_off(1, 2 * H + 1, 1)>(vb);
;     vf[8] = tr_read<v_rd_off(2, 2 * H, 0)>(vb); vf[9] = tr_read<v_rd_off(2, 2 * H, 1)>(vb); vf[10] = tr_read<v_rd_off(2, 2 * H + 1, 0)>(vb); vf[11] = tr_read<v_rd_off(2, 2 * H + 1, 1)>(vb);
;     vf[12] = tr_read<v_rd_off(3, 2 * H, 0)>(vb); vf[13] = tr_read<v_rd_off(3, 2 * H, 1)>(vb); vf[14] = tr_read<v_rd_off(3, 2 * H + 1, 0)>(vb); vf[15] = tr_read<v_rd_off(3, 2 * H + 1, 1)>(vb);
; }
; DI void pv_mma(f32x16* o, const s16x4* vf, bf16x8 pa0, bf16x8 pa1) {
;     ...
; #pragma unroll
;     for (int d0 = 0; d0 < 4; ++d0) {
;         o[d0] = __builtin_amdgcn_mfma_f32_32x32x16_bf16(pa0, ATT_PK(vf[4 * d0], vf[4 * d0 + 1]), o[d0], 0, 0, 0);
;         o[d0] = __builtin_amdgcn_mfma_f32_32x32x16_bf16(pa1, ATT_PK(vf[4 * d0 + 2], vf[4 * d0 + 3]), o[d0], 0, 0, 0); }
;     ...
; }
; template <int DQK, int D0A, int D0B> DI void k_reads(bf16x8* kf, const LAS unsigned char* Ks, int half, int r32, int hi) {
; #pragma unroll
;     for (int d0 = D0A; d0 < D0B; ++d0) kf[d0 - D0A] = *(const LAS bf16x8*)(Ks + half * (32 * DQK * 2) + kswz<DQK>(r32, (d0 * 16 + hi * 8) * 2));
; }
; template <int D0A, int D0B> DI void qk_mma(f32x16& p, const bf16x8* kf, const bf16x8* qr) {
; #pragma unroll
;     for (int d0 = D0A; d0 < D0B; ++d0) {
.LBB0_1973:
	ds_read_b128 v[98:101], v107 offset:28672
	ds_read_b128 v[102:105], v108 offset:28672
	ds_read_b128 v[112:115], v109 offset:28672
	ds_read_b128 v[108:111], v110 offset:28672
	ds_read_b64_tr_b16 v[116:117], v106 offset:0
	ds_read_b64_tr_b16 v[118:119], v106 offset:0x800
	ds_read_b64_tr_b16 v[120:121], v106 offset:0x1000
	ds_read_b64_tr_b16 v[122:123], v106 offset:0x1800
	ds_read_b64_tr_b16 v[124:125], v106 offset:0x200
	ds_read_b64_tr_b16 v[126:127], v106 offset:0xa00
	ds_read_b64_tr_b16 v[132:133], v106 offset:0x1200
	ds_read_b64_tr_b16 v[134:135], v106 offset:0x1a00
	ds_read_b64_tr_b16 v[136:137], v106 offset:0x400
	ds_read_b64_tr_b16 v[138:139], v106 offset:0xc00
	ds_read_b64_tr_b16 v[140:141], v106 offset:0x1400
	ds_read_b64_tr_b16 v[142:143], v106 offset:0x1c00
	ds_read_b64_tr_b16 v[144:145], v106 offset:0x600
	ds_read_b64_tr_b16 v[146:147], v106 offset:0xe00
	ds_read_b64_tr_b16 v[148:149], v106 offset:0x1600
	ds_read_b64_tr_b16 v[150:151], v106 offset:0x1e00
	s_setprio 3
	v_exp_f32_e32 v64, v64
	v_exp_f32_e32 v65, v65
	v_exp_f32_e32 v66, v66
	v_exp_f32_e32 v67, v67
	v_exp_f32_e32 v68, v68
	v_add_f32_e32 v107, 0, v64
	v_exp_f32_e32 v69, v69
	v_add_f32_e32 v107, v65, v107
	v_exp_f32_e32 v70, v70
	v_add_f32_e32 v107, v66, v107
	v_exp_f32_e32 v71, v71
	v_add_f32_e32 v107, v67, v107
	v_exp_f32_e32 v72, v72
	v_add_f32_e32 v107, v68, v107
	v_exp_f32_e32 v73, v73
	v_add_f32_e32 v107, v69, v107
	v_exp_f32_e32 v74, v74
	v_add_f32_e32 v107, v70, v107
	v_exp_f32_e32 v75, v75
	v_add_f32_e32 v107, v71, v107
	v_exp_f32_e32 v76, v76
	v_add_f32_e32 v107, v72, v107
	v_exp_f32_e32 v77, v77
	v_add_f32_e32 v107, v73, v107
	v_exp_f32_e32 v78, v78
	v_add_f32_e32 v107, v74, v107
	v_exp_f32_e32 v79, v79
	v_add_f32_e32 v107, v75, v107
	v_add_f32_e32 v107, v76, v107
	v_add_f32_e32 v107, v77, v107
	v_add_f32_e32 v107, v78, v107
	v_add_f32_e32 v107, v79, v107
	v_add_f32_e32 v96, v107, v96
	v_cvt_pk_bf16_f32 v64, v64, v65
	v_cvt_pk_bf16_f32 v65, v66, v67
	v_cvt_pk_bf16_f32 v66, v68, v69
	v_cvt_pk_bf16_f32 v67, v70, v71
	v_cvt_pk_bf16_f32 v68, v72, v73
	v_cvt_pk_bf16_f32 v69, v74, v75
	v_cvt_pk_bf16_f32 v70, v76, v77
	v_cvt_pk_bf16_f32 v71, v78, v79
	s_nop 0
	v_permlane32_swap_b32_e32 v64, v66
	v_permlane32_swap_b32_e32 v65, v67
	v_permlane32_swap_b32_e32 v68, v70
	v_permlane32_swap_b32_e32 v69, v71
	s_waitcnt lgkmcnt(0)
	s_setprio 0
	v_mfma_f32_32x32x16_bf16 v[0:15], v[64:67], v[116:119], v[0:15]
	s_and_b64 vcc, exec, s[2:3]
	v_mfma_f32_32x32x16_bf16 v[48:63], v[64:67], v[124:127], v[48:63]
	v_mfma_f32_32x32x16_bf16 v[16:31], v[64:67], v[136:139], v[16:31]
	v_mfma_f32_32x32x16_bf16 v[32:47], v[64:67], v[144:147], v[32:47]
	v_mfma_f32_32x32x16_bf16 v[0:15], v[68:71], v[120:123], v[0:15]
	v_mfma_f32_32x32x16_bf16 v[48:63], v[68:71], v[132:135], v[48:63]
	v_mfma_f32_32x32x16_bf16 v[16:31], v[68:71], v[140:143], v[16:31]
	v_mfma_f32_32x32x16_bf16 v[32:47], v[68:71], v[148:151], v[32:47]
	s_waitcnt lgkmcnt(0)
	v_mfma_f32_32x32x16_bf16 v[64:79], v[98:101], v[92:95], 0
	v_mfma_f32_32x32x16_bf16 v[64:79], v[102:105], v[88:91], v[64:79]
	v_mfma_f32_32x32x16_bf16 v[64:79], v[112:115], v[84:87], v[64:79]
	v_mfma_f32_32x32x16_bf16 v[64:79], v[108:111], v[80:83], v[64:79]
	s_cbranch_vccnz .LBB0_1975
	v_add3_u32 v80, s88, v97, v130
	v_add_u32_e32 v88, 0x400, v80
	v_add_u32_e32 v90, 0x408, v80
	v_add_u32_e32 v92, 0x420, v80
	v_add_u32_e32 v94, 0x428, v80
	v_add_u32_e32 v81, 0x440, v80
	v_add_u32_e32 v82, 0x448, v80
	v_add_u32_e32 v84, 0x460, v80
	v_add_u32_e32 v86, 0x468, v80
	ds_read2_b32 v[80:81], v81 offset1:1
	ds_read2_b32 v[82:83], v82 offset1:1
	ds_read2_b32 v[84:85], v84 offset1:1
	ds_read2_b32 v[86:87], v86 offset1:1
	ds_read2_b32 v[88:89], v88 offset1:1
	ds_read2_b32 v[90:91], v90 offset1:1
	ds_read2_b32 v[92:93], v92 offset1:1
	ds_read2_b32 v[94:95], v94 offset1:1
	s_waitcnt lgkmcnt(0)
	v_pk_add_f32 v[78:79], v[78:79], v[86:87]
	v_pk_add_f32 v[76:77], v[76:77], v[84:85]
	v_pk_add_f32 v[74:75], v[74:75], v[82:83]
	v_pk_add_f32 v[72:73], v[72:73], v[80:81]
	v_pk_add_f32 v[70:71], v[70:71], v[94:95]
	v_pk_add_f32 v[68:69], v[68:69], v[92:93]
	v_pk_add_f32 v[66:67], v[66:67], v[90:91]
	v_pk_add_f32 v[64:65], v[64:65], v[88:89]
.LBB0_1975:
	s_lshl_b32 s0, s44, 2
	s_add_i32 s0, s0, 0
	s_add_i32 s0, s0, 0x24000
	ds_read_b64_tr_b16 v[80:81], v106 offset:0x2000
	ds_read_b64_tr_b16 v[82:83], v106 offset:0x2800
	ds_read_b64_tr_b16 v[84:85], v106 offset:0x3000
	ds_read_b64_tr_b16 v[86:87], v106 offset:0x3800
	ds_read_b64_tr_b16 v[88:89], v106 offset:0x2200
	ds_read_b64_tr_b16 v[90:91], v106 offset:0x2a00
	ds_read_b64_tr_b16 v[92:93], v106 offset:0x3200
	ds_read_b64_tr_b16 v[94:95], v106 offset:0x3a00
	ds_read_b64_tr_b16 v[98:99], v106 offset:0x2400
	ds_read_b64_tr_b16 v[100:101], v106 offset:0x2c00
	ds_read_b64_tr_b16 v[102:103], v106 offset:0x3400
	ds_read_b64_tr_b16 v[104:105], v106 offset:0x3c00
	ds_read_b64_tr_b16 v[108:109], v106 offset:0x2600
	ds_read_b64_tr_b16 v[110:111], v106 offset:0x2e00
	ds_read_b64_tr_b16 v[112:113], v106 offset:0x3600
	ds_read_b64_tr_b16 v[114:115], v106 offset:0x3e00
	s_nop 7
	s_setprio 3
	v_exp_f32_e32 v97, v64
	v_exp_f32_e32 v65, v65
	v_exp_f32_e32 v106, v66
	v_exp_f32_e32 v67, v67
	v_exp_f32_e32 v68, v68
	v_add_f32_e32 v64, 0, v97
	v_exp_f32_e32 v69, v69
	v_add_f32_e32 v64, v65, v64
	v_exp_f32_e32 v70, v70
	v_add_f32_e32 v64, v106, v64
	v_exp_f32_e32 v71, v71
	v_add_f32_e32 v64, v67, v64
	v_exp_f32_e32 v72, v72
	v_add_f32_e32 v64, v68, v64
	v_exp_f32_e32 v73, v73
	v_add_f32_e32 v64, v69, v64
	v_exp_f32_e32 v74, v74
	v_add_f32_e32 v64, v70, v64
	v_exp_f32_e32 v75, v75
	v_add_f32_e32 v64, v71, v64
	v_exp_f32_e32 v76, v76
	v_add_f32_e32 v64, v72, v64
	v_exp_f32_e32 v77, v77
	v_add_f32_e32 v64, v73, v64
	v_exp_f32_e32 v78, v78
	v_add_f32_e32 v64, v74, v64
	v_exp_f32_e32 v79, v79
	v_add_f32_e32 v64, v75, v64
	v_add_f32_e32 v64, v76, v64
	v_add_f32_e32 v64, v77, v64
	v_add_f32_e32 v64, v78, v64
	v_add_f32_e32 v64, v79, v64
	v_add_f32_e32 v64, v96, v64
	v_cvt_pk_bf16_f32 v66, v97, v65
	v_cvt_pk_bf16_f32 v67, v106, v67
	v_cvt_pk_bf16_f32 v68, v68, v69
	v_cvt_pk_bf16_f32 v69, v70, v71
	v_cvt_pk_bf16_f32 v70, v72, v73
	v_cvt_pk_bf16_f32 v71, v74, v75
	v_cvt_pk_bf16_f32 v72, v76, v77
	v_cvt_pk_bf16_f32 v73, v78, v79
	s_nop 0
	v_permlane32_swap_b32_e32 v66, v68
	v_permlane32_swap_b32_e32 v67, v69
	v_permlane32_swap_b32_e32 v70, v72
	v_permlane32_swap_b32_e32 v71, v73
	s_waitcnt lgkmcnt(0)
; template <int TAG = 0> DI int fresh_tid(int wv) { int l; asm volatile("v_mbcnt_lo_u32_b32 %0, -1, 0\n\tv_mbcnt_hi_u32_b32 %0, -1, %0 ; site %1" : "=v"(l) : "n"(TAG)); return wv * 64 + l; }
; DI int crow(int r, int hi) { return (r & 3) + 8 * (r >> 2) + 4 * hi; }
; DI float swap_sum(float v) { auto rr = __builtin_amdgcn_permlane32_swap(__float_as_uint(v), __float_as_uint(v), false, false); return __uint_as_float(rr[0]) + __uint_as_float(rr[1]); }
; template <int DQK, int MODE, int LDQ, int LDK, int LDV> ...
;     ...
;     __builtin_amdgcn_s_setprio(0);
;     ...
;     l_reg = swap_sum(l_reg);
;     { const int lane2 = fresh_tid<110 + MODE>(wv) & 63, r32 = lane2 & 31, hi = lane2 >> 5;
;     if (hi == 0) li_l[r32] = l_reg;
;     asm volatile("s_waitcnt lgkmcnt(0)" ::: "memory");
;     float s0v[MODE == 2 ? 16 : 1][4];
;     if constexpr (MODE == 2) {
; #pragma unroll
;         for (int r = 0; r < 16; ++r)
; #pragma unroll
;             for (int d0 = 0; d0 < 4; ++d0) s0v[r][d0] = S0[(size_t)(wid * 32 + crow(r, hi)) * 512 + d0 * 32 + r32];
	s_setprio 0
	v_mfma_f32_32x32x16_bf16 v[0:15], v[66:69], v[80:83], v[0:15]
	v_mfma_f32_32x32x16_bf16 v[48:63], v[66:69], v[88:91], v[48:63]
	v_mfma_f32_32x32x16_bf16 v[16:31], v[66:69], v[98:101], v[16:31]
	v_mfma_f32_32x32x16_bf16 v[32:47], v[66:69], v[108:111], v[32:47]
	v_mfma_f32_32x32x16_bf16 v[0:15], v[70:73], v[84:87], v[0:15]
	v_mfma_f32_32x32x16_bf16 v[48:63], v[70:73], v[92:95], v[48:63]
	v_mfma_f32_32x32x16_bf16 v[16:31], v[70:73], v[102:105], v[16:31]
	v_mfma_f32_32x32x16_bf16 v[32:47], v[70:73], v[112:115], v[32:47]
	s_setprio 0
	v_mov_b32_e32 v66, v64
	v_mbcnt_lo_u32_b32 v65, -1, 0
	v_mbcnt_hi_u32_b32 v65, -1, v65
	s_nop 1
	v_permlane32_swap_b32_e32 v64, v66
	v_and_b32_e32 v114, 63, v65
	v_and_b32_e32 v170, 31, v65
	v_cmp_gt_u32_e32 vcc, 32, v114
	s_and_saveexec_b64 s[2:3], vcc
	v_lshl_add_u32 v67, v170, 2, s0
	v_add_f32_e32 v64, v64, v66
	ds_write_b32 v67, v64
	s_or_b64 exec, exec, s[2:3]
	v_lshrrev_b32_e32 v64, 3, v65
	v_and_b32_e32 v69, 4, v64
	v_or_b32_e32 v102, s46, v69
	v_lshlrev_b32_e32 v130, 2, v170
	v_ashrrev_i32_e32 v103, 31, v102
	v_or_b32_e32 v66, 1, v102
	v_lshl_add_u64 v[92:93], s[54:55], 0, v[130:131]
	v_lshlrev_b64 v[156:157], 11, v[102:103]
	v_ashrrev_i32_e32 v67, 31, v66
	s_waitcnt lgkmcnt(0)
	v_lshl_add_u64 v[64:65], v[92:93], 0, v[156:157]
	v_lshlrev_b64 v[148:149], 11, v[66:67]
	v_lshl_add_u64 v[66:67], v[92:93], 0, v[148:149]
	global_load_dword v110, v[64:65], off
	global_load_dword v111, v[64:65], off offset:128
	global_load_dword v109, v[64:65], off offset:256
	global_load_dword v108, v[64:65], off offset:384
	global_load_dword v106, v[66:67], off
	global_load_dword v107, v[66:67], off offset:128
	global_load_dword v105, v[66:67], off offset:256
	global_load_dword v104, v[66:67], off offset:384
	v_or_b32_e32 v64, 2, v102
	v_or_b32_e32 v66, 3, v102
	v_ashrrev_i32_e32 v65, 31, v64
	v_ashrrev_i32_e32 v67, 31, v66
	v_lshlrev_b64 v[146:147], 11, v[64:65]
	v_lshlrev_b64 v[136:137], 11, v[66:67]
	v_lshl_add_u64 v[64:65], v[92:93], 0, v[146:147]
	v_lshl_add_u64 v[66:67], v[92:93], 0, v[136:137]
	global_load_dword v158, v[64:65], off
	global_load_dword v159, v[64:65], off offset:128
	global_load_dword v155, v[64:65], off offset:256
	global_load_dword v154, v[64:65], off offset:384
	global_load_dword v152, v[66:67], off
	global_load_dword v153, v[66:67], off offset:128
	global_load_dword v151, v[66:67], off offset:256
	global_load_dword v150, v[66:67], off offset:384
	v_or_b32_e32 v64, 8, v102
	v_or_b32_e32 v66, 9, v102
	v_ashrrev_i32_e32 v65, 31, v64
	v_ashrrev_i32_e32 v67, 31, v66
	v_lshlrev_b64 v[134:135], 11, v[64:65]
	v_lshlrev_b64 v[120:121], 11, v[66:67]
	v_lshl_add_u64 v[64:65], v[92:93], 0, v[134:135]
	v_lshl_add_u64 v[66:67], v[92:93], 0, v[120:121]
	global_load_dword v144, v[64:65], off
	global_load_dword v145, v[64:65], off offset:128
	global_load_dword v143, v[64:65], off offset:256
	global_load_dword v142, v[64:65], off offset:384
	global_load_dword v140, v[66:67], off
	global_load_dword v141, v[66:67], off offset:128
	global_load_dword v139, v[66:67], off offset:256
	global_load_dword v138, v[66:67], off offset:384
	v_or_b32_e32 v64, 10, v102
	v_or_b32_e32 v66, 11, v102
	v_ashrrev_i32_e32 v65, 31, v64
	v_ashrrev_i32_e32 v67, 31, v66
	v_lshlrev_b64 v[118:119], 11, v[64:65]
	v_lshlrev_b64 v[90:91], 11, v[66:67]
	v_lshl_add_u64 v[64:65], v[92:93], 0, v[118:119]
	v_lshl_add_u64 v[66:67], v[92:93], 0, v[90:91]
	global_load_dword v132, v[64:65], off
	global_load_dword v133, v[64:65], off offset:128
	global_load_dword v127, v[64:65], off offset:256
	global_load_dword v126, v[64:65], off offset:384
	global_load_dword v124, v[66:67], off
	global_load_dword v125, v[66:67], off offset:128
	global_load_dword v123, v[66:67], off offset:256
	global_load_dword v122, v[66:67], off offset:384
	v_or_b32_e32 v64, 16, v102
	v_or_b32_e32 v66, 17, v102
	v_ashrrev_i32_e32 v65, 31, v64
	v_ashrrev_i32_e32 v67, 31, v66
	v_lshlrev_b64 v[86:87], 11, v[64:65]
	v_lshlrev_b64 v[78:79], 11, v[66:67]
	v_lshl_add_u64 v[64:65], v[92:93], 0, v[86:87]
	v_lshl_add_u64 v[66:67], v[92:93], 0, v[78:79]
	global_load_dword v100, v[64:65], off
	global_load_dword v101, v[64:65], off offset:128
	global_load_dword v99, v[64:65], off offset:256
	global_load_dword v98, v[64:65], off offset:384
	global_load_dword v96, v[66:67], off
	global_load_dword v97, v[66:67], off offset:128
	global_load_dword v95, v[66:67], off offset:256
	global_load_dword v94, v[66:67], off offset:384
	v_or_b32_e32 v64, 18, v102
	v_or_b32_e32 v66, 19, v102
	v_ashrrev_i32_e32 v65, 31, v64
	v_ashrrev_i32_e32 v67, 31, v66
	v_lshlrev_b64 v[76:77], 11, v[64:65]
	v_lshlrev_b64 v[72:73], 11, v[66:67]
	v_lshl_add_u64 v[64:65], v[92:93], 0, v[76:77]
	v_lshl_add_u64 v[66:67], v[92:93], 0, v[72:73]
	v_lshl_add_u32 v169, v69, 2, s0
	global_load_dword v88, v[64:65], off
	global_load_dword v89, v[64:65], off offset:128
	global_load_dword v85, v[64:65], off offset:256
	global_load_dword v84, v[64:65], off offset:384
	global_load_dword v82, v[66:67], off
	global_load_dword v83, v[66:67], off offset:128
	global_load_dword v81, v[66:67], off offset:256
	global_load_dword v80, v[66:67], off offset:384
	ds_read_b128 v[64:67], v169
	v_or_b32_e32 v68, 24, v102
	v_ashrrev_i32_e32 v69, 31, v68
	v_lshlrev_b64 v[74:75], 11, v[68:69]
	ds_read_b128 v[68:71], v169 offset:32
	s_waitcnt lgkmcnt(0)
; DI unsigned short f2bf(float x) { unsigned u = __float_as_uint(x); u += 0x7fffu + ((u >> 16) & 1u); return (unsigned short)(u >> 16); }
; DI float shx(float v, int mask, int lane) { return __int_as_float(__builtin_amdgcn_ds_bpermute((lane ^ mask) << 2, __float_as_int(v))); }
; DI int crow(int r, int hi) { return (r & 3) + 8 * (r >> 2) + 4 * hi; }
; template <int DQK, int MODE, int LDQ, int LDK, int LDV> ...
;     ...
;     for (int r = 0; r < 16; ++r) { const int orow = wid * 32 + crow(r, hi); const float rl = __builtin_amdgcn_rcpf(li_l[crow(r, hi)]);
;         if constexpr (MODE == 0) {
; #pragma unroll
;             for (int d0 = 0; d0 < 4; ++d0) AOb[(size_t)orow * 1024 + d0 * 32 + r32] = f2bf(o[d0][r] * rl);
;         } else if constexpr (MODE == 1) {
; #pragma unroll
;             for (int d0 = 0; d0 < 4; ++d0) S0[(size_t)orow * 512 + d0 * 32 + r32] = o[d0][r] * rl;
;         } else {
;             float v[4]; float ss = 0.f;
; #pragma unroll
;             for (int d0 = 0; d0 < 4; ++d0) { v[d0] = s0v[r][d0] - lam * (o[d0][r] * rl); ss += v[d0] * v[d0]; }
; #pragma unroll
;             for (int mk = 1; mk <= 16; mk <<= 1) ss += shx(ss, mk, lane2);
;             const float rs = rsqrtf(ss * (1.f / 128.f) + EPS) * 0.8f;
; #pragma unroll
;             for (int d0 = 0; d0 < 4; ++d0) AOb[(size_t)orow * 1024 + d0 * 32 + r32] = f2bf(v[d0] * rs * gout[d0 * 32 + r32]);
;         } }
	v_rcp_f32_e32 v64, v64
	v_mov_b32_e32 v162, v0
	v_mov_b32_e32 v163, v48
	v_rcp_f32_e32 v0, v65
	v_pk_mul_f32 v[162:163], v[162:163], v[64:65] op_sel_hi:[1,0]
	v_mov_b32_e32 v48, v1
	v_lshlrev_b32_e32 v166, 2, v114
	v_pk_mul_f32 v[48:49], v[48:49], v[0:1] op_sel_hi:[1,0]
	v_xor_b32_e32 v164, 4, v166
	v_xor_b32_e32 v165, 8, v166
	v_xor_b32_e32 v168, 16, v166
	v_xor_b32_e32 v167, 32, v166
	v_or_b32_e32 v116, 25, v102
	v_ashrrev_i32_e32 v117, 31, v116
	v_xor_b32_e32 v166, 64, v166
	v_lshl_add_u64 v[112:113], v[92:93], 0, v[74:75]
	s_add_u32 s1, s60, s58
	s_mov_b32 s0, 0x358637bd
	s_addc_u32 s3, s61, s59
	s_lshl_b32 s2, s87, 1
	s_add_u32 s2, s1, s2
	s_addc_u32 s3, s3, 0
	s_waitcnt vmcnt(0)
	v_pk_fma_f32 v[172:173], v[128:129], v[162:163], v[110:111] neg_lo:[1,0,0] neg_hi:[1,0,0]
	v_mov_b32_e32 v162, v32
	v_mov_b32_e32 v163, v16
	v_pk_mul_f32 v[162:163], v[162:163], v[64:65] op_sel_hi:[1,0]
	v_mov_b32_e32 v16, v33
	v_pk_fma_f32 v[174:175], v[128:129], v[162:163], v[108:109] neg_lo:[1,0,0] neg_hi:[1,0,0]
	global_load_dword v163, v130, s[50:51]
	global_load_dword v162, v130, s[50:51] offset:128
	global_load_dword v161, v130, s[50:51] offset:256
	s_nop 0
	global_load_dword v130, v130, s[50:51] offset:384
	v_pk_fma_f32 v[176:177], v[128:129], v[48:49], v[106:107] neg_lo:[1,0,0] neg_hi:[1,0,0]
	v_pk_mul_f32 v[0:1], v[16:17], v[0:1] op_sel_hi:[1,0]
	v_pk_mul_f32 v[110:111], v[172:173], v[172:173]
	v_pk_mul_f32 v[48:49], v[176:177], v[176:177]
	v_pk_fma_f32 v[0:1], v[128:129], v[0:1], v[104:105] neg_lo:[1,0,0] neg_hi:[1,0,0]
	v_pk_mul_f32 v[108:109], v[174:175], v[174:175]
	v_pk_mul_f32 v[16:17], v[0:1], v[0:1]
	v_mov_b32_e32 v32, v48
	v_mov_b32_e32 v33, v110
	v_mov_b32_e32 v110, v49
	v_pk_add_f32 v[32:33], v[32:33], v[110:111]
	v_mov_b32_e32 v48, v17
	v_mov_b32_e32 v49, v109
	v_pk_add_f32 v[32:33], v[48:49], v[32:33]
	v_mov_b32_e32 v17, v108
	v_pk_add_f32 v[16:17], v[16:17], v[32:33]
	ds_bpermute_b32 v33, v164, v17
	ds_bpermute_b32 v32, v164, v16
	v_lshlrev_b64 v[64:65], 11, v[116:117]
	v_lshl_add_u64 v[48:49], v[92:93], 0, v[64:65]
	global_load_dword v116, v[112:113], off
	global_load_dword v117, v[112:113], off offset:128
	global_load_dword v115, v[112:113], off offset:256
	global_load_dword v114, v[112:113], off offset:384
	s_nop 0
	global_load_dword v112, v[48:49], off
	global_load_dword v113, v[48:49], off offset:128
	global_load_dword v111, v[48:49], off offset:256
	global_load_dword v110, v[48:49], off offset:384
	v_or_b32_e32 v48, 26, v102
	s_waitcnt lgkmcnt(0)
	v_pk_add_f32 v[16:17], v[16:17], v[32:33]
	ds_bpermute_b32 v33, v165, v17
	ds_bpermute_b32 v32, v165, v16
	v_or_b32_e32 v102, 27, v102
	v_ashrrev_i32_e32 v49, 31, v48
	v_ashrrev_i32_e32 v103, 31, v102
	v_lshlrev_b64 v[48:49], 11, v[48:49]
	s_waitcnt lgkmcnt(0)
	v_pk_add_f32 v[16:17], v[16:17], v[32:33]
	ds_bpermute_b32 v33, v168, v17
	ds_bpermute_b32 v32, v168, v16
	v_lshl_add_u64 v[104:105], v[92:93], 0, v[48:49]
	v_lshlrev_b32_e32 v170, 1, v170
	v_mov_b32_e32 v171, v131
	v_rcp_f32_e32 v66, v66
	s_waitcnt lgkmcnt(0)
	v_pk_add_f32 v[32:33], v[16:17], v[32:33]
	ds_bpermute_b32 v107, v167, v33
	ds_bpermute_b32 v106, v167, v32
	v_lshlrev_b64 v[16:17], 11, v[102:103]
	v_lshl_add_u64 v[92:93], v[92:93], 0, v[16:17]
	s_waitcnt lgkmcnt(0)
	v_pk_add_f32 v[32:33], v[32:33], v[106:107]
	ds_bpermute_b32 v179, v166, v33
	ds_bpermute_b32 v178, v166, v32
	global_load_dword v108, v[104:105], off
	global_load_dword v109, v[104:105], off offset:128
	global_load_dword v107, v[104:105], off offset:256
	global_load_dword v106, v[104:105], off offset:384
	s_nop 0
	global_load_dword v104, v[92:93], off
	global_load_dword v105, v[92:93], off offset:128
	global_load_dword v103, v[92:93], off offset:256
	global_load_dword v102, v[92:93], off offset:384
	v_mov_b64_e32 v[92:93], s[0:1]
	s_waitcnt lgkmcnt(0)
	v_pk_add_f32 v[32:33], v[32:33], v[178:179]
	s_nop 0
	v_pk_fma_f32 v[178:179], v[32:33], s[24:25], v[92:93] op_sel_hi:[1,0,0]
	s_nop 0
	v_mul_f32_e32 v32, 0x4b800000, v179
	v_cmp_gt_f32_e32 vcc, s67, v179
	s_nop 1
	v_cndmask_b32_e32 v32, v179, v32, vcc
	v_rsq_f32_e32 v179, v32
	v_lshl_add_u64 v[32:33], s[2:3], 0, v[170:171]
	v_lshl_add_u64 v[156:157], v[32:33], 0, v[156:157]
	v_lshl_add_u64 v[148:149], v[32:33], 0, v[148:149]
	v_mul_f32_e32 v170, 0x45800000, v179
	v_cndmask_b32_e32 v170, v179, v170, vcc
	v_mul_f32_e32 v170, 0x3f4ccccd, v170
	v_mul_f32_e32 v171, v172, v170
	v_cmp_gt_f32_e32 vcc, s67, v178
	s_mov_b64 s[2:3], 0
	s_waitcnt vmcnt(19)
	v_mul_f32_e32 v171, v163, v171
	v_bfe_u32 v172, v171, 16, 1
	v_add3_u32 v171, v171, v172, s68
	global_store_short_d16_hi v[156:157], v171, off offset:1024
	v_mul_f32_e32 v171, v173, v170
	s_waitcnt vmcnt(19)
	v_mul_f32_e32 v171, v162, v171
	v_bfe_u32 v172, v171, 16, 1
	v_add3_u32 v171, v171, v172, s68
	global_store_short_d16_hi v[156:157], v171, off offset:1088
	v_mul_f32_e32 v171, v175, v170
	s_waitcnt vmcnt(19)
	v_mul_f32_e32 v171, v161, v171
	v_bfe_u32 v172, v171, 16, 1
	v_add3_u32 v171, v171, v172, s68
	global_store_short_d16_hi v[156:157], v171, off offset:1152
	v_mul_f32_e32 v171, 0x4b800000, v178
	v_cndmask_b32_e32 v171, v178, v171, vcc
	v_mul_f32_e32 v170, v174, v170
	v_rsq_f32_e32 v171, v171
	s_waitcnt vmcnt(19)
; DI unsigned short f2bf(float x) { unsigned u = __float_as_uint(x); u += 0x7fffu + ((u >> 16) & 1u); return (unsigned short)(u >> 16); }
; DI float shx(float v, int mask, int lane) { return __int_as_float(__builtin_amdgcn_ds_bpermute((lane ^ mask) << 2, __float_as_int(v))); }
; DI int crow(int r, int hi) { return (r & 3) + 8 * (r >> 2) + 4 * hi; }
; template <int DQK, int MODE, int LDQ, int LDK, int LDV> ...
;     ...
;     for (int r = 0; r < 16; ++r) { const int orow = wid * 32 + crow(r, hi); const float rl = __builtin_amdgcn_rcpf(li_l[crow(r, hi)]);
;         if constexpr (MODE == 0) {
; #pragma unroll
;             for (int d0 = 0; d0 < 4; ++d0) AOb[(size_t)orow * 1024 + d0 * 32 + r32] = f2bf(o[d0][r] * rl);
;         } else if constexpr (MODE == 1) {
; #pragma unroll
;             for (int d0 = 0; d0 < 4; ++d0) S0[(size_t)orow * 512 + d0 * 32 + r32] = o[d0][r] * rl;
;         } else {
;             float v[4]; float ss = 0.f;
; #pragma unroll
;             for (int d0 = 0; d0 < 4; ++d0) { v[d0] = s0v[r][d0] - lam * (o[d0][r] * rl); ss += v[d0] * v[d0]; }
; #pragma unroll
;             for (int mk = 1; mk <= 16; mk <<= 1) ss += shx(ss, mk, lane2);
;             const float rs = rsqrtf(ss * (1.f / 128.f) + EPS) * 0.8f;
; #pragma unroll
;             for (int d0 = 0; d0 < 4; ++d0) AOb[(size_t)orow * 1024 + d0 * 32 + r32] = f2bf(v[d0] * rs * gout[d0 * 32 + r32]);
;         } }
	v_mul_f32_e32 v170, v130, v170
	v_bfe_u32 v172, v170, 16, 1
	v_add3_u32 v170, v170, v172, s68
	global_store_short_d16_hi v[156:157], v170, off offset:1216
	v_mul_f32_e32 v156, 0x45800000, v171
	v_cndmask_b32_e32 v172, v171, v156, vcc
	v_mov_b32_e32 v156, v2
	v_rcp_f32_e32 v2, v67
	v_mov_b32_e32 v157, v50
	v_mov_b32_e32 v50, v3
	v_pk_mul_f32 v[156:157], v[156:157], v[66:67] op_sel_hi:[1,0]
	v_mov_b32_e32 v170, v34
	v_mov_b32_e32 v171, v18
	v_pk_mul_f32 v[50:51], v[50:51], v[2:3] op_sel_hi:[1,0]
	v_mov_b32_e32 v18, v35
	v_pk_fma_f32 v[156:157], v[128:129], v[156:157], v[158:159] neg_lo:[1,0,0] neg_hi:[1,0,0]
	v_pk_mul_f32 v[170:171], v[170:171], v[66:67] op_sel_hi:[1,0]
	v_pk_fma_f32 v[50:51], v[128:129], v[50:51], v[152:153] neg_lo:[1,0,0] neg_hi:[1,0,0]
	v_pk_mul_f32 v[2:3], v[18:19], v[2:3] op_sel_hi:[1,0]
	v_pk_mul_f32 v[158:159], v[156:157], v[156:157]
	v_pk_fma_f32 v[66:67], v[128:129], v[170:171], v[154:155] neg_lo:[1,0,0] neg_hi:[1,0,0]
	v_pk_mul_f32 v[152:153], v[50:51], v[50:51]
	v_pk_fma_f32 v[2:3], v[128:129], v[2:3], v[150:151] neg_lo:[1,0,0] neg_hi:[1,0,0]
	v_pk_mul_f32 v[154:155], v[66:67], v[66:67]
	v_pk_mul_f32 v[18:19], v[2:3], v[2:3]
	v_mov_b32_e32 v34, v152
	v_mov_b32_e32 v35, v158
	v_mov_b32_e32 v158, v153
	v_pk_add_f32 v[34:35], v[34:35], v[158:159]
	v_mov_b32_e32 v150, v19
	v_mov_b32_e32 v151, v155
	v_pk_add_f32 v[34:35], v[150:151], v[34:35]
	v_mov_b32_e32 v19, v154
	v_pk_add_f32 v[18:19], v[18:19], v[34:35]
	ds_bpermute_b32 v35, v164, v19
	ds_bpermute_b32 v34, v164, v18
	v_mul_f32_e32 v150, 0x3f4ccccd, v172
	v_mul_f32_e32 v151, v176, v150
	v_mul_f32_e32 v151, v163, v151
	v_bfe_u32 v152, v151, 16, 1
	s_waitcnt lgkmcnt(0)
	v_pk_add_f32 v[18:19], v[18:19], v[34:35]
	ds_bpermute_b32 v35, v165, v19
	ds_bpermute_b32 v34, v165, v18
	v_add3_u32 v151, v151, v152, s68
	global_store_short_d16_hi v[148:149], v151, off offset:1024
	v_mul_f32_e32 v151, v177, v150
	v_mul_f32_e32 v151, v162, v151
	s_waitcnt lgkmcnt(0)
	v_pk_add_f32 v[18:19], v[18:19], v[34:35]
	ds_bpermute_b32 v35, v168, v19
	ds_bpermute_b32 v34, v168, v18
	v_bfe_u32 v152, v151, 16, 1
	v_mul_f32_e32 v1, v1, v150
	v_add3_u32 v151, v151, v152, s68
	v_mul_f32_e32 v1, v161, v1
	s_waitcnt lgkmcnt(0)
	v_pk_add_f32 v[18:19], v[18:19], v[34:35]
	ds_bpermute_b32 v35, v167, v19
	ds_bpermute_b32 v34, v167, v18
	global_store_short_d16_hi v[148:149], v151, off offset:1088
	v_bfe_u32 v151, v1, 16, 1
	v_add3_u32 v1, v1, v151, s68
	v_mul_f32_e32 v0, v0, v150
	s_waitcnt lgkmcnt(0)
	v_pk_add_f32 v[18:19], v[18:19], v[34:35]
	ds_bpermute_b32 v35, v166, v19
	ds_bpermute_b32 v34, v166, v18
	global_store_short_d16_hi v[148:149], v1, off offset:1152
	v_mul_f32_e32 v150, v130, v0
	v_bfe_u32 v151, v150, 16, 1
	s_waitcnt lgkmcnt(0)
	v_pk_add_f32 v[0:1], v[18:19], v[34:35]
	s_nop 0
	v_pk_fma_f32 v[0:1], v[0:1], s[24:25], v[92:93] op_sel_hi:[1,0,0]
	s_nop 0
	v_mul_f32_e32 v18, 0x4b800000, v1
	v_cmp_gt_f32_e32 vcc, s67, v1
	s_nop 1
	v_cndmask_b32_e32 v1, v1, v18, vcc
	v_rsq_f32_e32 v1, v1
	v_add3_u32 v18, v150, v151, s68
	global_store_short_d16_hi v[148:149], v18, off offset:1216
	v_lshl_add_u64 v[18:19], v[32:33], 0, v[146:147]
	v_mul_f32_e32 v34, 0x45800000, v1
	v_cndmask_b32_e32 v1, v1, v34, vcc
	v_mul_f32_e32 v1, 0x3f4ccccd, v1
	v_mul_f32_e32 v34, v156, v1
	v_mul_f32_e32 v34, v163, v34
	v_bfe_u32 v35, v34, 16, 1
	v_add3_u32 v34, v34, v35, s68
	global_store_short_d16_hi v[18:19], v34, off offset:1024
	v_mul_f32_e32 v34, v157, v1
	v_mul_f32_e32 v34, v162, v34
	v_bfe_u32 v35, v34, 16, 1
	v_add3_u32 v34, v34, v35, s68
	global_store_short_d16_hi v[18:19], v34, off offset:1088
	v_mul_f32_e32 v34, v67, v1
	v_mul_f32_e32 v34, v161, v34
	v_bfe_u32 v35, v34, 16, 1
	v_add3_u32 v34, v34, v35, s68
	global_store_short_d16_hi v[18:19], v34, off offset:1152
	v_mul_f32_e32 v1, v66, v1
	v_mul_f32_e32 v34, 0x4b800000, v0
	v_cmp_gt_f32_e32 vcc, s67, v0
	v_mul_f32_e32 v1, v130, v1
	v_mov_b32_e32 v66, v36
	v_cndmask_b32_e32 v0, v0, v34, vcc
	v_rsq_f32_e32 v34, v0
	v_bfe_u32 v0, v1, 16, 1
	v_add3_u32 v0, v1, v0, s68
	global_store_short_d16_hi v[18:19], v0, off offset:1216
	v_rcp_f32_e32 v0, v68
	v_mov_b32_e32 v18, v4
	v_rcp_f32_e32 v4, v69
	v_mul_f32_e32 v1, 0x45800000, v34
	v_mov_b32_e32 v19, v52
	v_mov_b32_e32 v52, v5
	v_pk_mul_f32 v[18:19], v[18:19], v[0:1] op_sel_hi:[1,0]
	v_mov_b32_e32 v67, v20
	v_pk_mul_f32 v[52:53], v[52:53], v[4:5] op_sel_hi:[1,0]
	v_mov_b32_e32 v20, v37
	v_cndmask_b32_e32 v146, v34, v1, vcc
	v_pk_fma_f32 v[18:19], v[128:129], v[18:19], v[144:145] neg_lo:[1,0,0] neg_hi:[1,0,0]
	v_pk_mul_f32 v[0:1], v[66:67], v[0:1] op_sel_hi:[1,0]
	v_pk_fma_f32 v[52:53], v[128:129], v[52:53], v[140:141] neg_lo:[1,0,0] neg_hi:[1,0,0]
	v_pk_mul_f32 v[4:5], v[20:21], v[4:5] op_sel_hi:[1,0]
	v_pk_mul_f32 v[34:35], v[18:19], v[18:19]
	v_pk_fma_f32 v[0:1], v[128:129], v[0:1], v[142:143] neg_lo:[1,0,0] neg_hi:[1,0,0]
	v_pk_mul_f32 v[68:69], v[52:53], v[52:53]
	v_pk_fma_f32 v[4:5], v[128:129], v[4:5], v[138:139] neg_lo:[1,0,0] neg_hi:[1,0,0]
	v_pk_mul_f32 v[66:67], v[0:1], v[0:1]
	v_pk_mul_f32 v[20:21], v[4:5], v[4:5]
	v_mov_b32_e32 v36, v68
	v_mov_b32_e32 v37, v34
	v_mov_b32_e32 v34, v69
	v_pk_add_f32 v[34:35], v[36:37], v[34:35]
	v_mov_b32_e32 v36, v21
	v_mov_b32_e32 v37, v67
	v_pk_add_f32 v[34:35], v[36:37], v[34:35]
	v_mov_b32_e32 v21, v66
	v_pk_add_f32 v[20:21], v[20:21], v[34:35]
	ds_bpermute_b32 v35, v164, v21
	ds_bpermute_b32 v34, v164, v20
	v_mul_f32_e32 v66, 0x3f4ccccd, v146
	v_mul_f32_e32 v50, v50, v66
	v_mul_f32_e32 v50, v163, v50
	v_bfe_u32 v67, v50, 16, 1
	s_waitcnt lgkmcnt(0)
; DI unsigned short f2bf(float x) { unsigned u = __float_as_uint(x); u += 0x7fffu + ((u >> 16) & 1u); return (unsigned short)(u >> 16); }
; DI float shx(float v, int mask, int lane) { return __int_as_float(__builtin_amdgcn_ds_bpermute((lane ^ mask) << 2, __float_as_int(v))); }
; DI int crow(int r, int hi) { return (r & 3) + 8 * (r >> 2) + 4 * hi; }
; template <int DQK, int MODE, int LDQ, int LDK, int LDV> ...
;     ...
;     for (int r = 0; r < 16; ++r) { const int orow = wid * 32 + crow(r, hi); const float rl = __builtin_amdgcn_rcpf(li_l[crow(r, hi)]);
;         if constexpr (MODE == 0) {
; #pragma unroll
;             for (int d0 = 0; d0 < 4; ++d0) AOb[(size_t)orow * 1024 + d0 * 32 + r32] = f2bf(o[d0][r] * rl);
;         } else if constexpr (MODE == 1) {
; #pragma unroll
;             for (int d0 = 0; d0 < 4; ++d0) S0[(size_t)orow * 512 + d0 * 32 + r32] = o[d0][r] * rl;
;         } else {
;             float v[4]; float ss = 0.f;
; #pragma unroll
;             for (int d0 = 0; d0 < 4; ++d0) { v[d0] = s0v[r][d0] - lam * (o[d0][r] * rl); ss += v[d0] * v[d0]; }
; #pragma unroll
;             for (int mk = 1; mk <= 16; mk <<= 1) ss += shx(ss, mk, lane2);
;             const float rs = rsqrtf(ss * (1.f / 128.f) + EPS) * 0.8f;
; #pragma unroll
;             for (int d0 = 0; d0 < 4; ++d0) AOb[(size_t)orow * 1024 + d0 * 32 + r32] = f2bf(v[d0] * rs * gout[d0 * 32 + r32]);
;         } }
	v_pk_add_f32 v[20:21], v[20:21], v[34:35]
	ds_bpermute_b32 v35, v165, v21
	ds_bpermute_b32 v34, v165, v20
	v_lshl_add_u64 v[36:37], v[32:33], 0, v[136:137]
	v_add3_u32 v50, v50, v67, s68
	global_store_short_d16_hi v[36:37], v50, off offset:1024
	v_mul_f32_e32 v50, v51, v66
	s_waitcnt lgkmcnt(0)
	v_pk_add_f32 v[20:21], v[20:21], v[34:35]
	ds_bpermute_b32 v35, v168, v21
	ds_bpermute_b32 v34, v168, v20
	v_mul_f32_e32 v50, v162, v50
	v_bfe_u32 v51, v50, 16, 1
	v_mul_f32_e32 v3, v3, v66
	v_add3_u32 v50, v50, v51, s68
	s_waitcnt lgkmcnt(0)
	v_pk_add_f32 v[20:21], v[20:21], v[34:35]
	ds_bpermute_b32 v35, v167, v21
	ds_bpermute_b32 v34, v167, v20
	v_mul_f32_e32 v3, v161, v3
	global_store_short_d16_hi v[36:37], v50, off offset:1088
	v_bfe_u32 v50, v3, 16, 1
	v_add3_u32 v3, v3, v50, s68
	s_waitcnt lgkmcnt(0)
	v_pk_add_f32 v[20:21], v[20:21], v[34:35]
	ds_bpermute_b32 v35, v166, v21
	ds_bpermute_b32 v34, v166, v20
	v_mul_f32_e32 v2, v2, v66
	global_store_short_d16_hi v[36:37], v3, off offset:1152
	v_mul_f32_e32 v50, v130, v2
	v_bfe_u32 v51, v50, 16, 1
	s_waitcnt lgkmcnt(0)
	v_pk_add_f32 v[2:3], v[20:21], v[34:35]
	s_nop 0
	v_pk_fma_f32 v[2:3], v[2:3], s[24:25], v[92:93] op_sel_hi:[1,0,0]
	s_nop 0
	v_mul_f32_e32 v20, 0x4b800000, v3
	v_cmp_gt_f32_e32 vcc, s67, v3
	s_nop 1
	v_cndmask_b32_e32 v3, v3, v20, vcc
	v_rsq_f32_e32 v3, v3
	v_add3_u32 v20, v50, v51, s68
	global_store_short_d16_hi v[36:37], v20, off offset:1216
	v_lshl_add_u64 v[20:21], v[32:33], 0, v[134:135]
	v_mul_f32_e32 v34, 0x45800000, v3
	v_cndmask_b32_e32 v3, v3, v34, vcc
	v_mul_f32_e32 v3, 0x3f4ccccd, v3
	v_mul_f32_e32 v18, v18, v3
	v_mul_f32_e32 v18, v163, v18
	v_bfe_u32 v34, v18, 16, 1
	v_add3_u32 v18, v18, v34, s68
	global_store_short_d16_hi v[20:21], v18, off offset:1024
	v_mul_f32_e32 v18, v19, v3
	v_mul_f32_e32 v18, v162, v18
	v_bfe_u32 v19, v18, 16, 1
	v_mul_f32_e32 v1, v1, v3
	v_add3_u32 v18, v18, v19, s68
	v_mul_f32_e32 v1, v161, v1
	global_store_short_d16_hi v[20:21], v18, off offset:1088
	v_bfe_u32 v18, v1, 16, 1
	v_add3_u32 v1, v1, v18, s68
	global_store_short_d16_hi v[20:21], v1, off offset:1152
	v_mul_f32_e32 v1, 0x4b800000, v2
	v_cmp_gt_f32_e32 vcc, s67, v2
	v_mul_f32_e32 v0, v0, v3
	v_mul_f32_e32 v0, v130, v0
	v_cndmask_b32_e32 v1, v2, v1, vcc
	v_rsq_f32_e32 v1, v1
	v_bfe_u32 v2, v0, 16, 1
	v_add3_u32 v0, v0, v2, s68
	global_store_short_d16_hi v[20:21], v0, off offset:1216
	v_mul_f32_e32 v2, 0x45800000, v1
	v_rcp_f32_e32 v0, v70
	v_cndmask_b32_e32 v66, v1, v2, vcc
	v_mov_b32_e32 v2, v6
	v_rcp_f32_e32 v6, v71
	v_mov_b32_e32 v3, v54
	v_mov_b32_e32 v18, v38
	v_mov_b32_e32 v19, v22
	v_mov_b32_e32 v54, v7
	v_pk_mul_f32 v[2:3], v[2:3], v[0:1] op_sel_hi:[1,0]
	v_pk_mul_f32 v[0:1], v[18:19], v[0:1] op_sel_hi:[1,0]
	v_pk_mul_f32 v[18:19], v[54:55], v[6:7] op_sel_hi:[1,0]
	v_mov_b32_e32 v22, v39
	v_pk_fma_f32 v[2:3], v[128:129], v[2:3], v[132:133] neg_lo:[1,0,0] neg_hi:[1,0,0]
	v_pk_fma_f32 v[20:21], v[128:129], v[18:19], v[124:125] neg_lo:[1,0,0] neg_hi:[1,0,0]
	v_pk_mul_f32 v[6:7], v[22:23], v[6:7] op_sel_hi:[1,0]
	v_pk_mul_f32 v[34:35], v[2:3], v[2:3]
	v_pk_fma_f32 v[0:1], v[128:129], v[0:1], v[126:127] neg_lo:[1,0,0] neg_hi:[1,0,0]
	v_pk_mul_f32 v[50:51], v[20:21], v[20:21]
	v_pk_fma_f32 v[18:19], v[128:129], v[6:7], v[122:123] neg_lo:[1,0,0] neg_hi:[1,0,0]
	v_pk_mul_f32 v[36:37], v[0:1], v[0:1]
	v_pk_mul_f32 v[6:7], v[18:19], v[18:19]
	v_mov_b32_e32 v22, v50
	v_mov_b32_e32 v23, v34
	v_mov_b32_e32 v34, v51
	v_pk_add_f32 v[22:23], v[22:23], v[34:35]
	v_mov_b32_e32 v34, v7
	v_mov_b32_e32 v35, v37
	v_pk_add_f32 v[22:23], v[34:35], v[22:23]
	v_mov_b32_e32 v7, v36
	v_pk_add_f32 v[6:7], v[6:7], v[22:23]
	ds_bpermute_b32 v23, v164, v7
	ds_bpermute_b32 v22, v164, v6
	v_mul_f32_e32 v36, 0x3f4ccccd, v66
	v_mul_f32_e32 v37, v52, v36
	v_mul_f32_e32 v37, v163, v37
	v_bfe_u32 v38, v37, 16, 1
	s_waitcnt lgkmcnt(0)
	v_pk_add_f32 v[6:7], v[6:7], v[22:23]
	ds_bpermute_b32 v23, v165, v7
	ds_bpermute_b32 v22, v165, v6
	v_lshl_add_u64 v[34:35], v[32:33], 0, v[120:121]
	v_add3_u32 v37, v37, v38, s68
	global_store_short_d16_hi v[34:35], v37, off offset:1024
	v_mul_f32_e32 v37, v53, v36
	s_waitcnt lgkmcnt(0)
	v_pk_add_f32 v[6:7], v[6:7], v[22:23]
	ds_bpermute_b32 v23, v168, v7
	ds_bpermute_b32 v22, v168, v6
	v_mul_f32_e32 v37, v162, v37
	v_bfe_u32 v38, v37, 16, 1
	v_mul_f32_e32 v5, v5, v36
	v_add3_u32 v37, v37, v38, s68
	s_waitcnt lgkmcnt(0)
	v_pk_add_f32 v[6:7], v[6:7], v[22:23]
	ds_bpermute_b32 v23, v167, v7
	ds_bpermute_b32 v22, v167, v6
	v_mul_f32_e32 v5, v161, v5
	global_store_short_d16_hi v[34:35], v37, off offset:1088
	v_bfe_u32 v37, v5, 16, 1
	v_add3_u32 v5, v5, v37, s68
	s_waitcnt lgkmcnt(0)
	v_pk_add_f32 v[6:7], v[6:7], v[22:23]
	ds_bpermute_b32 v23, v166, v7
	ds_bpermute_b32 v22, v166, v6
	v_mul_f32_e32 v4, v4, v36
	global_store_short_d16_hi v[34:35], v5, off offset:1152
	v_mul_f32_e32 v36, v130, v4
	v_bfe_u32 v37, v36, 16, 1
	s_waitcnt lgkmcnt(0)
	v_pk_add_f32 v[4:5], v[6:7], v[22:23]
	v_lshl_add_u64 v[22:23], v[32:33], 0, v[118:119]
	v_pk_fma_f32 v[4:5], v[4:5], s[24:25], v[92:93] op_sel_hi:[1,0,0]
	s_nop 0
	v_mul_f32_e32 v6, 0x4b800000, v5
	v_cmp_gt_f32_e32 vcc, s67, v5
	s_nop 1
	v_cndmask_b32_e32 v5, v5, v6, vcc
	v_rsq_f32_e32 v5, v5
	v_add3_u32 v6, v36, v37, s68
	global_store_short_d16_hi v[34:35], v6, off offset:1216
	v_mov_b32_e32 v36, v40
	v_mul_f32_e32 v6, 0x45800000, v5
	v_cndmask_b32_e32 v5, v5, v6, vcc
	v_mul_f32_e32 v5, 0x3f4ccccd, v5
	v_mul_f32_e32 v2, v2, v5
	v_mul_f32_e32 v2, v163, v2
	v_bfe_u32 v6, v2, 16, 1
	v_add3_u32 v2, v2, v6, s68
	global_store_short_d16_hi v[22:23], v2, off offset:1024
	v_mul_f32_e32 v2, v3, v5
	v_mul_f32_e32 v2, v162, v2
	v_bfe_u32 v3, v2, 16, 1
	v_mul_f32_e32 v1, v1, v5
	v_add3_u32 v2, v2, v3, s68
	v_mul_f32_e32 v1, v161, v1
	global_store_short_d16_hi v[22:23], v2, off offset:1088
	v_bfe_u32 v2, v1, 16, 1
	v_add3_u32 v1, v1, v2, s68
	v_mul_f32_e32 v2, 0x4b800000, v4
	v_cmp_gt_f32_e32 vcc, s67, v4
	v_mul_f32_e32 v0, v0, v5
	v_mul_f32_e32 v0, v130, v0
	v_cndmask_b32_e32 v2, v4, v2, vcc
	ds_read_b128 v[4:7], v169 offset:64
	global_store_short_d16_hi v[22:23], v1, off offset:1152
	v_bfe_u32 v1, v0, 16, 1
	v_rsq_f32_e32 v34, v2
	v_add3_u32 v0, v0, v1, s68
	global_store_short_d16_hi v[22:23], v0, off offset:1216
	ds_read_b128 v[0:3], v169 offset:96
	s_waitcnt lgkmcnt(1)
; DI unsigned short f2bf(float x) { unsigned u = __float_as_uint(x); u += 0x7fffu + ((u >> 16) & 1u); return (unsigned short)(u >> 16); }
; DI float shx(float v, int mask, int lane) { return __int_as_float(__builtin_amdgcn_ds_bpermute((lane ^ mask) << 2, __float_as_int(v))); }
; DI int crow(int r, int hi) { return (r & 3) + 8 * (r >> 2) + 4 * hi; }
; template <int DQK, int MODE, int LDQ, int LDK, int LDV> ...
;     ...
;     for (int r = 0; r < 16; ++r) { const int orow = wid * 32 + crow(r, hi); const float rl = __builtin_amdgcn_rcpf(li_l[crow(r, hi)]);
;         if constexpr (MODE == 0) {
; #pragma unroll
;             for (int d0 = 0; d0 < 4; ++d0) AOb[(size_t)orow * 1024 + d0 * 32 + r32] = f2bf(o[d0][r] * rl);
;         } else if constexpr (MODE == 1) {
; #pragma unroll
;             for (int d0 = 0; d0 < 4; ++d0) S0[(size_t)orow * 512 + d0 * 32 + r32] = o[d0][r] * rl;
;         } else {
;             float v[4]; float ss = 0.f;
; #pragma unroll
;             for (int d0 = 0; d0 < 4; ++d0) { v[d0] = s0v[r][d0] - lam * (o[d0][r] * rl); ss += v[d0] * v[d0]; }
; #pragma unroll
;             for (int mk = 1; mk <= 16; mk <<= 1) ss += shx(ss, mk, lane2);
;             const float rs = rsqrtf(ss * (1.f / 128.f) + EPS) * 0.8f;
; #pragma unroll
;             for (int d0 = 0; d0 < 4; ++d0) AOb[(size_t)orow * 1024 + d0 * 32 + r32] = f2bf(v[d0] * rs * gout[d0 * 32 + r32]);
;         } }
	v_rcp_f32_e32 v4, v4
	v_mul_f32_e32 v22, 0x45800000, v34
	v_cndmask_b32_e32 v52, v34, v22, vcc
	v_mov_b32_e32 v22, v8
	v_mov_b32_e32 v23, v56
	v_mov_b32_e32 v37, v24
	v_pk_mul_f32 v[22:23], v[22:23], v[4:5] op_sel_hi:[1,0]
	v_pk_mul_f32 v[36:37], v[36:37], v[4:5] op_sel_hi:[1,0]
	v_rcp_f32_e32 v4, v5
	v_mov_b32_e32 v56, v9
	v_mov_b32_e32 v24, v41
	v_pk_fma_f32 v[22:23], v[128:129], v[22:23], v[100:101] neg_lo:[1,0,0] neg_hi:[1,0,0]
	v_pk_mul_f32 v[8:9], v[56:57], v[4:5] op_sel_hi:[1,0]
	v_pk_mul_f32 v[4:5], v[24:25], v[4:5] op_sel_hi:[1,0]
	v_pk_fma_f32 v[8:9], v[128:129], v[8:9], v[96:97] neg_lo:[1,0,0] neg_hi:[1,0,0]
	v_pk_mul_f32 v[34:35], v[22:23], v[22:23]
	v_pk_fma_f32 v[36:37], v[128:129], v[36:37], v[98:99] neg_lo:[1,0,0] neg_hi:[1,0,0]
	v_pk_mul_f32 v[50:51], v[8:9], v[8:9]
	v_pk_fma_f32 v[4:5], v[128:129], v[4:5], v[94:95] neg_lo:[1,0,0] neg_hi:[1,0,0]
	v_pk_mul_f32 v[38:39], v[36:37], v[36:37]
	v_pk_mul_f32 v[24:25], v[4:5], v[4:5]
	v_mov_b32_e32 v40, v50
	v_mov_b32_e32 v41, v34
	v_mov_b32_e32 v34, v51
	v_pk_add_f32 v[34:35], v[40:41], v[34:35]
	v_mov_b32_e32 v40, v25
	v_mov_b32_e32 v41, v39
	v_pk_add_f32 v[34:35], v[40:41], v[34:35]
	v_mov_b32_e32 v25, v38
	v_pk_add_f32 v[24:25], v[24:25], v[34:35]
	ds_bpermute_b32 v35, v164, v25
	ds_bpermute_b32 v34, v164, v24
	v_mul_f32_e32 v40, 0x3f4ccccd, v52
	v_mul_f32_e32 v20, v20, v40
	v_mul_f32_e32 v20, v163, v20
	v_bfe_u32 v41, v20, 16, 1
	s_waitcnt lgkmcnt(0)
	v_pk_add_f32 v[24:25], v[24:25], v[34:35]
	ds_bpermute_b32 v35, v165, v25
	ds_bpermute_b32 v34, v165, v24
	v_lshl_add_u64 v[38:39], v[32:33], 0, v[90:91]
	v_add3_u32 v20, v20, v41, s68
	global_store_short_d16_hi v[38:39], v20, off offset:1024
	v_mul_f32_e32 v41, v21, v40
	s_waitcnt lgkmcnt(0)
	v_pk_add_f32 v[20:21], v[24:25], v[34:35]
	ds_bpermute_b32 v25, v168, v21
	ds_bpermute_b32 v24, v168, v20
	v_mul_f32_e32 v34, v162, v41
	v_bfe_u32 v35, v34, 16, 1
	v_mul_f32_e32 v19, v19, v40
	v_add3_u32 v34, v34, v35, s68
	s_waitcnt lgkmcnt(0)
	v_pk_add_f32 v[20:21], v[20:21], v[24:25]
	ds_bpermute_b32 v25, v167, v21
	ds_bpermute_b32 v24, v167, v20
	v_mul_f32_e32 v19, v161, v19
	global_store_short_d16_hi v[38:39], v34, off offset:1088
	v_bfe_u32 v34, v19, 16, 1
	v_add3_u32 v19, v19, v34, s68
	s_waitcnt lgkmcnt(0)
	v_pk_add_f32 v[20:21], v[20:21], v[24:25]
	ds_bpermute_b32 v25, v166, v21
	ds_bpermute_b32 v24, v166, v20
	v_mul_f32_e32 v18, v18, v40
	global_store_short_d16_hi v[38:39], v19, off offset:1152
	v_mul_f32_e32 v34, v130, v18
	v_bfe_u32 v35, v34, 16, 1
	s_waitcnt lgkmcnt(0)
	v_pk_add_f32 v[18:19], v[20:21], v[24:25]
	v_rcp_f32_e32 v6, v6
	v_pk_fma_f32 v[18:19], v[18:19], s[24:25], v[92:93] op_sel_hi:[1,0,0]
	v_rcp_f32_e32 v0, v0
	v_mul_f32_e32 v20, 0x4b800000, v19
	v_cmp_gt_f32_e32 vcc, s67, v19
	v_rcp_f32_e32 v2, v2
	s_nop 0
	v_cndmask_b32_e32 v19, v19, v20, vcc
	v_rsq_f32_e32 v19, v19
	v_add3_u32 v20, v34, v35, s68
	global_store_short_d16_hi v[38:39], v20, off offset:1216
	v_lshl_add_u64 v[20:21], v[32:33], 0, v[86:87]
	v_mul_f32_e32 v24, 0x45800000, v19
	v_cndmask_b32_e32 v19, v19, v24, vcc
	v_mul_f32_e32 v19, 0x3f4ccccd, v19
	v_mul_f32_e32 v22, v22, v19
	v_mul_f32_e32 v22, v163, v22
	v_bfe_u32 v24, v22, 16, 1
	v_add3_u32 v22, v22, v24, s68
	global_store_short_d16_hi v[20:21], v22, off offset:1024
	v_mul_f32_e32 v22, v23, v19
	v_mul_f32_e32 v22, v162, v22
	v_bfe_u32 v23, v22, 16, 1
	v_add3_u32 v22, v22, v23, s68
	global_store_short_d16_hi v[20:21], v22, off offset:1088
	v_mul_f32_e32 v22, v37, v19
	v_mul_f32_e32 v22, v161, v22
	v_bfe_u32 v23, v22, 16, 1
	v_add3_u32 v22, v22, v23, s68
	global_store_short_d16_hi v[20:21], v22, off offset:1152
	v_mul_f32_e32 v22, 0x4b800000, v18
	v_cmp_gt_f32_e32 vcc, s67, v18
	v_mul_f32_e32 v19, v36, v19
	v_mul_f32_e32 v19, v130, v19
	v_cndmask_b32_e32 v18, v18, v22, vcc
	v_rsq_f32_e32 v18, v18
	v_bfe_u32 v22, v19, 16, 1
	v_add3_u32 v19, v19, v22, s68
	global_store_short_d16_hi v[20:21], v19, off offset:1216
	v_mul_f32_e32 v19, 0x45800000, v18
	v_cndmask_b32_e32 v38, v18, v19, vcc
	v_mov_b32_e32 v18, v10
	v_mov_b32_e32 v19, v58
	v_mov_b32_e32 v22, v42
	v_mov_b32_e32 v23, v26
	v_pk_mul_f32 v[18:19], v[18:19], v[6:7] op_sel_hi:[1,0]
	v_pk_mul_f32 v[22:23], v[22:23], v[6:7] op_sel_hi:[1,0]
	v_rcp_f32_e32 v6, v7
	v_mov_b32_e32 v58, v11
	v_mov_b32_e32 v26, v43
	v_pk_fma_f32 v[18:19], v[128:129], v[18:19], v[88:89] neg_lo:[1,0,0] neg_hi:[1,0,0]
	v_pk_mul_f32 v[10:11], v[58:59], v[6:7] op_sel_hi:[1,0]
	v_pk_mul_f32 v[6:7], v[26:27], v[6:7] op_sel_hi:[1,0]
	v_pk_fma_f32 v[10:11], v[128:129], v[10:11], v[82:83] neg_lo:[1,0,0] neg_hi:[1,0,0]
	v_pk_mul_f32 v[20:21], v[18:19], v[18:19]
	v_pk_fma_f32 v[22:23], v[128:129], v[22:23], v[84:85] neg_lo:[1,0,0] neg_hi:[1,0,0]
	v_pk_mul_f32 v[34:35], v[10:11], v[10:11]
	v_pk_fma_f32 v[6:7], v[128:129], v[6:7], v[80:81] neg_lo:[1,0,0] neg_hi:[1,0,0]
	v_pk_mul_f32 v[24:25], v[22:23], v[22:23]
	v_pk_mul_f32 v[26:27], v[6:7], v[6:7]
	v_mov_b32_e32 v36, v34
	v_mov_b32_e32 v37, v20
	v_mov_b32_e32 v20, v35
	v_pk_add_f32 v[20:21], v[36:37], v[20:21]
	v_mov_b32_e32 v34, v27
	v_mov_b32_e32 v35, v25
	v_pk_add_f32 v[20:21], v[34:35], v[20:21]
	v_mov_b32_e32 v27, v24
	v_pk_add_f32 v[20:21], v[26:27], v[20:21]
	ds_bpermute_b32 v25, v164, v21
	ds_bpermute_b32 v24, v164, v20
	v_mul_f32_e32 v34, 0x3f4ccccd, v38
	v_mul_f32_e32 v8, v8, v34
	v_mul_f32_e32 v8, v163, v8
	v_bfe_u32 v35, v8, 16, 1
	s_waitcnt lgkmcnt(0)
	v_pk_add_f32 v[20:21], v[20:21], v[24:25]
	ds_bpermute_b32 v25, v165, v21
	ds_bpermute_b32 v24, v165, v20
	v_lshl_add_u64 v[26:27], v[32:33], 0, v[78:79]
	v_add3_u32 v8, v8, v35, s68
	global_store_short_d16_hi v[26:27], v8, off offset:1024
	v_mul_f32_e32 v35, v9, v34
	s_waitcnt lgkmcnt(0)
; DI unsigned short f2bf(float x) { unsigned u = __float_as_uint(x); u += 0x7fffu + ((u >> 16) & 1u); return (unsigned short)(u >> 16); }
; DI float shx(float v, int mask, int lane) { return __int_as_float(__builtin_amdgcn_ds_bpermute((lane ^ mask) << 2, __float_as_int(v))); }
; DI int crow(int r, int hi) { return (r & 3) + 8 * (r >> 2) + 4 * hi; }
; template <int DQK, int MODE, int LDQ, int LDK, int LDV> ...
;     ...
;     for (int r = 0; r < 16; ++r) { const int orow = wid * 32 + crow(r, hi); const float rl = __builtin_amdgcn_rcpf(li_l[crow(r, hi)]);
;         if constexpr (MODE == 0) {
; #pragma unroll
;             for (int d0 = 0; d0 < 4; ++d0) AOb[(size_t)orow * 1024 + d0 * 32 + r32] = f2bf(o[d0][r] * rl);
;         } else if constexpr (MODE == 1) {
; #pragma unroll
;             for (int d0 = 0; d0 < 4; ++d0) S0[(size_t)orow * 512 + d0 * 32 + r32] = o[d0][r] * rl;
;         } else {
;             float v[4]; float ss = 0.f;
; #pragma unroll
;             for (int d0 = 0; d0 < 4; ++d0) { v[d0] = s0v[r][d0] - lam * (o[d0][r] * rl); ss += v[d0] * v[d0]; }
; #pragma unroll
;             for (int mk = 1; mk <= 16; mk <<= 1) ss += shx(ss, mk, lane2);
;             const float rs = rsqrtf(ss * (1.f / 128.f) + EPS) * 0.8f;
; #pragma unroll
;             for (int d0 = 0; d0 < 4; ++d0) AOb[(size_t)orow * 1024 + d0 * 32 + r32] = f2bf(v[d0] * rs * gout[d0 * 32 + r32]);
;         } }
	v_pk_add_f32 v[8:9], v[20:21], v[24:25]
	ds_bpermute_b32 v21, v168, v9
	ds_bpermute_b32 v20, v168, v8
	v_mul_f32_e32 v24, v162, v35
	v_bfe_u32 v25, v24, 16, 1
	v_mul_f32_e32 v5, v5, v34
	v_add3_u32 v24, v24, v25, s68
	s_waitcnt lgkmcnt(0)
	v_pk_add_f32 v[8:9], v[8:9], v[20:21]
	ds_bpermute_b32 v21, v167, v9
	ds_bpermute_b32 v20, v167, v8
	v_mul_f32_e32 v5, v161, v5
	global_store_short_d16_hi v[26:27], v24, off offset:1088
	v_bfe_u32 v24, v5, 16, 1
	v_add3_u32 v5, v5, v24, s68
	s_waitcnt lgkmcnt(0)
	v_pk_add_f32 v[8:9], v[8:9], v[20:21]
	ds_bpermute_b32 v21, v166, v9
	ds_bpermute_b32 v20, v166, v8
	v_mul_f32_e32 v4, v4, v34
	global_store_short_d16_hi v[26:27], v5, off offset:1152
	v_mul_f32_e32 v24, v130, v4
	v_bfe_u32 v25, v24, 16, 1
	s_waitcnt lgkmcnt(0)
	v_pk_add_f32 v[4:5], v[8:9], v[20:21]
	s_nop 0
	v_pk_fma_f32 v[4:5], v[4:5], s[24:25], v[92:93] op_sel_hi:[1,0,0]
	s_nop 0
	v_mul_f32_e32 v8, 0x4b800000, v5
	v_cmp_gt_f32_e32 vcc, s67, v5
	s_nop 1
	v_cndmask_b32_e32 v5, v5, v8, vcc
	v_rsq_f32_e32 v5, v5
	v_add3_u32 v8, v24, v25, s68
	global_store_short_d16_hi v[26:27], v8, off offset:1216
	v_lshl_add_u64 v[8:9], v[32:33], 0, v[76:77]
	v_mul_f32_e32 v20, 0x45800000, v5
	v_cndmask_b32_e32 v5, v5, v20, vcc
	v_mul_f32_e32 v5, 0x3f4ccccd, v5
	v_mul_f32_e32 v18, v18, v5
	v_mul_f32_e32 v18, v163, v18
	v_bfe_u32 v20, v18, 16, 1
	v_add3_u32 v18, v18, v20, s68
	global_store_short_d16_hi v[8:9], v18, off offset:1024
	v_mul_f32_e32 v18, v19, v5
	v_mul_f32_e32 v18, v162, v18
	v_bfe_u32 v19, v18, 16, 1
	v_add3_u32 v18, v18, v19, s68
	global_store_short_d16_hi v[8:9], v18, off offset:1088
	v_mul_f32_e32 v18, v23, v5
	v_mul_f32_e32 v18, v161, v18
	v_bfe_u32 v19, v18, 16, 1
	v_add3_u32 v18, v18, v19, s68
	global_store_short_d16_hi v[8:9], v18, off offset:1152
	v_mul_f32_e32 v18, 0x4b800000, v4
	v_cmp_gt_f32_e32 vcc, s67, v4
	v_mul_f32_e32 v5, v22, v5
	v_mul_f32_e32 v5, v130, v5
	v_cndmask_b32_e32 v4, v4, v18, vcc
	v_rsq_f32_e32 v4, v4
	v_bfe_u32 v18, v5, 16, 1
	v_add3_u32 v5, v5, v18, s68
	global_store_short_d16_hi v[8:9], v5, off offset:1216
	v_mul_f32_e32 v5, 0x45800000, v4
	v_cndmask_b32_e32 v34, v4, v5, vcc
	v_mov_b32_e32 v4, v12
	v_mov_b32_e32 v5, v60
	v_mov_b32_e32 v18, v44
	v_mov_b32_e32 v19, v28
	v_pk_mul_f32 v[4:5], v[4:5], v[0:1] op_sel_hi:[1,0]
	v_pk_mul_f32 v[18:19], v[18:19], v[0:1] op_sel_hi:[1,0]
	v_rcp_f32_e32 v0, v1
	v_mov_b32_e32 v60, v13
	v_mov_b32_e32 v28, v45
	s_waitcnt vmcnt(58)
	v_pk_fma_f32 v[4:5], v[128:129], v[4:5], v[116:117] neg_lo:[1,0,0] neg_hi:[1,0,0]
	v_pk_mul_f32 v[12:13], v[60:61], v[0:1] op_sel_hi:[1,0]
	v_pk_mul_f32 v[0:1], v[28:29], v[0:1] op_sel_hi:[1,0]
	s_waitcnt vmcnt(54)
	v_pk_fma_f32 v[12:13], v[128:129], v[12:13], v[112:113] neg_lo:[1,0,0] neg_hi:[1,0,0]
	v_pk_mul_f32 v[8:9], v[4:5], v[4:5]
	v_pk_fma_f32 v[18:19], v[128:129], v[18:19], v[114:115] neg_lo:[1,0,0] neg_hi:[1,0,0]
	v_pk_mul_f32 v[22:23], v[12:13], v[12:13]
	s_waitcnt vmcnt(52)
	v_pk_fma_f32 v[0:1], v[128:129], v[0:1], v[110:111] neg_lo:[1,0,0] neg_hi:[1,0,0]
	v_pk_mul_f32 v[20:21], v[18:19], v[18:19]
	v_pk_mul_f32 v[24:25], v[0:1], v[0:1]
	v_mov_b32_e32 v26, v22
	v_mov_b32_e32 v27, v8
	v_mov_b32_e32 v8, v23
	v_pk_add_f32 v[8:9], v[26:27], v[8:9]
	v_mov_b32_e32 v22, v25
	v_mov_b32_e32 v23, v21
	v_pk_add_f32 v[8:9], v[22:23], v[8:9]
	v_mov_b32_e32 v25, v20
	v_pk_add_f32 v[8:9], v[24:25], v[8:9]
	ds_bpermute_b32 v21, v164, v9
	ds_bpermute_b32 v20, v164, v8
	v_mul_f32_e32 v24, 0x3f4ccccd, v34
	v_mul_f32_e32 v10, v10, v24
	v_mul_f32_e32 v10, v163, v10
	v_bfe_u32 v25, v10, 16, 1
	s_waitcnt lgkmcnt(0)
	v_pk_add_f32 v[8:9], v[8:9], v[20:21]
	ds_bpermute_b32 v21, v165, v9
	ds_bpermute_b32 v20, v165, v8
	v_lshl_add_u64 v[22:23], v[32:33], 0, v[72:73]
	v_add3_u32 v10, v10, v25, s68
	global_store_short_d16_hi v[22:23], v10, off offset:1024
	v_mul_f32_e32 v25, v11, v24
	s_waitcnt lgkmcnt(0)
	v_pk_add_f32 v[8:9], v[8:9], v[20:21]
	ds_bpermute_b32 v11, v168, v9
	ds_bpermute_b32 v10, v168, v8
	v_mul_f32_e32 v20, v162, v25
	v_bfe_u32 v21, v20, 16, 1
	v_mul_f32_e32 v7, v7, v24
	v_add3_u32 v20, v20, v21, s68
	s_waitcnt lgkmcnt(0)
	v_pk_add_f32 v[8:9], v[8:9], v[10:11]
	ds_bpermute_b32 v11, v167, v9
	ds_bpermute_b32 v10, v167, v8
	v_mul_f32_e32 v7, v161, v7
	global_store_short_d16_hi v[22:23], v20, off offset:1088
	v_bfe_u32 v20, v7, 16, 1
	v_add3_u32 v7, v7, v20, s68
	s_waitcnt lgkmcnt(0)
	v_pk_add_f32 v[8:9], v[8:9], v[10:11]
	ds_bpermute_b32 v11, v166, v9
	ds_bpermute_b32 v10, v166, v8
	v_mul_f32_e32 v6, v6, v24
	global_store_short_d16_hi v[22:23], v7, off offset:1152
	v_mul_f32_e32 v20, v130, v6
	v_bfe_u32 v21, v20, 16, 1
	s_waitcnt lgkmcnt(0)
; DI unsigned short f2bf(float x) { unsigned u = __float_as_uint(x); u += 0x7fffu + ((u >> 16) & 1u); return (unsigned short)(u >> 16); }
; DI float shx(float v, int mask, int lane) { return __int_as_float(__builtin_amdgcn_ds_bpermute((lane ^ mask) << 2, __float_as_int(v))); }
; DI int crow(int r, int hi) { return (r & 3) + 8 * (r >> 2) + 4 * hi; }
; template <int DQK, int MODE, int LDQ, int LDK, int LDV> ...
;     ...
;     for (int r = 0; r < 16; ++r) { const int orow = wid * 32 + crow(r, hi); const float rl = __builtin_amdgcn_rcpf(li_l[crow(r, hi)]);
;         if constexpr (MODE == 0) {
; #pragma unroll
;             for (int d0 = 0; d0 < 4; ++d0) AOb[(size_t)orow * 1024 + d0 * 32 + r32] = f2bf(o[d0][r] * rl);
;         } else if constexpr (MODE == 1) {
; #pragma unroll
;             for (int d0 = 0; d0 < 4; ++d0) S0[(size_t)orow * 512 + d0 * 32 + r32] = o[d0][r] * rl;
;         } else {
;             float v[4]; float ss = 0.f;
; #pragma unroll
;             for (int d0 = 0; d0 < 4; ++d0) { v[d0] = s0v[r][d0] - lam * (o[d0][r] * rl); ss += v[d0] * v[d0]; }
; #pragma unroll
;             for (int mk = 1; mk <= 16; mk <<= 1) ss += shx(ss, mk, lane2);
;             const float rs = rsqrtf(ss * (1.f / 128.f) + EPS) * 0.8f;
; #pragma unroll
;             for (int d0 = 0; d0 < 4; ++d0) AOb[(size_t)orow * 1024 + d0 * 32 + r32] = f2bf(v[d0] * rs * gout[d0 * 32 + r32]);
;         } }
; DI void phase4(const Params& p, LAS unsigned char* lds, int wv) {
;     ...
;             __syncthreads();
	v_pk_add_f32 v[6:7], v[8:9], v[10:11]
	s_nop 0
	v_pk_fma_f32 v[6:7], v[6:7], s[24:25], v[92:93] op_sel_hi:[1,0,0]
	s_nop 0
	v_mul_f32_e32 v8, 0x4b800000, v7
	v_cmp_gt_f32_e32 vcc, s67, v7
	s_nop 1
	v_cndmask_b32_e32 v7, v7, v8, vcc
	v_rsq_f32_e32 v7, v7
	v_add3_u32 v8, v20, v21, s68
	global_store_short_d16_hi v[22:23], v8, off offset:1216
	v_lshl_add_u64 v[8:9], v[32:33], 0, v[74:75]
	v_mul_f32_e32 v10, 0x45800000, v7
	v_cndmask_b32_e32 v7, v7, v10, vcc
	v_mul_f32_e32 v7, 0x3f4ccccd, v7
	v_mul_f32_e32 v4, v4, v7
	v_mul_f32_e32 v4, v163, v4
	v_bfe_u32 v10, v4, 16, 1
	v_add3_u32 v4, v4, v10, s68
	global_store_short_d16_hi v[8:9], v4, off offset:1024
	v_mul_f32_e32 v4, v5, v7
	v_mul_f32_e32 v4, v162, v4
	v_bfe_u32 v5, v4, 16, 1
	v_add3_u32 v4, v4, v5, s68
	global_store_short_d16_hi v[8:9], v4, off offset:1088
	v_mul_f32_e32 v4, v19, v7
	v_mul_f32_e32 v4, v161, v4
	v_bfe_u32 v5, v4, 16, 1
	v_add3_u32 v4, v4, v5, s68
	v_mul_f32_e32 v5, 0x4b800000, v6
	v_cmp_gt_f32_e32 vcc, s67, v6
	global_store_short_d16_hi v[8:9], v4, off offset:1152
	v_mul_f32_e32 v4, v18, v7
	v_cndmask_b32_e32 v5, v6, v5, vcc
	v_rsq_f32_e32 v5, v5
	v_mul_f32_e32 v4, v130, v4
	v_bfe_u32 v6, v4, 16, 1
	v_add3_u32 v4, v4, v6, s68
	global_store_short_d16_hi v[8:9], v4, off offset:1216
	v_mul_f32_e32 v4, 0x45800000, v5
	v_cndmask_b32_e32 v24, v5, v4, vcc
	v_mov_b32_e32 v4, v14
	v_mov_b32_e32 v5, v62
	v_mov_b32_e32 v8, v46
	v_mov_b32_e32 v9, v30
	v_pk_mul_f32 v[4:5], v[4:5], v[2:3] op_sel_hi:[1,0]
	v_pk_mul_f32 v[8:9], v[8:9], v[2:3] op_sel_hi:[1,0]
	v_rcp_f32_e32 v2, v3
	v_mov_b32_e32 v62, v15
	v_mov_b32_e32 v30, v47
	s_waitcnt vmcnt(58)
	v_pk_fma_f32 v[4:5], v[128:129], v[4:5], v[108:109] neg_lo:[1,0,0] neg_hi:[1,0,0]
	v_pk_mul_f32 v[14:15], v[62:63], v[2:3] op_sel_hi:[1,0]
	v_pk_mul_f32 v[2:3], v[30:31], v[2:3] op_sel_hi:[1,0]
	s_waitcnt vmcnt(54)
	v_pk_fma_f32 v[14:15], v[128:129], v[14:15], v[104:105] neg_lo:[1,0,0] neg_hi:[1,0,0]
	v_pk_mul_f32 v[6:7], v[4:5], v[4:5]
	v_pk_fma_f32 v[8:9], v[128:129], v[8:9], v[106:107] neg_lo:[1,0,0] neg_hi:[1,0,0]
	v_pk_mul_f32 v[18:19], v[14:15], v[14:15]
	s_waitcnt vmcnt(52)
	v_pk_fma_f32 v[2:3], v[128:129], v[2:3], v[102:103] neg_lo:[1,0,0] neg_hi:[1,0,0]
	v_pk_mul_f32 v[10:11], v[8:9], v[8:9]
	v_pk_mul_f32 v[20:21], v[2:3], v[2:3]
	v_mov_b32_e32 v22, v18
	v_mov_b32_e32 v23, v6
	v_mov_b32_e32 v6, v19
	v_pk_add_f32 v[6:7], v[22:23], v[6:7]
	v_mov_b32_e32 v18, v21
	v_mov_b32_e32 v19, v11
	v_pk_add_f32 v[6:7], v[18:19], v[6:7]
	v_mov_b32_e32 v21, v10
	v_pk_add_f32 v[6:7], v[20:21], v[6:7]
	ds_bpermute_b32 v11, v164, v7
	ds_bpermute_b32 v10, v164, v6
	v_mul_f32_e32 v20, 0x3f4ccccd, v24
	v_mul_f32_e32 v12, v12, v20
	v_mul_f32_e32 v12, v163, v12
	v_bfe_u32 v21, v12, 16, 1
	s_waitcnt lgkmcnt(0)
	v_pk_add_f32 v[6:7], v[6:7], v[10:11]
	ds_bpermute_b32 v11, v165, v7
	ds_bpermute_b32 v10, v165, v6
	v_lshl_add_u64 v[18:19], v[32:33], 0, v[64:65]
	v_add3_u32 v12, v12, v21, s68
	global_store_short_d16_hi v[18:19], v12, off offset:1024
	v_mul_f32_e32 v12, v13, v20
	s_waitcnt lgkmcnt(0)
	v_pk_add_f32 v[6:7], v[6:7], v[10:11]
	ds_bpermute_b32 v11, v168, v7
	ds_bpermute_b32 v10, v168, v6
	v_mul_f32_e32 v12, v162, v12
	v_bfe_u32 v13, v12, 16, 1
	v_mul_f32_e32 v1, v1, v20
	v_add3_u32 v12, v12, v13, s68
	s_waitcnt lgkmcnt(0)
	v_pk_add_f32 v[6:7], v[6:7], v[10:11]
	ds_bpermute_b32 v11, v167, v7
	ds_bpermute_b32 v10, v167, v6
	v_mul_f32_e32 v1, v161, v1
	global_store_short_d16_hi v[18:19], v12, off offset:1088
	v_bfe_u32 v12, v1, 16, 1
	v_add3_u32 v1, v1, v12, s68
	s_waitcnt lgkmcnt(0)
	v_pk_add_f32 v[6:7], v[6:7], v[10:11]
	ds_bpermute_b32 v11, v166, v7
	ds_bpermute_b32 v10, v166, v6
	v_mul_f32_e32 v0, v0, v20
	global_store_short_d16_hi v[18:19], v1, off offset:1152
	v_mul_f32_e32 v12, v130, v0
	v_bfe_u32 v13, v12, 16, 1
	s_waitcnt lgkmcnt(0)
	v_pk_add_f32 v[0:1], v[6:7], v[10:11]
	s_nop 0
	v_pk_fma_f32 v[0:1], v[0:1], s[24:25], v[92:93] op_sel_hi:[1,0,0]
	s_nop 0
	v_mul_f32_e32 v6, 0x4b800000, v1
	v_cmp_gt_f32_e32 vcc, s67, v1
	s_nop 1
	v_cndmask_b32_e32 v1, v1, v6, vcc
	v_rsq_f32_e32 v1, v1
	v_add3_u32 v6, v12, v13, s68
	global_store_short_d16_hi v[18:19], v6, off offset:1216
	v_lshl_add_u64 v[6:7], v[32:33], 0, v[48:49]
	v_mul_f32_e32 v10, 0x45800000, v1
	v_cndmask_b32_e32 v1, v1, v10, vcc
	v_mul_f32_e32 v1, 0x3f4ccccd, v1
	v_mul_f32_e32 v4, v4, v1
	v_mul_f32_e32 v4, v163, v4
	v_bfe_u32 v10, v4, 16, 1
	v_add3_u32 v4, v4, v10, s68
	global_store_short_d16_hi v[6:7], v4, off offset:1024
	v_mul_f32_e32 v4, v5, v1
	v_mul_f32_e32 v4, v162, v4
	v_bfe_u32 v5, v4, 16, 1
	v_add3_u32 v4, v4, v5, s68
	global_store_short_d16_hi v[6:7], v4, off offset:1088
	v_mul_f32_e32 v4, v9, v1
	v_mul_f32_e32 v4, v161, v4
	v_bfe_u32 v5, v4, 16, 1
	v_add3_u32 v4, v4, v5, s68
	global_store_short_d16_hi v[6:7], v4, off offset:1152
	v_mul_f32_e32 v4, 0x4b800000, v0
	v_cmp_gt_f32_e32 vcc, s67, v0
	v_mul_f32_e32 v1, v8, v1
	v_mul_f32_e32 v1, v130, v1
	v_cndmask_b32_e32 v0, v0, v4, vcc
	v_rsq_f32_e32 v0, v0
	v_bfe_u32 v4, v1, 16, 1
	v_add3_u32 v1, v1, v4, s68
	global_store_short_d16_hi v[6:7], v1, off offset:1216
	v_mul_f32_e32 v1, 0x45800000, v0
	v_cndmask_b32_e32 v0, v0, v1, vcc
	v_mul_f32_e32 v4, 0x3f4ccccd, v0
	v_mul_f32_e32 v5, v14, v4
	v_mul_f32_e32 v5, v163, v5
	v_bfe_u32 v6, v5, 16, 1
	v_lshl_add_u64 v[0:1], v[32:33], 0, v[16:17]
	v_add3_u32 v5, v5, v6, s68
	global_store_short_d16_hi v[0:1], v5, off offset:1024
	v_mul_f32_e32 v5, v15, v4
	v_mul_f32_e32 v5, v162, v5
	v_bfe_u32 v6, v5, 16, 1
	v_mul_f32_e32 v3, v3, v4
	v_add3_u32 v5, v5, v6, s68
	v_mul_f32_e32 v3, v161, v3
	global_store_short_d16_hi v[0:1], v5, off offset:1088
	v_bfe_u32 v5, v3, 16, 1
	v_mul_f32_e32 v2, v2, v4
	v_add3_u32 v3, v3, v5, s68
	v_mul_f32_e32 v2, v130, v2
	global_store_short_d16_hi v[0:1], v3, off offset:1152
	v_bfe_u32 v3, v2, 16, 1
	v_add3_u32 v2, v2, v3, s68
	global_store_short_d16_hi v[0:1], v2, off offset:1216
	s_waitcnt vmcnt(63) expcnt(7) lgkmcnt(15)
	s_barrier

; #define LAS __attribute__((address_space(3)))
; DI void expsum(f32x16& p, float& l_reg, bf16x8& pa0, bf16x8& pa1) {
; #pragma unroll
;     for (int r = 0; r < 16; ++r) p[r] = __builtin_amdgcn_exp2f(p[r]);
;     float ps = 0.f;
; #pragma unroll
;     for (int r = 0; r < 16; ++r) ps += p[r];
;     l_reg += ps; asm volatile("" : "+v"(l_reg));
;     ...
;     ATT_PK4(p, 0, pa0); ATT_PK4(p, 8, pa1);
;     ...
; }
; DI int v_rd_base(int lane) { return ((lane & 3) << 3) | (((lane >> 2) & 3) << 6) | (((lane >> 4) & 1) << 5) | (((lane >> 5) & 1) << 8); }
; template <int OFF> DI s16x4 tr_read(int vb) { s16x4 r; asm volatile("ds_read_b64_tr_b16 %0, %1 offset:%2" : "=&v"(r) : "v"(vb), "i"(OFF) : "memory"); return r; }
; template <int H> DI void v_reads(s16x4* vf, int vb) {
;     vf[0] = tr_read<v_rd_off(0, 2 * H, 0)>(vb); vf[1] = tr_read<v_rd_off(0, 2 * H, 1)>(vb); vf[2] = tr_read<v_rd_off(0, 2 * H + 1, 0)>(vb); vf[3] = tr_read<v_rd_off(0, 2 * H + 1, 1)>(vb);
;     vf[4] = tr_read<v_rd_off(1, 2 * H, 0)>(vb); vf[5] = tr_read<v_rd_off(1, 2 * H, 1)>(vb); vf[6] = tr_read<v_rd_off(1, 2 * H + 1, 0)>(vb); vf[7] = tr_read<v_rd_off(1, 2 * H + 1, 1)>(vb);
;     vf[8] = tr_read<v_rd_off(2, 2 * H, 0)>(vb); vf[9] = tr_read<v_rd_off(2, 2 * H, 1)>(vb); vf[10] = tr_read<v_rd_off(2, 2 * H + 1, 0)>(vb); vf[11] = tr_read<v_rd_off(2, 2 * H + 1, 1)>(vb);
;     vf[12] = tr_read<v_rd_off(3, 2 * H, 0)>(vb); vf[13] = tr_read<v_rd_off(3, 2 * H, 1)>(vb); vf[14] = tr_read<v_rd_off(3, 2 * H + 1, 0)>(vb); vf[15] = tr_read<v_rd_off(3, 2 * H + 1, 1)>(vb);
; }
; DI void pv_mma(f32x16* o, const s16x4* vf, bf16x8 pa0, bf16x8 pa1) {
;     ...
; #pragma unroll
;     for (int d0 = 0; d0 < 4; ++d0) {
;         o[d0] = __builtin_amdgcn_mfma_f32_32x32x16_bf16(pa0, ATT_PK(vf[4 * d0], vf[4 * d0 + 1]), o[d0], 0, 0, 0);
;         o[d0] = __builtin_amdgcn_mfma_f32_32x32x16_bf16(pa1, ATT_PK(vf[4 * d0 + 2], vf[4 * d0 + 3]), o[d0], 0, 0, 0); }
;     ...
; }
; template <int DQK, int D0A, int D0B> DI void k_reads(bf16x8* kf, const LAS unsigned char* Ks, int half, int r32, int hi) {
; #pragma unroll
;     for (int d0 = D0A; d0 < D0B; ++d0) kf[d0 - D0A] = *(const LAS bf16x8*)(Ks + half * (32 * DQK * 2) + kswz<DQK>(r32, (d0 * 16 + hi * 8) * 2));
; }
; template <int D0A, int D0B> DI void qk_mma(f32x16& p, const bf16x8* kf, const bf16x8* qr) {
; #pragma unroll
;     for (int d0 = D0A; d0 < D0B; ++d0) {
.Lstg_mla_top_2:
	s_mov_b32 m0, s1
	s_mov_b32 s0, s5
	s_mov_b32 s5, s44
	s_mov_b32 s44, s4
	s_lshl_b32 s4, s4, 14
	global_load_lds_dwordx4 v136, s[34:35]
	s_add_i32 m0, s1, 0x2000
	s_add_i32 s4, s52, s4
	global_load_lds_dwordx4 v138, s[34:35]
	s_add_i32 m0, s1, 0x4000
	s_add_i32 s6, s4, 0x400
	global_load_lds_dwordx4 v140, s[34:35]
	s_mov_b32 m0, s4
	s_add_i32 s1, s43, -3
	global_load_lds_dwordx4 v144, s[34:35]
	s_mov_b32 m0, s6
	s_nop 0
	global_load_lds_dwordx4 v142, s[34:35]
	s_and_b32 s1, s1, 3
	s_mulk_i32 s1, 0x6000
	v_add_u32_e32 v246, s1, v158
	v_add_u32_e32 v174, v246, v151
	v_add_u32_e32 v178, v246, v149
	v_add_u32_e32 v182, v246, v148
	v_add_u32_e32 v186, v246, v147
	v_add_u32_e32 v190, v246, v146
	v_add_u32_e32 v194, v246, v150
	s_lshl_b32 s1, s0, 14
	ds_read_b128 v[174:177], v174 offset:12288
	ds_read_b128 v[178:181], v178 offset:12288
	ds_read_b128 v[182:185], v182 offset:12288
	ds_read_b128 v[186:189], v186 offset:12288
	ds_read_b128 v[190:193], v190 offset:12288
	ds_read_b128 v[194:197], v194 offset:12288
	v_add_u32_e32 v254, s1, v130
	ds_read_b64_tr_b16 v[198:199], v254 offset:0
	ds_read_b64_tr_b16 v[200:201], v254 offset:0x800
	ds_read_b64_tr_b16 v[202:203], v254 offset:0x1000
	ds_read_b64_tr_b16 v[204:205], v254 offset:0x1800
	ds_read_b64_tr_b16 v[206:207], v254 offset:0x200
	ds_read_b64_tr_b16 v[208:209], v254 offset:0xa00
	ds_read_b64_tr_b16 v[210:211], v254 offset:0x1200
	ds_read_b64_tr_b16 v[212:213], v254 offset:0x1a00
	ds_read_b64_tr_b16 v[214:215], v254 offset:0x400
	ds_read_b64_tr_b16 v[216:217], v254 offset:0xc00
	ds_read_b64_tr_b16 v[218:219], v254 offset:0x1400
	ds_read_b64_tr_b16 v[220:221], v254 offset:0x1c00
	ds_read_b64_tr_b16 v[222:223], v254 offset:0x600
	ds_read_b64_tr_b16 v[224:225], v254 offset:0xe00
	ds_read_b64_tr_b16 v[226:227], v254 offset:0x1600
	ds_read_b64_tr_b16 v[228:229], v254 offset:0x1e00
	s_setprio 3
	v_exp_f32_e32 v64, v64
	v_exp_f32_e32 v65, v65
	v_exp_f32_e32 v66, v66
	v_exp_f32_e32 v67, v67
	v_exp_f32_e32 v68, v68
	v_add_f32_e32 v230, 0, v64
	v_exp_f32_e32 v69, v69
	v_add_f32_e32 v230, v65, v230
	v_exp_f32_e32 v70, v70
	v_add_f32_e32 v230, v66, v230
	v_exp_f32_e32 v71, v71
	v_add_f32_e32 v230, v67, v230
	v_exp_f32_e32 v72, v72
	v_add_f32_e32 v230, v68, v230
	v_exp_f32_e32 v73, v73
	v_add_f32_e32 v230, v69, v230
	v_exp_f32_e32 v74, v74
	v_add_f32_e32 v230, v70, v230
	v_exp_f32_e32 v75, v75
	v_add_f32_e32 v230, v71, v230
	v_exp_f32_e32 v76, v76
	v_add_f32_e32 v230, v72, v230
	v_exp_f32_e32 v77, v77
	v_add_f32_e32 v230, v73, v230
	v_exp_f32_e32 v78, v78
	v_add_f32_e32 v230, v74, v230
	v_exp_f32_e32 v79, v79
	v_add_f32_e32 v230, v75, v230
	v_add_f32_e32 v230, v76, v230
	v_add_f32_e32 v230, v77, v230
	v_add_f32_e32 v230, v78, v230
	v_add_f32_e32 v230, v79, v230
	v_add_f32_e32 v173, v173, v230
	v_cvt_pk_bf16_f32 v64, v64, v65
	v_cvt_pk_bf16_f32 v65, v66, v67
	v_cvt_pk_bf16_f32 v66, v68, v69
	v_cvt_pk_bf16_f32 v67, v70, v71
	v_cvt_pk_bf16_f32 v68, v72, v73
	v_cvt_pk_bf16_f32 v69, v74, v75
	v_cvt_pk_bf16_f32 v70, v76, v77
	v_cvt_pk_bf16_f32 v71, v78, v79
	s_nop 0
	v_permlane32_swap_b32_e32 v64, v66
	v_permlane32_swap_b32_e32 v65, v67
	v_permlane32_swap_b32_e32 v68, v70
	v_permlane32_swap_b32_e32 v69, v71
	s_waitcnt lgkmcnt(0)
	v_add_u32_e32 v72, v246, v152
	v_add_u32_e32 v73, v246, v153
	ds_read_b128 v[230:233], v72 offset:12288
	ds_read_b128 v[234:237], v73 offset:12288
	v_add_u32_e32 v72, v246, v154
	v_add_u32_e32 v73, v246, v155
	ds_read_b128 v[238:241], v72 offset:12288
	ds_read_b128 v[242:245], v73 offset:12288
	v_add_u32_e32 v72, v246, v156
	v_add_u32_e32 v73, v246, v157
	ds_read_b128 v[246:249], v72 offset:12288
	ds_read_b128 v[250:253], v73 offset:12288
	s_setprio 0
	v_mfma_f32_32x32x16_bf16 v[48:63], v[64:67], v[198:201], v[48:63]
	v_mfma_f32_32x32x16_bf16 v[32:47], v[64:67], v[206:209], v[32:47]
	v_mfma_f32_32x32x16_bf16 v[16:31], v[64:67], v[214:217], v[16:31]
	v_mfma_f32_32x32x16_bf16 v[0:15], v[64:67], v[222:225], v[0:15]
	v_mfma_f32_32x32x16_bf16 v[48:63], v[68:71], v[202:205], v[48:63]
	v_mfma_f32_32x32x16_bf16 v[32:47], v[68:71], v[210:213], v[32:47]
	v_mfma_f32_32x32x16_bf16 v[16:31], v[68:71], v[218:221], v[16:31]
	v_mfma_f32_32x32x16_bf16 v[0:15], v[68:71], v[226:229], v[0:15]
	s_waitcnt lgkmcnt(0)
; #define LAS __attribute__((address_space(3)))
; DI void expsum(f32x16& p, float& l_reg, bf16x8& pa0, bf16x8& pa1) {
; #pragma unroll
;     for (int r = 0; r < 16; ++r) p[r] = __builtin_amdgcn_exp2f(p[r]);
;     float ps = 0.f;
; #pragma unroll
;     for (int r = 0; r < 16; ++r) ps += p[r];
;     l_reg += ps; asm volatile("" : "+v"(l_reg));
;     ...
;     ATT_PK4(p, 0, pa0); ATT_PK4(p, 8, pa1);
;     ...
; }
; DI int v_rd_base(int lane) { return ((lane & 3) << 3) | (((lane >> 2) & 3) << 6) | (((lane >> 4) & 1) << 5) | (((lane >> 5) & 1) << 8); }
; template <int OFF> DI s16x4 tr_read(int vb) { s16x4 r; asm volatile("ds_read_b64_tr_b16 %0, %1 offset:%2" : "=&v"(r) : "v"(vb), "i"(OFF) : "memory"); return r; }
; template <int H> DI void v_reads(s16x4* vf, int vb) {
;     vf[0] = tr_read<v_rd_off(0, 2 * H, 0)>(vb); vf[1] = tr_read<v_rd_off(0, 2 * H, 1)>(vb); vf[2] = tr_read<v_rd_off(0, 2 * H + 1, 0)>(vb); vf[3] = tr_read<v_rd_off(0, 2 * H + 1, 1)>(vb);
;     vf[4] = tr_read<v_rd_off(1, 2 * H, 0)>(vb); vf[5] = tr_read<v_rd_off(1, 2 * H, 1)>(vb); vf[6] = tr_read<v_rd_off(1, 2 * H + 1, 0)>(vb); vf[7] = tr_read<v_rd_off(1, 2 * H + 1, 1)>(vb);
;     vf[8] = tr_read<v_rd_off(2, 2 * H, 0)>(vb); vf[9] = tr_read<v_rd_off(2, 2 * H, 1)>(vb); vf[10] = tr_read<v_rd_off(2, 2 * H + 1, 0)>(vb); vf[11] = tr_read<v_rd_off(2, 2 * H + 1, 1)>(vb);
;     vf[12] = tr_read<v_rd_off(3, 2 * H, 0)>(vb); vf[13] = tr_read<v_rd_off(3, 2 * H, 1)>(vb); vf[14] = tr_read<v_rd_off(3, 2 * H + 1, 0)>(vb); vf[15] = tr_read<v_rd_off(3, 2 * H + 1, 1)>(vb);
; }
; DI void pv_mma(f32x16* o, const s16x4* vf, bf16x8 pa0, bf16x8 pa1) {
;     ...
; #pragma unroll
;     for (int d0 = 0; d0 < 4; ++d0) {
;         o[d0] = __builtin_amdgcn_mfma_f32_32x32x16_bf16(pa0, ATT_PK(vf[4 * d0], vf[4 * d0 + 1]), o[d0], 0, 0, 0);
;         o[d0] = __builtin_amdgcn_mfma_f32_32x32x16_bf16(pa1, ATT_PK(vf[4 * d0 + 2], vf[4 * d0 + 3]), o[d0], 0, 0, 0); }
;     ...
; }
; template <int DQK, int D0A, int D0B> DI void k_reads(bf16x8* kf, const LAS unsigned char* Ks, int half, int r32, int hi) {
; #pragma unroll
;     for (int d0 = D0A; d0 < D0B; ++d0) kf[d0 - D0A] = *(const LAS bf16x8*)(Ks + half * (32 * DQK * 2) + kswz<DQK>(r32, (d0 * 16 + hi * 8) * 2));
; }
; template <int D0A, int D0B> DI void qk_mma(f32x16& p, const bf16x8* kf, const bf16x8* qr) {
; #pragma unroll
;     for (int d0 = D0A; d0 < D0B; ++d0) {
	v_mfma_f32_32x32x16_bf16 v[64:79], v[174:177], v[80:83], 0
	v_mfma_f32_32x32x16_bf16 v[64:79], v[178:181], v[84:87], v[64:79]
	v_mfma_f32_32x32x16_bf16 v[64:79], v[182:185], v[88:91], v[64:79]
	v_mfma_f32_32x32x16_bf16 v[64:79], v[186:189], v[92:95], v[64:79]
	v_mfma_f32_32x32x16_bf16 v[64:79], v[190:193], v[96:99], v[64:79]
	v_mfma_f32_32x32x16_bf16 v[64:79], v[194:197], v[100:103], v[64:79]
	v_mfma_f32_32x32x16_bf16 v[64:79], v[230:233], v[104:107], v[64:79]
	v_mfma_f32_32x32x16_bf16 v[64:79], v[234:237], v[108:111], v[64:79]
	v_mfma_f32_32x32x16_bf16 v[64:79], v[238:241], v[112:115], v[64:79]
	v_mfma_f32_32x32x16_bf16 v[64:79], v[242:245], v[116:119], v[64:79]
	v_mfma_f32_32x32x16_bf16 v[64:79], v[246:249], v[120:123], v[64:79]
	v_mfma_f32_32x32x16_bf16 v[64:79], v[250:253], v[124:127], v[64:79]
	s_add_i32 s4, s43, -2
	s_and_b32 s4, s4, 3
	s_mulk_i32 s4, 0x6000
	v_add_u32_e32 v246, s4, v158
	v_add_u32_e32 v174, v246, v151
	v_add_u32_e32 v178, v246, v149
	v_add_u32_e32 v182, v246, v148
	v_add_u32_e32 v186, v246, v147
	v_add_u32_e32 v190, v246, v146
	v_add_u32_e32 v194, v246, v150
	ds_read_b128 v[174:177], v174
	ds_read_b128 v[178:181], v178
	ds_read_b128 v[182:185], v182
	ds_read_b128 v[186:189], v186
	ds_read_b128 v[190:193], v190
	ds_read_b128 v[194:197], v194
	ds_read_b64_tr_b16 v[198:199], v254 offset:0x2000
	ds_read_b64_tr_b16 v[200:201], v254 offset:0x2800
	ds_read_b64_tr_b16 v[202:203], v254 offset:0x3000
	ds_read_b64_tr_b16 v[204:205], v254 offset:0x3800
	ds_read_b64_tr_b16 v[206:207], v254 offset:0x2200
	ds_read_b64_tr_b16 v[208:209], v254 offset:0x2a00
	ds_read_b64_tr_b16 v[210:211], v254 offset:0x3200
	ds_read_b64_tr_b16 v[212:213], v254 offset:0x3a00
	ds_read_b64_tr_b16 v[214:215], v254 offset:0x2400
	ds_read_b64_tr_b16 v[216:217], v254 offset:0x2c00
	ds_read_b64_tr_b16 v[218:219], v254 offset:0x3400
	ds_read_b64_tr_b16 v[220:221], v254 offset:0x3c00
	ds_read_b64_tr_b16 v[222:223], v254 offset:0x2600
	ds_read_b64_tr_b16 v[224:225], v254 offset:0x2e00
	ds_read_b64_tr_b16 v[226:227], v254 offset:0x3600
	ds_read_b64_tr_b16 v[228:229], v254 offset:0x3e00
	s_setprio 3
	v_exp_f32_e32 v64, v64
	v_exp_f32_e32 v65, v65
	v_exp_f32_e32 v66, v66
	v_exp_f32_e32 v67, v67
	v_exp_f32_e32 v68, v68
	v_add_f32_e32 v230, 0, v64
	v_exp_f32_e32 v69, v69
	v_add_f32_e32 v230, v65, v230
	v_exp_f32_e32 v70, v70
	v_add_f32_e32 v230, v66, v230
	v_exp_f32_e32 v71, v71
	v_add_f32_e32 v230, v67, v230
	v_exp_f32_e32 v72, v72
	v_add_f32_e32 v230, v68, v230
	v_exp_f32_e32 v73, v73
	v_add_f32_e32 v230, v69, v230
	v_exp_f32_e32 v74, v74
	v_add_f32_e32 v230, v70, v230
	v_exp_f32_e32 v75, v75
	v_add_f32_e32 v230, v71, v230
	v_exp_f32_e32 v76, v76
	v_add_f32_e32 v230, v72, v230
	v_exp_f32_e32 v77, v77
	v_add_f32_e32 v230, v73, v230
	v_exp_f32_e32 v78, v78
	v_add_f32_e32 v230, v74, v230
	v_exp_f32_e32 v79, v79
	v_add_f32_e32 v230, v75, v230
	v_add_f32_e32 v230, v76, v230
	v_add_f32_e32 v230, v77, v230
	v_add_f32_e32 v230, v78, v230
	v_add_f32_e32 v230, v79, v230
	v_add_f32_e32 v173, v173, v230
	v_cvt_pk_bf16_f32 v64, v64, v65
	v_cvt_pk_bf16_f32 v65, v66, v67
	v_cvt_pk_bf16_f32 v66, v68, v69
	v_cvt_pk_bf16_f32 v67, v70, v71
	v_cvt_pk_bf16_f32 v68, v72, v73
	v_cvt_pk_bf16_f32 v69, v74, v75
	v_cvt_pk_bf16_f32 v70, v76, v77
	v_cvt_pk_bf16_f32 v71, v78, v79
	s_nop 0
	v_permlane32_swap_b32_e32 v64, v66
	v_permlane32_swap_b32_e32 v65, v67
	v_permlane32_swap_b32_e32 v68, v70
	v_permlane32_swap_b32_e32 v69, v71
	s_waitcnt lgkmcnt(0)
	v_add_u32_e32 v72, v246, v152
	v_add_u32_e32 v73, v246, v153
	ds_read_b128 v[230:233], v72
	ds_read_b128 v[234:237], v73
	v_add_u32_e32 v72, v246, v154
	v_add_u32_e32 v73, v246, v155
	ds_read_b128 v[238:241], v72
	ds_read_b128 v[242:245], v73
	v_add_u32_e32 v72, v246, v156
	v_add_u32_e32 v73, v246, v157
	ds_read_b128 v[246:249], v72
	ds_read_b128 v[250:253], v73
	s_setprio 0
	s_cmp_lt_u32 s33, 0x100
	s_cbranch_scc1 .Lstg_mla_mid_3
	s_waitcnt vmcnt(5)
	s_barrier

; #define LAS __attribute__((address_space(3)))
; DI void expsum(f32x16& p, float& l_reg, bf16x8& pa0, bf16x8& pa1) {
; #pragma unroll
;     for (int r = 0; r < 16; ++r) p[r] = __builtin_amdgcn_exp2f(p[r]);
;     float ps = 0.f;
; #pragma unroll
;     for (int r = 0; r < 16; ++r) ps += p[r];
;     l_reg += ps; asm volatile("" : "+v"(l_reg));
;     ...
;     ATT_PK4(p, 0, pa0); ATT_PK4(p, 8, pa1);
;     ...
; }
; DI int v_rd_base(int lane) { return ((lane & 3) << 3) | (((lane >> 2) & 3) << 6) | (((lane >> 4) & 1) << 5) | (((lane >> 5) & 1) << 8); }
; template <int OFF> DI s16x4 tr_read(int vb) { s16x4 r; asm volatile("ds_read_b64_tr_b16 %0, %1 offset:%2" : "=&v"(r) : "v"(vb), "i"(OFF) : "memory"); return r; }
; template <int H> DI void v_reads(s16x4* vf, int vb) {
;     vf[0] = tr_read<v_rd_off(0, 2 * H, 0)>(vb); vf[1] = tr_read<v_rd_off(0, 2 * H, 1)>(vb); vf[2] = tr_read<v_rd_off(0, 2 * H + 1, 0)>(vb); vf[3] = tr_read<v_rd_off(0, 2 * H + 1, 1)>(vb);
;     vf[4] = tr_read<v_rd_off(1, 2 * H, 0)>(vb); vf[5] = tr_read<v_rd_off(1, 2 * H, 1)>(vb); vf[6] = tr_read<v_rd_off(1, 2 * H + 1, 0)>(vb); vf[7] = tr_read<v_rd_off(1, 2 * H + 1, 1)>(vb);
;     vf[8] = tr_read<v_rd_off(2, 2 * H, 0)>(vb); vf[9] = tr_read<v_rd_off(2, 2 * H, 1)>(vb); vf[10] = tr_read<v_rd_off(2, 2 * H + 1, 0)>(vb); vf[11] = tr_read<v_rd_off(2, 2 * H + 1, 1)>(vb);
;     vf[12] = tr_read<v_rd_off(3, 2 * H, 0)>(vb); vf[13] = tr_read<v_rd_off(3, 2 * H, 1)>(vb); vf[14] = tr_read<v_rd_off(3, 2 * H + 1, 0)>(vb); vf[15] = tr_read<v_rd_off(3, 2 * H + 1, 1)>(vb);
; }
; DI void pv_mma(f32x16* o, const s16x4* vf, bf16x8 pa0, bf16x8 pa1) {
;     ...
; #pragma unroll
;     for (int d0 = 0; d0 < 4; ++d0) {
;         o[d0] = __builtin_amdgcn_mfma_f32_32x32x16_bf16(pa0, ATT_PK(vf[4 * d0], vf[4 * d0 + 1]), o[d0], 0, 0, 0);
;         o[d0] = __builtin_amdgcn_mfma_f32_32x32x16_bf16(pa1, ATT_PK(vf[4 * d0 + 2], vf[4 * d0 + 3]), o[d0], 0, 0, 0); }
;     ...
; }
; template <int DQK, int D0A, int D0B> DI void k_reads(bf16x8* kf, const LAS unsigned char* Ks, int half, int r32, int hi) {
; #pragma unroll
;     for (int d0 = D0A; d0 < D0B; ++d0) kf[d0 - D0A] = *(const LAS bf16x8*)(Ks + half * (32 * DQK * 2) + kswz<DQK>(r32, (d0 * 16 + hi * 8) * 2));
; }
; template <int D0A, int D0B> DI void qk_mma(f32x16& p, const bf16x8* kf, const bf16x8* qr) {
; #pragma unroll
;     for (int d0 = D0A; d0 < D0B; ++d0) {
.Lstg_mla_t61_4:
	v_lshl_add_u64 v[132:133], v[132:133], 1, s[0:1]
	s_mov_b32 m0, s6
	v_lshl_add_u64 v[134:135], v[134:135], 1, s[0:1]
	global_load_lds_dwordx4 v[132:133], off
	s_mov_b32 m0, s7
	s_nop 0
	global_load_lds_dwordx4 v[134:135], off
	ds_read_b128 v[132:135], v161 offset:36864
	ds_read_b128 v[136:139], v162 offset:36864
	ds_read_b128 v[140:143], v163 offset:36864
	ds_read_b128 v[174:177], v164 offset:36864
	ds_read_b128 v[178:181], v165 offset:36864
	ds_read_b128 v[182:185], v166 offset:36864
	v_lshl_add_u32 v144, s5, 14, v130
	ds_read_b64_tr_b16 v[186:187], v144 offset:0
	ds_read_b64_tr_b16 v[188:189], v144 offset:0x800
	ds_read_b64_tr_b16 v[190:191], v144 offset:0x1000
	ds_read_b64_tr_b16 v[192:193], v144 offset:0x1800
	ds_read_b64_tr_b16 v[194:195], v144 offset:0x200
	ds_read_b64_tr_b16 v[196:197], v144 offset:0xa00
	ds_read_b64_tr_b16 v[198:199], v144 offset:0x1200
	ds_read_b64_tr_b16 v[200:201], v144 offset:0x1a00
	ds_read_b64_tr_b16 v[202:203], v144 offset:0x400
	ds_read_b64_tr_b16 v[204:205], v144 offset:0xc00
	ds_read_b64_tr_b16 v[206:207], v144 offset:0x1400
	ds_read_b64_tr_b16 v[208:209], v144 offset:0x1c00
	ds_read_b64_tr_b16 v[210:211], v144 offset:0x600
	ds_read_b64_tr_b16 v[212:213], v144 offset:0xe00
	ds_read_b64_tr_b16 v[214:215], v144 offset:0x1600
	ds_read_b64_tr_b16 v[216:217], v144 offset:0x1e00
	s_setprio 3
	v_exp_f32_e32 v64, v64
	v_exp_f32_e32 v65, v65
	v_exp_f32_e32 v66, v66
	v_exp_f32_e32 v67, v67
	v_exp_f32_e32 v68, v68
	v_add_f32_e32 v145, 0, v64
	v_exp_f32_e32 v69, v69
	v_add_f32_e32 v145, v65, v145
	v_exp_f32_e32 v70, v70
	v_add_f32_e32 v145, v66, v145
	v_exp_f32_e32 v71, v71
	v_add_f32_e32 v145, v67, v145
	v_exp_f32_e32 v72, v72
	v_add_f32_e32 v145, v68, v145
	v_exp_f32_e32 v73, v73
	v_add_f32_e32 v145, v69, v145
	v_exp_f32_e32 v74, v74
	v_add_f32_e32 v145, v70, v145
	v_exp_f32_e32 v75, v75
	v_add_f32_e32 v145, v71, v145
	v_exp_f32_e32 v76, v76
	v_add_f32_e32 v145, v72, v145
	v_exp_f32_e32 v77, v77
	v_add_f32_e32 v145, v73, v145
	v_exp_f32_e32 v78, v78
	v_add_f32_e32 v145, v74, v145
	v_exp_f32_e32 v79, v79
	v_add_f32_e32 v145, v75, v145
	v_add_f32_e32 v145, v76, v145
	v_add_f32_e32 v145, v77, v145
	v_add_f32_e32 v145, v78, v145
	v_add_f32_e32 v145, v79, v145
	v_add_f32_e32 v145, v173, v145
	v_cvt_pk_bf16_f32 v64, v64, v65
	v_cvt_pk_bf16_f32 v65, v66, v67
	v_cvt_pk_bf16_f32 v66, v68, v69
	v_cvt_pk_bf16_f32 v67, v70, v71
	v_cvt_pk_bf16_f32 v68, v72, v73
	v_cvt_pk_bf16_f32 v69, v74, v75
	v_cvt_pk_bf16_f32 v70, v76, v77
	v_cvt_pk_bf16_f32 v71, v78, v79
	s_nop 0
	v_permlane32_swap_b32_e32 v64, v66
	v_permlane32_swap_b32_e32 v65, v67
	v_permlane32_swap_b32_e32 v68, v70
	v_permlane32_swap_b32_e32 v69, v71
	s_waitcnt lgkmcnt(0)
	ds_read_b128 v[218:221], v167 offset:36864
	ds_read_b128 v[222:225], v168 offset:36864
	ds_read_b128 v[226:229], v169 offset:36864
	ds_read_b128 v[230:233], v170 offset:36864
	ds_read_b128 v[234:237], v171 offset:36864
	ds_read_b128 v[238:241], v172 offset:36864
	s_setprio 0
	v_mfma_f32_32x32x16_bf16 v[48:63], v[64:67], v[186:189], v[48:63]
	v_mfma_f32_32x32x16_bf16 v[32:47], v[64:67], v[194:197], v[32:47]
	v_mfma_f32_32x32x16_bf16 v[16:31], v[64:67], v[202:205], v[16:31]
	v_mfma_f32_32x32x16_bf16 v[0:15], v[64:67], v[210:213], v[0:15]
	v_mfma_f32_32x32x16_bf16 v[48:63], v[68:71], v[190:193], v[48:63]
	v_mfma_f32_32x32x16_bf16 v[32:47], v[68:71], v[198:201], v[32:47]
	v_mfma_f32_32x32x16_bf16 v[16:31], v[68:71], v[206:209], v[16:31]
	v_mfma_f32_32x32x16_bf16 v[0:15], v[68:71], v[214:217], v[0:15]
	s_waitcnt lgkmcnt(0)
; #define LAS __attribute__((address_space(3)))
; DI void expsum(f32x16& p, float& l_reg, bf16x8& pa0, bf16x8& pa1) {
; #pragma unroll
;     for (int r = 0; r < 16; ++r) p[r] = __builtin_amdgcn_exp2f(p[r]);
;     float ps = 0.f;
; #pragma unroll
;     for (int r = 0; r < 16; ++r) ps += p[r];
;     l_reg += ps; asm volatile("" : "+v"(l_reg));
;     ...
;     ATT_PK4(p, 0, pa0); ATT_PK4(p, 8, pa1);
;     ...
; }
; DI int v_rd_base(int lane) { return ((lane & 3) << 3) | (((lane >> 2) & 3) << 6) | (((lane >> 4) & 1) << 5) | (((lane >> 5) & 1) << 8); }
; template <int OFF> DI s16x4 tr_read(int vb) { s16x4 r; asm volatile("ds_read_b64_tr_b16 %0, %1 offset:%2" : "=&v"(r) : "v"(vb), "i"(OFF) : "memory"); return r; }
; template <int H> DI void v_reads(s16x4* vf, int vb) {
;     vf[0] = tr_read<v_rd_off(0, 2 * H, 0)>(vb); vf[1] = tr_read<v_rd_off(0, 2 * H, 1)>(vb); vf[2] = tr_read<v_rd_off(0, 2 * H + 1, 0)>(vb); vf[3] = tr_read<v_rd_off(0, 2 * H + 1, 1)>(vb);
;     vf[4] = tr_read<v_rd_off(1, 2 * H, 0)>(vb); vf[5] = tr_read<v_rd_off(1, 2 * H, 1)>(vb); vf[6] = tr_read<v_rd_off(1, 2 * H + 1, 0)>(vb); vf[7] = tr_read<v_rd_off(1, 2 * H + 1, 1)>(vb);
;     vf[8] = tr_read<v_rd_off(2, 2 * H, 0)>(vb); vf[9] = tr_read<v_rd_off(2, 2 * H, 1)>(vb); vf[10] = tr_read<v_rd_off(2, 2 * H + 1, 0)>(vb); vf[11] = tr_read<v_rd_off(2, 2 * H + 1, 1)>(vb);
;     vf[12] = tr_read<v_rd_off(3, 2 * H, 0)>(vb); vf[13] = tr_read<v_rd_off(3, 2 * H, 1)>(vb); vf[14] = tr_read<v_rd_off(3, 2 * H + 1, 0)>(vb); vf[15] = tr_read<v_rd_off(3, 2 * H + 1, 1)>(vb);
; }
; DI void pv_mma(f32x16* o, const s16x4* vf, bf16x8 pa0, bf16x8 pa1) {
;     ...
; #pragma unroll
;     for (int d0 = 0; d0 < 4; ++d0) {
;         o[d0] = __builtin_amdgcn_mfma_f32_32x32x16_bf16(pa0, ATT_PK(vf[4 * d0], vf[4 * d0 + 1]), o[d0], 0, 0, 0);
;         o[d0] = __builtin_amdgcn_mfma_f32_32x32x16_bf16(pa1, ATT_PK(vf[4 * d0 + 2], vf[4 * d0 + 3]), o[d0], 0, 0, 0); }
;     ...
; }
; template <int DQK, int D0A, int D0B> DI void k_reads(bf16x8* kf, const LAS unsigned char* Ks, int half, int r32, int hi) {
; #pragma unroll
;     for (int d0 = D0A; d0 < D0B; ++d0) kf[d0 - D0A] = *(const LAS bf16x8*)(Ks + half * (32 * DQK * 2) + kswz<DQK>(r32, (d0 * 16 + hi * 8) * 2));
; }
; template <int D0A, int D0B> DI void qk_mma(f32x16& p, const bf16x8* kf, const bf16x8* qr) {
; #pragma unroll
;     for (int d0 = D0A; d0 < D0B; ++d0) {
	v_mfma_f32_32x32x16_bf16 v[64:79], v[132:135], v[80:83], 0
	v_mfma_f32_32x32x16_bf16 v[64:79], v[136:139], v[84:87], v[64:79]
	v_mfma_f32_32x32x16_bf16 v[64:79], v[140:143], v[88:91], v[64:79]
	v_mfma_f32_32x32x16_bf16 v[64:79], v[174:177], v[92:95], v[64:79]
	v_mfma_f32_32x32x16_bf16 v[64:79], v[178:181], v[96:99], v[64:79]
	v_mfma_f32_32x32x16_bf16 v[64:79], v[182:185], v[100:103], v[64:79]
	s_waitcnt lgkmcnt(0)
	v_mfma_f32_32x32x16_bf16 v[64:79], v[218:221], v[104:107], v[64:79]
	v_mfma_f32_32x32x16_bf16 v[64:79], v[222:225], v[108:111], v[64:79]
	v_mfma_f32_32x32x16_bf16 v[64:79], v[226:229], v[112:115], v[64:79]
	v_mfma_f32_32x32x16_bf16 v[64:79], v[230:233], v[116:119], v[64:79]
	v_mfma_f32_32x32x16_bf16 v[64:79], v[234:237], v[120:123], v[64:79]
	v_mfma_f32_32x32x16_bf16 v[64:79], v[238:241], v[124:127], v[64:79]
	ds_read_b128 v[132:135], v161 offset:49152
	ds_read_b128 v[136:139], v162 offset:49152
	ds_read_b128 v[140:143], v163 offset:49152
	ds_read_b128 v[174:177], v164 offset:49152
	ds_read_b128 v[178:181], v165 offset:49152
	ds_read_b128 v[182:185], v166 offset:49152
	ds_read_b64_tr_b16 v[186:187], v144 offset:0x2000
	ds_read_b64_tr_b16 v[188:189], v144 offset:0x2800
	ds_read_b64_tr_b16 v[190:191], v144 offset:0x3000
	ds_read_b64_tr_b16 v[192:193], v144 offset:0x3800
	ds_read_b64_tr_b16 v[194:195], v144 offset:0x2200
	ds_read_b64_tr_b16 v[196:197], v144 offset:0x2a00
	ds_read_b64_tr_b16 v[198:199], v144 offset:0x3200
	ds_read_b64_tr_b16 v[200:201], v144 offset:0x3a00
	ds_read_b64_tr_b16 v[202:203], v144 offset:0x2400
	ds_read_b64_tr_b16 v[204:205], v144 offset:0x2c00
	ds_read_b64_tr_b16 v[206:207], v144 offset:0x3400
	ds_read_b64_tr_b16 v[208:209], v144 offset:0x3c00
	ds_read_b64_tr_b16 v[210:211], v144 offset:0x2600
	ds_read_b64_tr_b16 v[212:213], v144 offset:0x2e00
	ds_read_b64_tr_b16 v[214:215], v144 offset:0x3600
	ds_read_b64_tr_b16 v[216:217], v144 offset:0x3e00
	s_nop 5
	s_setprio 3
	v_exp_f32_e32 v64, v64
	v_exp_f32_e32 v65, v65
	v_exp_f32_e32 v66, v66
	v_exp_f32_e32 v67, v67
	v_exp_f32_e32 v68, v68
	v_add_f32_e32 v144, 0, v64
	v_exp_f32_e32 v69, v69
	v_add_f32_e32 v144, v65, v144
	v_exp_f32_e32 v70, v70
	v_add_f32_e32 v144, v66, v144
	v_exp_f32_e32 v71, v71
	v_add_f32_e32 v144, v67, v144
	v_exp_f32_e32 v72, v72
	v_add_f32_e32 v144, v68, v144
	v_exp_f32_e32 v73, v73
	v_add_f32_e32 v144, v69, v144
	v_exp_f32_e32 v74, v74
	v_add_f32_e32 v144, v70, v144
	v_exp_f32_e32 v75, v75
	v_add_f32_e32 v144, v71, v144
	v_exp_f32_e32 v76, v76
	v_add_f32_e32 v144, v72, v144
	v_exp_f32_e32 v77, v77
	v_add_f32_e32 v144, v73, v144
	v_exp_f32_e32 v78, v78
	v_add_f32_e32 v144, v74, v144
	v_exp_f32_e32 v79, v79
	v_add_f32_e32 v144, v75, v144
	v_add_f32_e32 v144, v76, v144
	v_add_f32_e32 v144, v77, v144
	v_add_f32_e32 v144, v78, v144
	v_add_f32_e32 v144, v79, v144
	v_add_f32_e32 v144, v145, v144
	v_cvt_pk_bf16_f32 v64, v64, v65
	v_cvt_pk_bf16_f32 v65, v66, v67
	v_cvt_pk_bf16_f32 v66, v68, v69
	v_cvt_pk_bf16_f32 v67, v70, v71
	v_cvt_pk_bf16_f32 v68, v72, v73
	v_cvt_pk_bf16_f32 v69, v74, v75
	v_cvt_pk_bf16_f32 v70, v76, v77
	v_cvt_pk_bf16_f32 v71, v78, v79
	s_nop 0
	v_permlane32_swap_b32_e32 v64, v66
	v_permlane32_swap_b32_e32 v65, v67
	v_permlane32_swap_b32_e32 v68, v70
	v_permlane32_swap_b32_e32 v69, v71
	s_waitcnt lgkmcnt(0)
	ds_read_b128 v[218:221], v167 offset:49152
	ds_read_b128 v[222:225], v168 offset:49152
	ds_read_b128 v[226:229], v169 offset:49152
	ds_read_b128 v[230:233], v170 offset:49152
	ds_read_b128 v[234:237], v171 offset:49152
	ds_read_b128 v[238:241], v172 offset:49152
	s_setprio 0
	s_cmp_lt_u32 s33, 0x100
	s_cbranch_scc1 .Lstg_mla_m61_5
	s_waitcnt vmcnt(0)
	s_barrier

; #define LAS __attribute__((address_space(3)))
; DI void expsum(f32x16& p, float& l_reg, bf16x8& pa0, bf16x8& pa1) {
; #pragma unroll
;     for (int r = 0; r < 16; ++r) p[r] = __builtin_amdgcn_exp2f(p[r]);
;     float ps = 0.f;
; #pragma unroll
;     for (int r = 0; r < 16; ++r) ps += p[r];
;     l_reg += ps; asm volatile("" : "+v"(l_reg));
;     ...
;     ATT_PK4(p, 0, pa0); ATT_PK4(p, 8, pa1);
;     ...
; }
; DI int v_rd_base(int lane) { return ((lane & 3) << 3) | (((lane >> 2) & 3) << 6) | (((lane >> 4) & 1) << 5) | (((lane >> 5) & 1) << 8); }
; template <int OFF> DI s16x4 tr_read(int vb) { s16x4 r; asm volatile("ds_read_b64_tr_b16 %0, %1 offset:%2" : "=&v"(r) : "v"(vb), "i"(OFF) : "memory"); return r; }
; template <int H> DI void v_reads(s16x4* vf, int vb) {
;     vf[0] = tr_read<v_rd_off(0, 2 * H, 0)>(vb); vf[1] = tr_read<v_rd_off(0, 2 * H, 1)>(vb); vf[2] = tr_read<v_rd_off(0, 2 * H + 1, 0)>(vb); vf[3] = tr_read<v_rd_off(0, 2 * H + 1, 1)>(vb);
;     vf[4] = tr_read<v_rd_off(1, 2 * H, 0)>(vb); vf[5] = tr_read<v_rd_off(1, 2 * H, 1)>(vb); vf[6] = tr_read<v_rd_off(1, 2 * H + 1, 0)>(vb); vf[7] = tr_read<v_rd_off(1, 2 * H + 1, 1)>(vb);
;     vf[8] = tr_read<v_rd_off(2, 2 * H, 0)>(vb); vf[9] = tr_read<v_rd_off(2, 2 * H, 1)>(vb); vf[10] = tr_read<v_rd_off(2, 2 * H + 1, 0)>(vb); vf[11] = tr_read<v_rd_off(2, 2 * H + 1, 1)>(vb);
;     vf[12] = tr_read<v_rd_off(3, 2 * H, 0)>(vb); vf[13] = tr_read<v_rd_off(3, 2 * H, 1)>(vb); vf[14] = tr_read<v_rd_off(3, 2 * H + 1, 0)>(vb); vf[15] = tr_read<v_rd_off(3, 2 * H + 1, 1)>(vb);
; }
; DI void pv_mma(f32x16* o, const s16x4* vf, bf16x8 pa0, bf16x8 pa1) {
;     ...
; #pragma unroll
;     for (int d0 = 0; d0 < 4; ++d0) {
;         o[d0] = __builtin_amdgcn_mfma_f32_32x32x16_bf16(pa0, ATT_PK(vf[4 * d0], vf[4 * d0 + 1]), o[d0], 0, 0, 0);
;         o[d0] = __builtin_amdgcn_mfma_f32_32x32x16_bf16(pa1, ATT_PK(vf[4 * d0 + 2], vf[4 * d0 + 3]), o[d0], 0, 0, 0); }
;     ...
; }
; template <int DQK, int D0A, int D0B> DI void k_reads(bf16x8* kf, const LAS unsigned char* Ks, int half, int r32, int hi) {
; #pragma unroll
;     for (int d0 = D0A; d0 < D0B; ++d0) kf[d0 - D0A] = *(const LAS bf16x8*)(Ks + half * (32 * DQK * 2) + kswz<DQK>(r32, (d0 * 16 + hi * 8) * 2));
; }
; template <int D0A, int D0B> DI void qk_mma(f32x16& p, const bf16x8* kf, const bf16x8* qr) {
; #pragma unroll
;     for (int d0 = D0A; d0 < D0B; ++d0) {
.Lstg_mla_t62_6:
	ds_read_b128 v[132:135], v161 offset:61440
	ds_read_b128 v[136:139], v162 offset:61440
	ds_read_b128 v[140:143], v163 offset:61440
	ds_read_b128 v[174:177], v164 offset:61440
	ds_read_b128 v[162:165], v165 offset:61440
	ds_read_b128 v[178:181], v166 offset:61440
	v_add_u32_e32 v145, 0x8000, v130
	ds_read_b64_tr_b16 v[182:183], v145 offset:0
	ds_read_b64_tr_b16 v[184:185], v145 offset:0x800
	ds_read_b64_tr_b16 v[186:187], v145 offset:0x1000
	ds_read_b64_tr_b16 v[188:189], v145 offset:0x1800
	ds_read_b64_tr_b16 v[190:191], v145 offset:0x200
	ds_read_b64_tr_b16 v[192:193], v145 offset:0xa00
	ds_read_b64_tr_b16 v[194:195], v145 offset:0x1200
	ds_read_b64_tr_b16 v[196:197], v145 offset:0x1a00
	ds_read_b64_tr_b16 v[198:199], v145 offset:0x400
	ds_read_b64_tr_b16 v[200:201], v145 offset:0xc00
	ds_read_b64_tr_b16 v[202:203], v145 offset:0x1400
	ds_read_b64_tr_b16 v[204:205], v145 offset:0x1c00
	ds_read_b64_tr_b16 v[206:207], v145 offset:0x600
	ds_read_b64_tr_b16 v[208:209], v145 offset:0xe00
	ds_read_b64_tr_b16 v[210:211], v145 offset:0x1600
	ds_read_b64_tr_b16 v[212:213], v145 offset:0x1e00
	s_nop 3
	s_setprio 3
	v_exp_f32_e32 v64, v64
	v_exp_f32_e32 v65, v65
	v_exp_f32_e32 v66, v66
	v_exp_f32_e32 v67, v67
	v_exp_f32_e32 v68, v68
	v_add_f32_e32 v161, 0, v64
	v_exp_f32_e32 v69, v69
	v_add_f32_e32 v161, v65, v161
	v_exp_f32_e32 v70, v70
	v_add_f32_e32 v161, v66, v161
	v_exp_f32_e32 v71, v71
	v_add_f32_e32 v161, v67, v161
	v_exp_f32_e32 v72, v72
	v_add_f32_e32 v161, v68, v161
	v_exp_f32_e32 v73, v73
	v_add_f32_e32 v161, v69, v161
	v_exp_f32_e32 v74, v74
	v_add_f32_e32 v161, v70, v161
	v_exp_f32_e32 v75, v75
	v_add_f32_e32 v161, v71, v161
	v_exp_f32_e32 v76, v76
	v_add_f32_e32 v161, v72, v161
	v_exp_f32_e32 v77, v77
	v_add_f32_e32 v161, v73, v161
	v_exp_f32_e32 v78, v78
	v_add_f32_e32 v161, v74, v161
	v_exp_f32_e32 v79, v79
	v_add_f32_e32 v161, v75, v161
	v_add_f32_e32 v161, v76, v161
	v_add_f32_e32 v161, v77, v161
	v_add_f32_e32 v161, v78, v161
	v_add_f32_e32 v161, v79, v161
	v_add_f32_e32 v144, v144, v161
	v_cvt_pk_bf16_f32 v64, v64, v65
	v_cvt_pk_bf16_f32 v65, v66, v67
	v_cvt_pk_bf16_f32 v66, v68, v69
	v_cvt_pk_bf16_f32 v67, v70, v71
	v_cvt_pk_bf16_f32 v68, v72, v73
	v_cvt_pk_bf16_f32 v69, v74, v75
	v_cvt_pk_bf16_f32 v70, v76, v77
	v_cvt_pk_bf16_f32 v71, v78, v79
	s_nop 0
	v_permlane32_swap_b32_e32 v64, v66
	v_permlane32_swap_b32_e32 v65, v67
	v_permlane32_swap_b32_e32 v68, v70
	v_permlane32_swap_b32_e32 v69, v71
	s_waitcnt lgkmcnt(0)
	ds_read_b128 v[214:217], v167 offset:61440
	ds_read_b128 v[218:221], v168 offset:61440
	ds_read_b128 v[166:169], v169 offset:61440
	ds_read_b128 v[222:225], v170 offset:61440
	ds_read_b128 v[226:229], v171 offset:61440
	ds_read_b128 v[170:173], v172 offset:61440
	s_setprio 0
	v_mfma_f32_32x32x16_bf16 v[48:63], v[64:67], v[182:185], v[48:63]
	v_mfma_f32_32x32x16_bf16 v[32:47], v[64:67], v[190:193], v[32:47]
	v_mfma_f32_32x32x16_bf16 v[16:31], v[64:67], v[198:201], v[16:31]
	v_mfma_f32_32x32x16_bf16 v[0:15], v[64:67], v[206:209], v[0:15]
	v_mfma_f32_32x32x16_bf16 v[48:63], v[68:71], v[186:189], v[48:63]
	v_mfma_f32_32x32x16_bf16 v[32:47], v[68:71], v[194:197], v[32:47]
	v_mfma_f32_32x32x16_bf16 v[16:31], v[68:71], v[202:205], v[16:31]
	v_mfma_f32_32x32x16_bf16 v[0:15], v[68:71], v[210:213], v[0:15]
	s_waitcnt lgkmcnt(0)
	v_mfma_f32_32x32x16_bf16 v[64:79], v[132:135], v[80:83], 0
	v_mfma_f32_32x32x16_bf16 v[64:79], v[136:139], v[84:87], v[64:79]
	v_mfma_f32_32x32x16_bf16 v[64:79], v[140:143], v[88:91], v[64:79]
	v_mfma_f32_32x32x16_bf16 v[64:79], v[174:177], v[92:95], v[64:79]
	v_mfma_f32_32x32x16_bf16 v[64:79], v[162:165], v[96:99], v[64:79]
	v_mfma_f32_32x32x16_bf16 v[64:79], v[178:181], v[100:103], v[64:79]
	s_waitcnt lgkmcnt(0)
; #define LAS __attribute__((address_space(3)))
; DI void expsum(f32x16& p, float& l_reg, bf16x8& pa0, bf16x8& pa1) {
; #pragma unroll
;     for (int r = 0; r < 16; ++r) p[r] = __builtin_amdgcn_exp2f(p[r]);
;     float ps = 0.f;
; #pragma unroll
;     for (int r = 0; r < 16; ++r) ps += p[r];
;     l_reg += ps; asm volatile("" : "+v"(l_reg));
;     ...
;     ATT_PK4(p, 0, pa0); ATT_PK4(p, 8, pa1);
;     ...
; }
; DI int v_rd_base(int lane) { return ((lane & 3) << 3) | (((lane >> 2) & 3) << 6) | (((lane >> 4) & 1) << 5) | (((lane >> 5) & 1) << 8); }
; template <int OFF> DI s16x4 tr_read(int vb) { s16x4 r; asm volatile("ds_read_b64_tr_b16 %0, %1 offset:%2" : "=&v"(r) : "v"(vb), "i"(OFF) : "memory"); return r; }
; template <int H> DI void v_reads(s16x4* vf, int vb) {
;     vf[0] = tr_read<v_rd_off(0, 2 * H, 0)>(vb); vf[1] = tr_read<v_rd_off(0, 2 * H, 1)>(vb); vf[2] = tr_read<v_rd_off(0, 2 * H + 1, 0)>(vb); vf[3] = tr_read<v_rd_off(0, 2 * H + 1, 1)>(vb);
;     vf[4] = tr_read<v_rd_off(1, 2 * H, 0)>(vb); vf[5] = tr_read<v_rd_off(1, 2 * H, 1)>(vb); vf[6] = tr_read<v_rd_off(1, 2 * H + 1, 0)>(vb); vf[7] = tr_read<v_rd_off(1, 2 * H + 1, 1)>(vb);
;     vf[8] = tr_read<v_rd_off(2, 2 * H, 0)>(vb); vf[9] = tr_read<v_rd_off(2, 2 * H, 1)>(vb); vf[10] = tr_read<v_rd_off(2, 2 * H + 1, 0)>(vb); vf[11] = tr_read<v_rd_off(2, 2 * H + 1, 1)>(vb);
;     vf[12] = tr_read<v_rd_off(3, 2 * H, 0)>(vb); vf[13] = tr_read<v_rd_off(3, 2 * H, 1)>(vb); vf[14] = tr_read<v_rd_off(3, 2 * H + 1, 0)>(vb); vf[15] = tr_read<v_rd_off(3, 2 * H + 1, 1)>(vb);
; }
; DI void pv_mma(f32x16* o, const s16x4* vf, bf16x8 pa0, bf16x8 pa1) {
;     ...
; #pragma unroll
;     for (int d0 = 0; d0 < 4; ++d0) {
;         o[d0] = __builtin_amdgcn_mfma_f32_32x32x16_bf16(pa0, ATT_PK(vf[4 * d0], vf[4 * d0 + 1]), o[d0], 0, 0, 0);
;         o[d0] = __builtin_amdgcn_mfma_f32_32x32x16_bf16(pa1, ATT_PK(vf[4 * d0 + 2], vf[4 * d0 + 3]), o[d0], 0, 0, 0); }
;     ...
; }
; template <int DQK, int D0A, int D0B> DI void k_reads(bf16x8* kf, const LAS unsigned char* Ks, int half, int r32, int hi) {
; #pragma unroll
;     for (int d0 = D0A; d0 < D0B; ++d0) kf[d0 - D0A] = *(const LAS bf16x8*)(Ks + half * (32 * DQK * 2) + kswz<DQK>(r32, (d0 * 16 + hi * 8) * 2));
; }
; template <int D0A, int D0B> DI void qk_mma(f32x16& p, const bf16x8* kf, const bf16x8* qr) {
; #pragma unroll
;     for (int d0 = D0A; d0 < D0B; ++d0) {
	v_mfma_f32_32x32x16_bf16 v[64:79], v[214:217], v[104:107], v[64:79]
	v_mfma_f32_32x32x16_bf16 v[64:79], v[218:221], v[108:111], v[64:79]
	v_mfma_f32_32x32x16_bf16 v[64:79], v[166:169], v[112:115], v[64:79]
	v_mfma_f32_32x32x16_bf16 v[64:79], v[222:225], v[116:119], v[64:79]
	v_mfma_f32_32x32x16_bf16 v[64:79], v[226:229], v[120:123], v[64:79]
	v_mfma_f32_32x32x16_bf16 v[64:79], v[170:173], v[124:127], v[64:79]
	v_add_u32_e32 v158, 0x12000, v158
	v_add_u32_e32 v132, v158, v151
	v_add_u32_e32 v136, v158, v149
	v_add_u32_e32 v140, v158, v148
	v_add_u32_e32 v161, v158, v147
	ds_read_b128 v[132:135], v132
	ds_read_b128 v[136:139], v136
	ds_read_b128 v[140:143], v140
	ds_read_b128 v[162:165], v161
	v_add_u32_e32 v161, v158, v146
	v_add_u32_e32 v170, v158, v150
	ds_read_b128 v[166:169], v161
	ds_read_b128 v[170:173], v170
	ds_read_b64_tr_b16 v[174:175], v145 offset:0x2000
	ds_read_b64_tr_b16 v[176:177], v145 offset:0x2800
	ds_read_b64_tr_b16 v[178:179], v145 offset:0x3000
	ds_read_b64_tr_b16 v[180:181], v145 offset:0x3800
	ds_read_b64_tr_b16 v[182:183], v145 offset:0x2200
	ds_read_b64_tr_b16 v[184:185], v145 offset:0x2a00
	ds_read_b64_tr_b16 v[186:187], v145 offset:0x3200
	ds_read_b64_tr_b16 v[188:189], v145 offset:0x3a00
	ds_read_b64_tr_b16 v[190:191], v145 offset:0x2400
	ds_read_b64_tr_b16 v[192:193], v145 offset:0x2c00
	ds_read_b64_tr_b16 v[194:195], v145 offset:0x3400
	ds_read_b64_tr_b16 v[196:197], v145 offset:0x3c00
	ds_read_b64_tr_b16 v[198:199], v145 offset:0x2600
	ds_read_b64_tr_b16 v[200:201], v145 offset:0x2e00
	ds_read_b64_tr_b16 v[202:203], v145 offset:0x3600
	ds_read_b64_tr_b16 v[204:205], v145 offset:0x3e00
	s_setprio 3
	v_exp_f32_e32 v64, v64
	v_exp_f32_e32 v65, v65
	v_exp_f32_e32 v66, v66
	v_exp_f32_e32 v67, v67
	v_exp_f32_e32 v68, v68
	v_add_f32_e32 v145, 0, v64
	v_exp_f32_e32 v69, v69
	v_add_f32_e32 v145, v65, v145
	v_exp_f32_e32 v70, v70
	v_add_f32_e32 v145, v66, v145
	v_exp_f32_e32 v71, v71
	v_add_f32_e32 v145, v67, v145
	v_exp_f32_e32 v72, v72
	v_add_f32_e32 v145, v68, v145
	v_exp_f32_e32 v73, v73
	v_add_f32_e32 v145, v69, v145
	v_exp_f32_e32 v74, v74
	v_add_f32_e32 v145, v70, v145
	v_exp_f32_e32 v75, v75
	v_add_f32_e32 v145, v71, v145
	v_exp_f32_e32 v76, v76
	v_add_f32_e32 v145, v72, v145
	v_exp_f32_e32 v77, v77
	v_add_f32_e32 v145, v73, v145
	v_exp_f32_e32 v78, v78
	v_add_f32_e32 v145, v74, v145
	v_exp_f32_e32 v79, v79
	v_add_f32_e32 v145, v75, v145
	v_add_f32_e32 v145, v76, v145
	v_add_f32_e32 v145, v77, v145
	v_add_f32_e32 v145, v78, v145
	v_add_f32_e32 v145, v79, v145
	v_add_f32_e32 v161, v144, v145
	v_cvt_pk_bf16_f32 v64, v64, v65
	v_cvt_pk_bf16_f32 v65, v66, v67
	v_cvt_pk_bf16_f32 v66, v68, v69
	v_cvt_pk_bf16_f32 v67, v70, v71
	v_cvt_pk_bf16_f32 v68, v72, v73
	v_cvt_pk_bf16_f32 v69, v74, v75
	v_cvt_pk_bf16_f32 v70, v76, v77
	v_cvt_pk_bf16_f32 v71, v78, v79
	s_nop 0
	v_permlane32_swap_b32_e32 v64, v66
	v_permlane32_swap_b32_e32 v65, v67
	v_permlane32_swap_b32_e32 v68, v70
	v_permlane32_swap_b32_e32 v69, v71
	s_waitcnt lgkmcnt(0)
	v_add_u32_e32 v72, v158, v152
	v_add_u32_e32 v73, v158, v153
	ds_read_b128 v[206:209], v72
	ds_read_b128 v[210:213], v73
	v_add_u32_e32 v72, v158, v154
	v_add_u32_e32 v73, v158, v155
	ds_read_b128 v[214:217], v72
	ds_read_b128 v[218:221], v73
	v_add_u32_e32 v72, v158, v156
	v_add_u32_e32 v73, v158, v157
	ds_read_b128 v[222:225], v72
	ds_read_b128 v[226:229], v73
	s_setprio 0
	s_cmp_lt_u32 s33, 0x100
	s_cbranch_scc1 .Lstg_mla_m62_7
	s_waitcnt vmcnt(0)
	s_barrier

; #define LAS __attribute__((address_space(3)))
; DI void expsum(f32x16& p, float& l_reg, bf16x8& pa0, bf16x8& pa1) {
; #pragma unroll
;     for (int r = 0; r < 16; ++r) p[r] = __builtin_amdgcn_exp2f(p[r]);
;     float ps = 0.f;
; #pragma unroll
;     for (int r = 0; r < 16; ++r) ps += p[r];
;     l_reg += ps; asm volatile("" : "+v"(l_reg));
;     ...
;     ATT_PK4(p, 0, pa0); ATT_PK4(p, 8, pa1);
;     ...
; }
; DI int v_rd_base(int lane) { return ((lane & 3) << 3) | (((lane >> 2) & 3) << 6) | (((lane >> 4) & 1) << 5) | (((lane >> 5) & 1) << 8); }
; template <int OFF> DI s16x4 tr_read(int vb) { s16x4 r; asm volatile("ds_read_b64_tr_b16 %0, %1 offset:%2" : "=&v"(r) : "v"(vb), "i"(OFF) : "memory"); return r; }
; template <int H> DI void v_reads(s16x4* vf, int vb) {
;     vf[0] = tr_read<v_rd_off(0, 2 * H, 0)>(vb); vf[1] = tr_read<v_rd_off(0, 2 * H, 1)>(vb); vf[2] = tr_read<v_rd_off(0, 2 * H + 1, 0)>(vb); vf[3] = tr_read<v_rd_off(0, 2 * H + 1, 1)>(vb);
;     vf[4] = tr_read<v_rd_off(1, 2 * H, 0)>(vb); vf[5] = tr_read<v_rd_off(1, 2 * H, 1)>(vb); vf[6] = tr_read<v_rd_off(1, 2 * H + 1, 0)>(vb); vf[7] = tr_read<v_rd_off(1, 2 * H + 1, 1)>(vb);
;     vf[8] = tr_read<v_rd_off(2, 2 * H, 0)>(vb); vf[9] = tr_read<v_rd_off(2, 2 * H, 1)>(vb); vf[10] = tr_read<v_rd_off(2, 2 * H + 1, 0)>(vb); vf[11] = tr_read<v_rd_off(2, 2 * H + 1, 1)>(vb);
;     vf[12] = tr_read<v_rd_off(3, 2 * H, 0)>(vb); vf[13] = tr_read<v_rd_off(3, 2 * H, 1)>(vb); vf[14] = tr_read<v_rd_off(3, 2 * H + 1, 0)>(vb); vf[15] = tr_read<v_rd_off(3, 2 * H + 1, 1)>(vb);
; }
; DI void pv_mma(f32x16* o, const s16x4* vf, bf16x8 pa0, bf16x8 pa1) {
;     ...
; #pragma unroll
;     for (int d0 = 0; d0 < 4; ++d0) {
;         o[d0] = __builtin_amdgcn_mfma_f32_32x32x16_bf16(pa0, ATT_PK(vf[4 * d0], vf[4 * d0 + 1]), o[d0], 0, 0, 0);
;         o[d0] = __builtin_amdgcn_mfma_f32_32x32x16_bf16(pa1, ATT_PK(vf[4 * d0 + 2], vf[4 * d0 + 3]), o[d0], 0, 0, 0); }
;     ...
; }
; template <int DQK, int D0A, int D0B> DI void k_reads(bf16x8* kf, const LAS unsigned char* Ks, int half, int r32, int hi) {
; #pragma unroll
;     for (int d0 = D0A; d0 < D0B; ++d0) kf[d0 - D0A] = *(const LAS bf16x8*)(Ks + half * (32 * DQK * 2) + kswz<DQK>(r32, (d0 * 16 + hi * 8) * 2));
; }
; template <int D0A, int D0B> DI void qk_mma(f32x16& p, const bf16x8* kf, const bf16x8* qr) {
; #pragma unroll
;     for (int d0 = D0A; d0 < D0B; ++d0) {
.Lstg_mla_t63_8:
	v_add_u32_e32 v158, s82, v159
	v_add_u32_e32 v132, v158, v151
	v_add_u32_e32 v136, v158, v149
	v_add_u32_e32 v140, v158, v148
	v_add_u32_e32 v144, v158, v147
	ds_read_b128 v[132:135], v132
	ds_read_b128 v[136:139], v136
	ds_read_b128 v[140:143], v140
	ds_read_b128 v[162:165], v144
	v_add_u32_e32 v144, v158, v146
	v_add_u32_e32 v148, v158, v150
	ds_read_b128 v[144:147], v144
	ds_read_b128 v[148:151], v148
	ds_read_b64_tr_b16 v[166:167], v130 offset:0
	ds_read_b64_tr_b16 v[168:169], v130 offset:0x800
	ds_read_b64_tr_b16 v[170:171], v130 offset:0x1000
	ds_read_b64_tr_b16 v[172:173], v130 offset:0x1800
	ds_read_b64_tr_b16 v[174:175], v130 offset:0x200
	ds_read_b64_tr_b16 v[176:177], v130 offset:0xa00
	ds_read_b64_tr_b16 v[178:179], v130 offset:0x1200
	ds_read_b64_tr_b16 v[180:181], v130 offset:0x1a00
	ds_read_b64_tr_b16 v[182:183], v130 offset:0x400
	ds_read_b64_tr_b16 v[184:185], v130 offset:0xc00
	ds_read_b64_tr_b16 v[186:187], v130 offset:0x1400
	ds_read_b64_tr_b16 v[188:189], v130 offset:0x1c00
	ds_read_b64_tr_b16 v[190:191], v130 offset:0x600
	ds_read_b64_tr_b16 v[192:193], v130 offset:0xe00
	ds_read_b64_tr_b16 v[194:195], v130 offset:0x1600
	ds_read_b64_tr_b16 v[196:197], v130 offset:0x1e00
	s_setprio 3
	v_exp_f32_e32 v64, v64
	v_exp_f32_e32 v65, v65
	v_exp_f32_e32 v66, v66
	v_exp_f32_e32 v67, v67
	v_exp_f32_e32 v68, v68
	v_add_f32_e32 v159, 0, v64
	v_exp_f32_e32 v69, v69
	v_add_f32_e32 v159, v65, v159
	v_exp_f32_e32 v70, v70
	v_add_f32_e32 v159, v66, v159
	v_exp_f32_e32 v71, v71
	v_add_f32_e32 v159, v67, v159
	v_exp_f32_e32 v72, v72
	v_add_f32_e32 v159, v68, v159
	v_exp_f32_e32 v73, v73
	v_add_f32_e32 v159, v69, v159
	v_exp_f32_e32 v74, v74
	v_add_f32_e32 v159, v70, v159
	v_exp_f32_e32 v75, v75
	v_add_f32_e32 v159, v71, v159
	v_exp_f32_e32 v76, v76
	v_add_f32_e32 v159, v72, v159
	v_exp_f32_e32 v77, v77
	v_add_f32_e32 v159, v73, v159
	v_exp_f32_e32 v78, v78
	v_add_f32_e32 v159, v74, v159
	v_exp_f32_e32 v79, v79
	v_add_f32_e32 v159, v75, v159
	v_add_f32_e32 v159, v76, v159
	v_add_f32_e32 v159, v77, v159
	v_add_f32_e32 v159, v78, v159
	v_add_f32_e32 v159, v79, v159
	v_add_f32_e32 v161, v161, v159
	v_cvt_pk_bf16_f32 v64, v64, v65
	v_cvt_pk_bf16_f32 v65, v66, v67
	v_cvt_pk_bf16_f32 v66, v68, v69
	v_cvt_pk_bf16_f32 v67, v70, v71
	v_cvt_pk_bf16_f32 v68, v72, v73
	v_cvt_pk_bf16_f32 v69, v74, v75
	v_cvt_pk_bf16_f32 v70, v76, v77
	v_cvt_pk_bf16_f32 v71, v78, v79
	s_nop 0
	v_permlane32_swap_b32_e32 v64, v66
	v_permlane32_swap_b32_e32 v65, v67
	v_permlane32_swap_b32_e32 v68, v70
	v_permlane32_swap_b32_e32 v69, v71
	s_waitcnt lgkmcnt(0)
	v_add_u32_e32 v72, v158, v152
	v_add_u32_e32 v73, v158, v153
	ds_read_b128 v[198:201], v72
	ds_read_b128 v[202:205], v73
	v_add_u32_e32 v72, v158, v154
	v_add_u32_e32 v73, v158, v155
	ds_read_b128 v[152:155], v72
	ds_read_b128 v[206:209], v73
	v_add_u32_e32 v72, v158, v156
	v_add_u32_e32 v73, v158, v157
	ds_read_b128 v[156:159], v72
	ds_read_b128 v[210:213], v73
	s_setprio 0
	v_mfma_f32_32x32x16_bf16 v[48:63], v[64:67], v[166:169], v[48:63]
	v_mfma_f32_32x32x16_bf16 v[32:47], v[64:67], v[174:177], v[32:47]
	v_mfma_f32_32x32x16_bf16 v[16:31], v[64:67], v[182:185], v[16:31]
	v_mfma_f32_32x32x16_bf16 v[0:15], v[64:67], v[190:193], v[0:15]
	v_mfma_f32_32x32x16_bf16 v[48:63], v[68:71], v[170:173], v[48:63]
	v_mfma_f32_32x32x16_bf16 v[32:47], v[68:71], v[178:181], v[32:47]
	v_mfma_f32_32x32x16_bf16 v[16:31], v[68:71], v[186:189], v[16:31]
	v_mfma_f32_32x32x16_bf16 v[0:15], v[68:71], v[194:197], v[0:15]
	s_waitcnt lgkmcnt(0)
; template <int TAG = 0> DI int fresh_tid(int wv) { int l; asm volatile("v_mbcnt_lo_u32_b32 %0, -1, 0\n\tv_mbcnt_hi_u32_b32 %0, -1, %0 ; site %1" : "=v"(l) : "n"(TAG)); return wv * 64 + l; }
; DI void expsum(f32x16& p, float& l_reg, bf16x8& pa0, bf16x8& pa1) {
; #pragma unroll
;     for (int r = 0; r < 16; ++r) p[r] = __builtin_amdgcn_exp2f(p[r]);
;     float ps = 0.f;
; #pragma unroll
;     for (int r = 0; r < 16; ++r) ps += p[r];
;     l_reg += ps; asm volatile("" : "+v"(l_reg));
;     ...
;     ATT_PK4(p, 0, pa0); ATT_PK4(p, 8, pa1);
;     ...
; }
; DI int v_rd_base(int lane) { return ((lane & 3) << 3) | (((lane >> 2) & 3) << 6) | (((lane >> 4) & 1) << 5) | (((lane >> 5) & 1) << 8); }
; template <int OFF> DI s16x4 tr_read(int vb) { s16x4 r; asm volatile("ds_read_b64_tr_b16 %0, %1 offset:%2" : "=&v"(r) : "v"(vb), "i"(OFF) : "memory"); return r; }
; template <int H> DI void v_reads(s16x4* vf, int vb) {
;     vf[0] = tr_read<v_rd_off(0, 2 * H, 0)>(vb); vf[1] = tr_read<v_rd_off(0, 2 * H, 1)>(vb); vf[2] = tr_read<v_rd_off(0, 2 * H + 1, 0)>(vb); vf[3] = tr_read<v_rd_off(0, 2 * H + 1, 1)>(vb);
;     vf[4] = tr_read<v_rd_off(1, 2 * H, 0)>(vb); vf[5] = tr_read<v_rd_off(1, 2 * H, 1)>(vb); vf[6] = tr_read<v_rd_off(1, 2 * H + 1, 0)>(vb); vf[7] = tr_read<v_rd_off(1, 2 * H + 1, 1)>(vb);
;     vf[8] = tr_read<v_rd_off(2, 2 * H, 0)>(vb); vf[9] = tr_read<v_rd_off(2, 2 * H, 1)>(vb); vf[10] = tr_read<v_rd_off(2, 2 * H + 1, 0)>(vb); vf[11] = tr_read<v_rd_off(2, 2 * H + 1, 1)>(vb);
;     vf[12] = tr_read<v_rd_off(3, 2 * H, 0)>(vb); vf[13] = tr_read<v_rd_off(3, 2 * H, 1)>(vb); vf[14] = tr_read<v_rd_off(3, 2 * H + 1, 0)>(vb); vf[15] = tr_read<v_rd_off(3, 2 * H + 1, 1)>(vb);
; }
; DI void pv_mma(f32x16* o, const s16x4* vf, bf16x8 pa0, bf16x8 pa1) {
;     ...
; #pragma unroll
;     for (int d0 = 0; d0 < 4; ++d0) {
;         o[d0] = __builtin_amdgcn_mfma_f32_32x32x16_bf16(pa0, ATT_PK(vf[4 * d0], vf[4 * d0 + 1]), o[d0], 0, 0, 0);
;         o[d0] = __builtin_amdgcn_mfma_f32_32x32x16_bf16(pa1, ATT_PK(vf[4 * d0 + 2], vf[4 * d0 + 3]), o[d0], 0, 0, 0); }
;     ...
; }
; template <int DQK, int MODE, int LDQ, int LDK, int LDV> ...
;     ...
;     l_reg = swap_sum(l_reg);
;     { const int lane2 = fresh_tid<110 + MODE>(wv) & 63, r32 = lane2 & 31, hi = lane2 >> 5;
;     if (hi == 0) li_l[r32] = l_reg;
	v_mfma_f32_32x32x16_bf16 v[64:79], v[132:135], v[80:83], 0
	v_mfma_f32_32x32x16_bf16 v[64:79], v[136:139], v[84:87], v[64:79]
	v_mfma_f32_32x32x16_bf16 v[64:79], v[140:143], v[88:91], v[64:79]
	v_mfma_f32_32x32x16_bf16 v[64:79], v[162:165], v[92:95], v[64:79]
	v_mfma_f32_32x32x16_bf16 v[64:79], v[144:147], v[96:99], v[64:79]
	v_mfma_f32_32x32x16_bf16 v[64:79], v[148:151], v[100:103], v[64:79]
	s_waitcnt lgkmcnt(0)
	v_mfma_f32_32x32x16_bf16 v[64:79], v[198:201], v[104:107], v[64:79]
	v_mfma_f32_32x32x16_bf16 v[64:79], v[202:205], v[108:111], v[64:79]
	v_mfma_f32_32x32x16_bf16 v[64:79], v[152:155], v[112:115], v[64:79]
	v_mfma_f32_32x32x16_bf16 v[64:79], v[206:209], v[116:119], v[64:79]
	v_mfma_f32_32x32x16_bf16 v[64:79], v[156:159], v[120:123], v[64:79]
	v_mfma_f32_32x32x16_bf16 v[64:79], v[210:213], v[124:127], v[64:79]
	ds_read_b64_tr_b16 v[80:81], v130 offset:0x2000
	ds_read_b64_tr_b16 v[82:83], v130 offset:0x2800
	ds_read_b64_tr_b16 v[84:85], v130 offset:0x3000
	ds_read_b64_tr_b16 v[86:87], v130 offset:0x3800
	ds_read_b64_tr_b16 v[88:89], v130 offset:0x2200
	ds_read_b64_tr_b16 v[90:91], v130 offset:0x2a00
	ds_read_b64_tr_b16 v[92:93], v130 offset:0x3200
	ds_read_b64_tr_b16 v[94:95], v130 offset:0x3a00
	ds_read_b64_tr_b16 v[96:97], v130 offset:0x2400
	ds_read_b64_tr_b16 v[98:99], v130 offset:0x2c00
	ds_read_b64_tr_b16 v[100:101], v130 offset:0x3400
	ds_read_b64_tr_b16 v[102:103], v130 offset:0x3c00
	ds_read_b64_tr_b16 v[104:105], v130 offset:0x2600
	ds_read_b64_tr_b16 v[106:107], v130 offset:0x2e00
	ds_read_b64_tr_b16 v[108:109], v130 offset:0x3600
	ds_read_b64_tr_b16 v[110:111], v130 offset:0x3e00
	s_nop 11
	s_setprio 3
	v_exp_f32_e32 v112, v64
	v_exp_f32_e32 v65, v65
	v_exp_f32_e32 v113, v66
	v_exp_f32_e32 v67, v67
	v_exp_f32_e32 v68, v68
	v_add_f32_e32 v64, 0, v112
	v_exp_f32_e32 v69, v69
	v_add_f32_e32 v64, v65, v64
	v_exp_f32_e32 v70, v70
	v_add_f32_e32 v64, v113, v64
	v_exp_f32_e32 v71, v71
	v_add_f32_e32 v64, v67, v64
	v_exp_f32_e32 v72, v72
	v_add_f32_e32 v64, v68, v64
	v_exp_f32_e32 v73, v73
	v_add_f32_e32 v64, v69, v64
	v_exp_f32_e32 v74, v74
	v_add_f32_e32 v64, v70, v64
	v_exp_f32_e32 v75, v75
	v_add_f32_e32 v64, v71, v64
	v_exp_f32_e32 v76, v76
	v_add_f32_e32 v64, v72, v64
	v_exp_f32_e32 v77, v77
	v_add_f32_e32 v64, v73, v64
	v_exp_f32_e32 v78, v78
	v_add_f32_e32 v64, v74, v64
	v_exp_f32_e32 v79, v79
	v_add_f32_e32 v64, v75, v64
	v_add_f32_e32 v64, v76, v64
	v_add_f32_e32 v64, v77, v64
	v_add_f32_e32 v64, v78, v64
	v_add_f32_e32 v64, v79, v64
	v_add_f32_e32 v64, v161, v64
	v_cvt_pk_bf16_f32 v66, v112, v65
	v_cvt_pk_bf16_f32 v67, v113, v67
	v_cvt_pk_bf16_f32 v68, v68, v69
	v_cvt_pk_bf16_f32 v69, v70, v71
	v_cvt_pk_bf16_f32 v70, v72, v73
	v_cvt_pk_bf16_f32 v71, v74, v75
	v_cvt_pk_bf16_f32 v72, v76, v77
	v_cvt_pk_bf16_f32 v73, v78, v79
	s_nop 0
	v_permlane32_swap_b32_e32 v66, v68
	v_permlane32_swap_b32_e32 v67, v69
	v_permlane32_swap_b32_e32 v70, v72
	v_permlane32_swap_b32_e32 v71, v73
	s_waitcnt lgkmcnt(0)
	s_setprio 0
	v_mfma_f32_32x32x16_bf16 v[48:63], v[66:69], v[80:83], v[48:63]
	v_mfma_f32_32x32x16_bf16 v[32:47], v[66:69], v[88:91], v[32:47]
	v_mfma_f32_32x32x16_bf16 v[16:31], v[66:69], v[96:99], v[16:31]
	v_mfma_f32_32x32x16_bf16 v[0:15], v[66:69], v[104:107], v[0:15]
	v_mfma_f32_32x32x16_bf16 v[48:63], v[70:73], v[84:87], v[48:63]
	v_mfma_f32_32x32x16_bf16 v[32:47], v[70:73], v[92:95], v[32:47]
	v_mfma_f32_32x32x16_bf16 v[16:31], v[70:73], v[100:103], v[16:31]
	v_mfma_f32_32x32x16_bf16 v[0:15], v[70:73], v[108:111], v[0:15]
	s_setprio 0
	v_mbcnt_lo_u32_b32 v66, -1, 0
	v_mbcnt_hi_u32_b32 v66, -1, v66
	v_mov_b32_e32 v67, v64
	v_and_b32_e32 v65, 31, v66
	v_bfe_u32 v66, v66, 5, 1
	v_permlane32_swap_b32_e32 v64, v67
	v_cmp_eq_u32_e32 vcc, 0, v66
	s_and_saveexec_b64 s[2:3], vcc
	s_cbranch_execz .LBB0_1910
	v_lshl_add_u32 v68, v65, 2, s4
	v_add_f32_e32 v64, v64, v67
	ds_write_b32 v68, v64
	s_branch .LBB0_1910
